# SO1 + cvt_pk_bf16 at 366 sites (incl. SDWA-form sites in the scan side work, early placement where inputs are reused) + pipelined attention loop
# speedup vs baseline: 1.0117x; 1.0035x over previous
.LBB0_107:
	v_add_u32_e32 v19, 0x8000, v9
	s_waitcnt lgkmcnt(0)
	s_barrier
	ds_read2_b32 v[20:21], v19 offset1:65
	s_ashr_i32 s14, s24, 31
	s_lshr_b32 s14, s14, 28
	s_add_i32 s14, s24, s14
	s_ashr_i32 s15, s14, 4
	s_waitcnt lgkmcnt(0)
	ds_read2_b32 v[22:23], v19 offset0:130 offset1:195
	v_cvt_pk_bf16_f32 v20, v20, v21
	s_waitcnt lgkmcnt(0)
	v_bfe_u32 v19, v22, 16, 1
	v_add3_u32 v19, v22, v19, s21
	v_add_u32_e32 v22, 0x8400, v9
	ds_read2_b32 v[24:25], v22 offset0:4 offset1:69
	v_bfe_u32 v21, v23, 16, 1
	ds_read2_b32 v[26:27], v22 offset0:134 offset1:199
	v_lshrrev_b32_e32 v19, 16, v19
	v_add3_u32 v21, v23, v21, s21
	v_and_or_b32 v21, v21, s22, v19
	s_waitcnt lgkmcnt(1)
	v_cvt_pk_bf16_f32 v22, v24, v25
	v_lshl_or_b32 v24, s15, 6, v8
	s_lshl_b32 s14, s15, 10
	v_ashrrev_i32_e32 v25, 31, v24
	s_sub_i32 s14, s0, s14
	s_waitcnt lgkmcnt(0)
	v_lshlrev_b64 v[24:25], 11, v[24:25]
	v_lshl_add_u64 v[24:25], s[6:7], 0, v[24:25]
	s_ashr_i32 s15, s14, 31
	v_lshl_add_u64 v[24:25], s[14:15], 1, v[24:25]
	v_cvt_pk_bf16_f32 v23, v26, v27
	v_lshl_add_u64 v[24:25], v[24:25], 0, v[2:3]
	global_store_dwordx4 v[24:25], v[20:23], off
	s_add_i32 s0, s0, s1
	v_add_u32_e32 v11, s2, v11
	s_andn2_b64 vcc, exec, s[12:13]
	s_mov_b32 s24, s23
	s_waitcnt vmcnt(8)
	v_mov_b32_e32 v19, v17
	s_waitcnt vmcnt(7)
	v_mov_b32_e32 v20, v16
	s_waitcnt vmcnt(6)
	v_mov_b32_e32 v21, v15
	s_waitcnt vmcnt(5)
	v_mov_b32_e32 v22, v14
	s_waitcnt vmcnt(4)
	v_mov_b32_e32 v23, v13
	s_waitcnt vmcnt(3)
	v_mov_b32_e32 v24, v5
	s_waitcnt vmcnt(2)
	v_mov_b32_e32 v25, v4
	s_waitcnt vmcnt(1)
	v_mov_b32_e32 v26, v18
	s_barrier
	s_cbranch_vccz .LBB0_117

.LBB0_119:
	s_waitcnt lgkmcnt(0)
	s_barrier
	ds_read2_b32 v[18:19], v7 offset1:65
	ds_read2_b32 v[20:21], v7 offset0:130 offset1:195
	ds_read2_b32 v[22:23], v8 offset0:4 offset1:69
	s_ashr_i32 s21, s15, 31
	s_lshr_b32 s21, s21, 27
	s_waitcnt lgkmcnt(2)
	v_cvt_pk_bf16_f32 v18, v18, v19
	s_waitcnt lgkmcnt(1)
	ds_read2_b32 v[24:25], v8 offset0:134 offset1:199
	s_add_i32 s15, s15, s21
	s_ashr_i32 s15, s15, 5
	v_cvt_pk_bf16_f32 v19, v20, v21
	s_waitcnt lgkmcnt(1)
	v_cvt_pk_bf16_f32 v20, v22, v23
	v_lshl_or_b32 v22, s15, 6, v4
	s_lshl_b32 s21, s15, 11
	v_ashrrev_i32_e32 v23, 31, v22
	s_sub_i32 s22, s16, s21
	s_waitcnt lgkmcnt(0)
	v_lshlrev_b64 v[22:23], 12, v[22:23]
	v_lshl_add_u64 v[22:23], s[6:7], 0, v[22:23]
	s_ashr_i32 s23, s22, 31
	v_lshl_add_u64 v[22:23], s[22:23], 1, v[22:23]
	v_cvt_pk_bf16_f32 v21, v24, v25
	v_lshl_add_u64 v[22:23], v[22:23], 0, v[2:3]
	global_store_dwordx4 v[22:23], v[18:21], off
	s_add_i32 s16, s16, s17
	s_andn2_b64 vcc, exec, s[12:13]
	s_mov_b32 s15, s20
	s_waitcnt vmcnt(8)
	v_mov_b32_e32 v17, v9
	s_waitcnt vmcnt(7)
	v_mov_b32_e32 v18, v10
	s_waitcnt vmcnt(6)
	v_mov_b32_e32 v19, v11
	s_waitcnt vmcnt(5)
	v_mov_b32_e32 v20, v12
	s_waitcnt vmcnt(4)
	v_mov_b32_e32 v21, v13
	s_waitcnt vmcnt(3)
	v_mov_b32_e32 v22, v14
	s_waitcnt vmcnt(2)
	v_mov_b32_e32 v23, v15
	s_waitcnt vmcnt(1)
	v_mov_b32_e32 v24, v16
	s_barrier
	s_cbranch_vccz .LBB0_122

.LBB0_378:
	s_waitcnt vmcnt(0)
	s_cmpk_lt_u32 s0, 0x100
	s_cselect_b64 s[82:83], -1, 0
	s_cmpk_gt_u32 s0, 0xff
	s_waitcnt lgkmcnt(0)
	s_barrier
	s_cbranch_scc0 .LBB0_380
	v_mov_b32_e32 v98, v1
	v_readlane_b32 s10, v255, 25
	v_lshlrev_b32_e32 v34, 7, v98
	v_ashrrev_i32_e32 v36, 1, v98
	v_and_b32_e32 v106, 0x780, v34
	v_readlane_b32 s11, v255, 26
	v_and_b32_e32 v36, -8, v36
	v_ashrrev_i32_e32 v37, 31, v36
	v_lshl_add_u64 v[34:35], s[10:11], 0, v[106:107]
	s_lshl_b32 s5, s30, 17
	s_lshl_b32 s7, s56, 13
	v_lshl_add_u64 v[34:35], v[36:37], 1, v[34:35]
	s_or_b32 s40, s7, s5
	v_lshl_add_u64 v[34:35], v[34:35], 0, s[40:41]
	s_movk_i32 s5, 0x1000
	v_add_co_u32_e32 v36, vcc, s5, v34
	s_mov_b32 s5, 0x40000
	s_nop 0
	v_addc_co_u32_e32 v37, vcc, 0, v35, vcc
	v_add_co_u32_e32 v42, vcc, s5, v34
	s_add_i32 s16, s1, -4
	s_nop 0
	v_addc_co_u32_e32 v43, vcc, 0, v35, vcc
	s_mov_b32 s5, 0x41000
	v_add_co_u32_e32 v86, vcc, s5, v34
	s_lshl_b32 s5, s16, 4
	s_add_i32 s17, s31, s5
	s_xor_b32 s10, s17, -8
	s_add_i32 s7, 0, 0x22000
	s_lshl_b32 s15, s16, 1
	s_add_i32 s14, s74, -1
	s_add_i32 s18, s10, s74
	s_and_b64 s[10:11], s[8:9], exec
	v_and_b32_e32 v78, 7, v98
	v_ashrrev_i32_e32 v89, 3, v98
	s_cselect_b32 s10, s17, s18
	v_lshlrev_b32_e32 v106, 4, v78
	v_add_u32_e32 v94, s10, v89
	v_lshl_add_u32 v99, v78, 5, s7
	v_sub_u32_e32 v79, 7, v89
	v_add_u32_e32 v88, 0, v106
	v_subrev_u32_e32 v78, s3, v94
	v_cndmask_b32_e64 v79, v79, v89, s[8:9]
	v_mad_u64_u32 v[100:101], s[10:11], v78, s58, v[88:89]
	global_load_dwordx4 v[66:69], v[34:35], off
	global_load_dwordx4 v[54:57], v[34:35], off offset:64
	global_load_dwordx4 v[58:61], v[34:35], off offset:2048
	global_load_dwordx4 v[62:65], v[34:35], off offset:2112
	global_load_dwordx4 v[74:77], v[36:37], off
	global_load_dwordx4 v[70:73], v[36:37], off offset:64
	global_load_dwordx4 v[50:53], v[36:37], off offset:2048
	global_load_dwordx4 v[46:49], v[36:37], off offset:2112
	v_addc_co_u32_e32 v87, vcc, 0, v35, vcc
	global_load_dwordx4 v[34:37], v[42:43], off offset:64
	global_load_dwordx4 v[38:41], v[42:43], off offset:2048
	s_nop 0
	global_load_dwordx4 v[42:45], v[42:43], off offset:2112
	v_lshlrev_b32_e32 v125, 7, v79
	ds_read_b128 v[78:81], v100 offset:35200
	ds_read_b128 v[82:85], v100 offset:35840
	ds_read_b128 v[90:93], v100 offset:36480
	s_lshl_b32 s10, s16, 11
	s_add_i32 s10, s10, 0
	v_add3_u32 v127, s10, v125, v106
	v_cmp_lt_i32_e64 s[10:11], 0, v94
	v_cmp_gt_i32_e32 vcc, s14, v94
	s_waitcnt lgkmcnt(1)
	v_and_b32_e32 v132, 0xffff0000, v82
	v_cndmask_b32_e64 v96, 0, v81, s[10:11]
	v_cndmask_b32_e64 v97, 0, v80, s[10:11]
	v_cndmask_b32_e64 v101, 0, v79, s[10:11]
	v_cndmask_b32_e64 v128, 0, v78, s[10:11]
	ds_read_b128 v[78:81], v99 offset:768
	s_waitcnt lgkmcnt(1)
	v_cndmask_b32_e32 v90, 0, v90, vcc
	v_cndmask_b32_e32 v130, 0, v93, vcc
	v_cndmask_b32_e32 v131, 0, v92, vcc
	v_and_b32_e32 v92, 0xffff0000, v90
	v_and_b32_e32 v93, 0xffff0000, v128
	v_lshlrev_b32_e32 v128, 16, v128
	v_lshlrev_b32_e32 v90, 16, v90
	v_add_f32_e32 v92, v92, v93
	v_add_f32_e32 v90, v90, v128
	v_lshlrev_b32_e32 v82, 16, v82
	v_fma_f32 v133, v92, 0.5, -v132
	v_fma_f32 v90, v90, 0.5, -v82
	ds_read_b128 v[92:95], v99 offset:784
	s_waitcnt lgkmcnt(1)
	v_fmac_f32_e32 v132, v79, v133
	v_fmac_f32_e32 v82, v78, v90
	v_add_f32_e32 v79, v132, v132
	v_add_f32_e32 v78, v82, v82
	v_mul_f32_e32 v79, 0x3fb8aa3b, v79
	v_mul_f32_e32 v78, 0x3fb8aa3b, v78
	v_exp_f32_e32 v79, v79
	v_exp_f32_e32 v82, v78
	v_cndmask_b32_e32 v90, 0, v91, vcc
	v_and_b32_e32 v91, 0xffff0000, v101
	v_add_f32_e32 v78, 1.0, v79
	v_add_f32_e32 v79, 1.0, v82
	v_and_b32_e32 v82, 0xffff0000, v90
	v_add_f32_e32 v82, v82, v91
	v_and_b32_e32 v91, 0xffff0000, v83
	v_fma_f32 v82, v82, 0.5, -v91
	v_fmac_f32_e32 v91, v81, v82
	v_lshlrev_b32_e32 v82, 16, v101
	v_lshlrev_b32_e32 v90, 16, v90
	v_add_f32_e32 v82, v90, v82
	v_lshlrev_b32_e32 v83, 16, v83
	v_fma_f32 v82, v82, 0.5, -v83
	v_fmac_f32_e32 v83, v80, v82
	v_add_f32_e32 v81, v91, v91
	v_add_f32_e32 v80, v83, v83
	v_mul_f32_e32 v81, 0x3fb8aa3b, v81
	v_mul_f32_e32 v80, 0x3fb8aa3b, v80
	v_exp_f32_e32 v81, v81
	v_exp_f32_e32 v82, v80
	v_rcp_f32_e32 v80, v79
	v_and_b32_e32 v83, 0xffff0000, v97
	v_add_f32_e32 v79, 1.0, v81
	v_add_f32_e32 v81, 1.0, v82
	v_and_b32_e32 v82, 0xffff0000, v131
	v_add_f32_e32 v82, v82, v83
	v_and_b32_e32 v83, 0xffff0000, v84
	v_fma_f32 v82, v82, 0.5, -v83
	s_waitcnt lgkmcnt(0)
	v_fmac_f32_e32 v83, v93, v82
	v_add_f32_e32 v82, v83, v83
	v_lshlrev_b32_e32 v83, 16, v97
	v_lshlrev_b32_e32 v90, 16, v131
	v_add_f32_e32 v83, v90, v83
	v_lshlrev_b32_e32 v84, 16, v84
	v_fma_f32 v83, v83, 0.5, -v84
	v_fmac_f32_e32 v84, v92, v83
	v_add_f32_e32 v83, v84, v84
	v_and_b32_e32 v84, 0xffff0000, v130
	v_and_b32_e32 v90, 0xffff0000, v96
	v_add_f32_e32 v84, v84, v90
	v_and_b32_e32 v90, 0xffff0000, v85
	v_fma_f32 v84, v84, 0.5, -v90
	v_fmac_f32_e32 v90, v84, v95
	v_add_f32_e32 v84, v90, v90
	v_mul_f32_e32 v84, 0x3fb8aa3b, v84
	v_exp_f32_e32 v90, v84
	v_lshlrev_b32_e32 v84, 16, v96
	v_lshlrev_b32_e32 v91, 16, v130
	v_add_f32_e32 v84, v91, v84
	v_lshlrev_b32_e32 v85, 16, v85
	v_fma_f32 v84, v84, 0.5, -v85
	v_fmac_f32_e32 v85, v84, v94
	v_add_f32_e32 v84, v85, v85
	v_mul_f32_e32 v83, 0x3fb8aa3b, v83
	v_mul_f32_e32 v84, 0x3fb8aa3b, v84
	v_exp_f32_e32 v83, v83
	v_exp_f32_e32 v85, v84
	v_mul_f32_e32 v82, 0x3fb8aa3b, v82
	v_exp_f32_e32 v82, v82
	v_add_f32_e32 v83, 1.0, v83
	v_add_f32_e32 v85, 1.0, v85
	v_rcp_f32_e32 v81, v81
	v_rcp_f32_e32 v84, v83
	v_rcp_f32_e32 v85, v85
	v_add_f32_e32 v82, 1.0, v82
	v_add_f32_e32 v83, 1.0, v90
	v_rcp_f32_e32 v78, v78
	v_rcp_f32_e32 v79, v79
	v_rcp_f32_e32 v82, v82
	v_rcp_f32_e32 v83, v83
	v_pk_fma_f32 v[80:81], v[80:81], 2.0, 1.0 op_sel_hi:[1,0,0] neg_lo:[1,0,0] neg_hi:[1,0,0]
	v_pk_fma_f32 v[84:85], v[84:85], 2.0, 1.0 op_sel_hi:[1,0,0] neg_lo:[1,0,0] neg_hi:[1,0,0]
	v_bfe_u32 v90, v80, 16, 1
	v_bfe_u32 v91, v81, 16, 1
	v_bfe_u32 v92, v84, 16, 1
	v_pk_fma_f32 v[78:79], v[78:79], 2.0, 1.0 op_sel_hi:[1,0,0] neg_lo:[1,0,0] neg_hi:[1,0,0]
	v_pk_fma_f32 v[82:83], v[82:83], 2.0, 1.0 op_sel_hi:[1,0,0] neg_lo:[1,0,0] neg_hi:[1,0,0]
	v_add3_u32 v84, v84, v92, s46
	v_add3_u32 v81, v81, v91, s46
	v_add3_u32 v80, v80, v90, s46
	v_lshrrev_b32_e32 v90, 16, v80
	v_lshrrev_b32_e32 v91, 16, v81
	v_lshrrev_b32_e32 v80, 16, v84
	v_cvt_pk_bf16_f32 v81, v85, v83
	v_bfe_u32 v85, v82, 16, 1
	v_bfe_u32 v92, v79, 16, 1
	v_bfe_u32 v93, v78, 16, 1
	v_add3_u32 v78, v78, v93, s46
	v_add3_u32 v79, v79, v92, s46
	v_add3_u32 v82, v82, v85, s46
	s_mov_b32 s18, 0xffff0000
	v_and_or_b32 v80, v82, s18, v80
	v_and_or_b32 v79, v79, s18, v91
	v_and_or_b32 v78, v78, s18, v90
	ds_write_b128 v127, v[78:81] offset:16384
	ds_read_b128 v[90:93], v100 offset:35328
	global_load_dwordx4 v[82:85], v[86:87], off offset:-4096
	global_load_dwordx4 v[78:81], v[86:87], off
	ds_read_b128 v[94:97], v100 offset:35968
	ds_read_b128 v[130:133], v100 offset:36608
	s_or_b32 s15, s15, 1
	s_waitcnt lgkmcnt(2)
	v_cndmask_b32_e64 v128, 0, v92, s[10:11]
	v_cndmask_b32_e64 v100, 0, v91, s[10:11]
	v_cndmask_b32_e64 v138, 0, v90, s[10:11]
	v_cndmask_b32_e64 v139, 0, v93, s[10:11]
	ds_read_b128 v[90:93], v99 offset:1024
	ds_read_b128 v[134:137], v99 offset:1040
	s_waitcnt lgkmcnt(2)
	v_cndmask_b32_e32 v149, 0, v131, vcc
	v_cndmask_b32_e32 v130, 0, v130, vcc
	v_lshlrev_b32_e32 v142, 16, v138
	v_lshlrev_b32_e32 v144, 16, v130
	v_lshlrev_b32_e32 v143, 16, v100
	v_lshlrev_b32_e32 v145, 16, v149
	v_pk_add_f32 v[142:143], v[142:143], v[144:145]
	v_lshlrev_b32_e32 v145, 16, v95
	v_lshlrev_b32_e32 v144, 16, v94
	v_pk_fma_f32 v[142:143], v[142:143], 0.5, v[144:145] op_sel_hi:[1,0,1] neg_lo:[0,0,1] neg_hi:[0,0,1]
	s_waitcnt lgkmcnt(1)
	v_mov_b32_e32 v150, v90
	v_mov_b32_e32 v151, v92
	v_pk_fma_f32 v[142:143], v[150:151], v[142:143], v[144:145]
	v_and_b32_e32 v146, 0xffff0000, v138
	v_and_b32_e32 v148, 0xffff0000, v130
	v_and_b32_e32 v147, 0xffff0000, v100
	v_and_b32_e32 v149, 0xffff0000, v149
	v_and_b32_sdwa v90, v143, v213 dst_sel:DWORD dst_unused:UNUSED_PAD src0_sel:WORD_1 src1_sel:DWORD
	v_and_b32_sdwa v92, v142, v213 dst_sel:DWORD dst_unused:UNUSED_PAD src0_sel:WORD_1 src1_sel:DWORD
	v_add3_u32 v100, v142, v92, s46
	v_add3_u32 v130, v143, v90, s46
	v_pk_add_f32 v[142:143], v[146:147], v[148:149]
	v_and_b32_e32 v95, 0xffff0000, v95
	v_and_b32_e32 v94, 0xffff0000, v94
	v_pk_fma_f32 v[142:143], v[142:143], 0.5, v[94:95] op_sel_hi:[1,0,1] neg_lo:[0,0,1] neg_hi:[0,0,1]
	v_mov_b32_e32 v92, v91
	v_pk_fma_f32 v[90:91], v[92:93], v[142:143], v[94:95]
	v_cndmask_b32_e32 v140, 0, v132, vcc
	v_and_b32_sdwa v92, v91, v213 dst_sel:DWORD dst_unused:UNUSED_PAD src0_sel:WORD_1 src1_sel:DWORD
	v_and_b32_sdwa v93, v90, v213 dst_sel:DWORD dst_unused:UNUSED_PAD src0_sel:WORD_1 src1_sel:DWORD
	v_add3_u32 v91, v91, v92, s46
	v_add3_u32 v90, v90, v93, s46
	v_cndmask_b32_e32 v141, 0, v133, vcc
	v_and_b32_e32 v91, 0xffff0000, v91
	v_and_b32_e32 v90, 0xffff0000, v90
	v_and_b32_e32 v101, 0xffff0000, v139
	v_and_b32_e32 v131, 0xffff0000, v141
	v_or_b32_sdwa v91, v130, v91 dst_sel:DWORD dst_unused:UNUSED_PAD src0_sel:WORD_1 src1_sel:DWORD
	v_or_b32_sdwa v90, v100, v90 dst_sel:DWORD dst_unused:UNUSED_PAD src0_sel:WORD_1 src1_sel:DWORD
	v_lshlrev_b32_e32 v100, 16, v128
	v_lshlrev_b32_e32 v130, 16, v140
	v_pk_add_f32 v[92:93], v[100:101], v[130:131]
	v_lshlrev_b32_e32 v94, 16, v96
	v_and_b32_e32 v95, 0xffff0000, v97
	s_waitcnt lgkmcnt(0)
	v_mov_b32_e32 v132, v135
	v_lshlrev_b32_e32 v139, 16, v139
	v_lshlrev_b32_e32 v141, 16, v141
	v_and_b32_e32 v138, 0xffff0000, v128
	v_and_b32_e32 v140, 0xffff0000, v140
	v_pk_fma_f32 v[92:93], v[92:93], 0.5, v[94:95] op_sel_hi:[1,0,1] neg_lo:[0,0,1] neg_hi:[0,0,1]
	v_mov_b32_e32 v135, v137
	v_pk_fma_f32 v[92:93], v[92:93], v[134:135], v[94:95]
	v_pk_add_f32 v[94:95], v[138:139], v[140:141]
	v_and_b32_e32 v96, 0xffff0000, v96
	v_lshlrev_b32_e32 v97, 16, v97
	s_lshl_b32 s10, s15, 3
	v_mov_b32_e32 v133, v136
	v_pk_fma_f32 v[94:95], v[94:95], 0.5, v[96:97] op_sel_hi:[1,0,1] neg_lo:[0,0,1] neg_hi:[0,0,1]
	s_add_i32 s16, s10, s31
	v_pk_fma_f32 v[94:95], v[94:95], v[132:133], v[96:97]
	s_xor_b32 s10, s16, -8
	s_add_i32 s17, s10, s74
	s_and_b64 s[10:11], s[8:9], exec
	s_cselect_b32 s10, s16, s17
	v_add_u32_e32 v96, s10, v89
	v_cvt_pk_bf16_f32 v93, v95, v93
	v_cvt_pk_bf16_f32 v92, v92, v94
	v_subrev_u32_e32 v89, s3, v96
	ds_write_b128 v127, v[90:93] offset:24576
	v_mad_u64_u32 v[100:101], s[10:11], v89, s58, v[88:89]
	ds_read_b128 v[88:91], v100 offset:35200
	ds_read_b128 v[92:95], v100 offset:35840
	ds_read_b128 v[130:133], v100 offset:36480
	s_lshl_b32 s3, s15, 10
	s_add_i32 s3, s3, 0
	v_cmp_lt_i32_e64 s[10:11], 0, v96
	v_add3_u32 v106, s3, v125, v106
	v_cmp_gt_i32_e32 vcc, s14, v96
	s_waitcnt lgkmcnt(2)
	v_cndmask_b32_e64 v97, 0, v91, s[10:11]
	v_cndmask_b32_e64 v101, 0, v90, s[10:11]
	v_cndmask_b32_e64 v125, 0, v89, s[10:11]
	v_cndmask_b32_e64 v127, 0, v88, s[10:11]
	ds_read_b128 v[88:91], v99 offset:768
	s_waitcnt lgkmcnt(1)
	v_cndmask_b32_e32 v130, 0, v130, vcc
	v_cndmask_b32_e32 v96, 0, v133, vcc
	v_cndmask_b32_e32 v128, 0, v132, vcc
	v_and_b32_e32 v132, 0xffff0000, v130
	v_and_b32_e32 v133, 0xffff0000, v127
	v_lshlrev_b32_e32 v127, 16, v127
	v_lshlrev_b32_e32 v130, 16, v130
	v_add_f32_e32 v132, v132, v133
	v_and_b32_e32 v136, 0xffff0000, v92
	v_add_f32_e32 v127, v130, v127
	v_lshlrev_b32_e32 v92, 16, v92
	v_fma_f32 v137, v132, 0.5, -v136
	v_fma_f32 v127, v127, 0.5, -v92
	ds_read_b128 v[132:135], v99 offset:784
	s_waitcnt lgkmcnt(1)
	v_fmac_f32_e32 v136, v89, v137
	v_fmac_f32_e32 v92, v88, v127
	v_add_f32_e32 v89, v136, v136
	v_add_f32_e32 v88, v92, v92
	v_mul_f32_e32 v89, 0x3fb8aa3b, v89
	v_mul_f32_e32 v88, 0x3fb8aa3b, v88
	v_exp_f32_e32 v89, v89
	v_exp_f32_e32 v92, v88
	v_cndmask_b32_e32 v127, 0, v131, vcc
	v_and_b32_e32 v130, 0xffff0000, v125
	v_add_f32_e32 v88, 1.0, v89
	v_add_f32_e32 v89, 1.0, v92
	v_and_b32_e32 v92, 0xffff0000, v127
	v_add_f32_e32 v92, v92, v130
	v_and_b32_e32 v130, 0xffff0000, v93
	v_fma_f32 v92, v92, 0.5, -v130
	v_fmac_f32_e32 v130, v91, v92
	v_lshlrev_b32_e32 v92, 16, v125
	v_lshlrev_b32_e32 v125, 16, v127
	v_add_f32_e32 v92, v125, v92
	v_lshlrev_b32_e32 v93, 16, v93
	v_fma_f32 v92, v92, 0.5, -v93
	v_fmac_f32_e32 v93, v90, v92
	v_add_f32_e32 v91, v130, v130
	v_add_f32_e32 v90, v93, v93
	v_mul_f32_e32 v91, 0x3fb8aa3b, v91
	v_mul_f32_e32 v90, 0x3fb8aa3b, v90
	v_exp_f32_e32 v91, v91
	v_exp_f32_e32 v92, v90
	v_rcp_f32_e32 v90, v89
	v_and_b32_e32 v93, 0xffff0000, v101
	v_add_f32_e32 v89, 1.0, v91
	v_add_f32_e32 v91, 1.0, v92
	v_and_b32_e32 v92, 0xffff0000, v128
	v_add_f32_e32 v92, v92, v93
	v_and_b32_e32 v93, 0xffff0000, v94
	v_fma_f32 v92, v92, 0.5, -v93
	s_waitcnt lgkmcnt(0)
	v_fmac_f32_e32 v93, v133, v92
	v_add_f32_e32 v92, v93, v93
	v_lshlrev_b32_e32 v93, 16, v101
	v_lshlrev_b32_e32 v101, 16, v128
	v_add_f32_e32 v93, v101, v93
	v_lshlrev_b32_e32 v94, 16, v94
	v_fma_f32 v93, v93, 0.5, -v94
	v_fmac_f32_e32 v94, v132, v93
	v_add_f32_e32 v93, v94, v94
	v_and_b32_e32 v94, 0xffff0000, v96
	v_and_b32_e32 v101, 0xffff0000, v97
	v_add_f32_e32 v94, v94, v101
	v_and_b32_e32 v101, 0xffff0000, v95
	v_fma_f32 v94, v94, 0.5, -v101
	v_fmac_f32_e32 v101, v94, v135
	v_add_f32_e32 v94, v101, v101
	v_mul_f32_e32 v94, 0x3fb8aa3b, v94
	v_exp_f32_e32 v101, v94
	v_lshlrev_b32_e32 v94, 16, v97
	v_lshlrev_b32_e32 v96, 16, v96
	v_add_f32_e32 v94, v96, v94
	v_lshlrev_b32_e32 v95, 16, v95
	v_fma_f32 v94, v94, 0.5, -v95
	v_fmac_f32_e32 v95, v94, v134
	v_add_f32_e32 v94, v95, v95
	v_mul_f32_e32 v93, 0x3fb8aa3b, v93
	v_mul_f32_e32 v94, 0x3fb8aa3b, v94
	v_exp_f32_e32 v93, v93
	v_exp_f32_e32 v95, v94
	v_mul_f32_e32 v92, 0x3fb8aa3b, v92
	v_exp_f32_e32 v92, v92
	v_add_f32_e32 v93, 1.0, v93
	v_add_f32_e32 v95, 1.0, v95
	v_rcp_f32_e32 v91, v91
	v_rcp_f32_e32 v94, v93
	v_rcp_f32_e32 v95, v95
	v_add_f32_e32 v92, 1.0, v92
	v_add_f32_e32 v93, 1.0, v101
	v_rcp_f32_e32 v88, v88
	v_rcp_f32_e32 v89, v89
	v_rcp_f32_e32 v92, v92
	v_rcp_f32_e32 v93, v93
	v_pk_fma_f32 v[90:91], v[90:91], 2.0, 1.0 op_sel_hi:[1,0,0] neg_lo:[1,0,0] neg_hi:[1,0,0]
	v_pk_fma_f32 v[94:95], v[94:95], 2.0, 1.0 op_sel_hi:[1,0,0] neg_lo:[1,0,0] neg_hi:[1,0,0]
	v_bfe_u32 v96, v90, 16, 1
	v_bfe_u32 v97, v91, 16, 1
	v_bfe_u32 v101, v94, 16, 1
	v_pk_fma_f32 v[88:89], v[88:89], 2.0, 1.0 op_sel_hi:[1,0,0] neg_lo:[1,0,0] neg_hi:[1,0,0]
	v_pk_fma_f32 v[92:93], v[92:93], 2.0, 1.0 op_sel_hi:[1,0,0] neg_lo:[1,0,0] neg_hi:[1,0,0]
	v_add3_u32 v94, v94, v101, s46
	v_add3_u32 v91, v91, v97, s46
	v_add3_u32 v90, v90, v96, s46
	v_lshrrev_b32_e32 v96, 16, v90
	v_lshrrev_b32_e32 v97, 16, v91
	v_lshrrev_b32_e32 v90, 16, v94
	v_cvt_pk_bf16_f32 v91, v95, v93
	v_bfe_u32 v95, v92, 16, 1
	v_bfe_u32 v101, v89, 16, 1
	v_bfe_u32 v125, v88, 16, 1
	v_add3_u32 v88, v88, v125, s46
	v_add3_u32 v89, v89, v101, s46
	v_add3_u32 v92, v92, v95, s46
	v_and_or_b32 v90, v92, s18, v90
	v_and_or_b32 v89, v89, s18, v97
	v_and_or_b32 v88, v88, s18, v96
	ds_write_b128 v106, v[88:91] offset:16384
	ds_read_b128 v[130:133], v100 offset:35328
	global_load_dwordx4 v[94:97], v[86:87], off offset:64
	global_load_dwordx4 v[90:93], v[86:87], off offset:2048
	s_nop 0
	global_load_dwordx4 v[86:89], v[86:87], off offset:2112
	ds_read_b128 v[134:137], v100 offset:35968
	ds_read_b128 v[138:141], v100 offset:36608
	s_waitcnt lgkmcnt(2)
	v_cndmask_b32_e64 v125, 0, v132, s[10:11]
	v_cndmask_b32_e64 v100, 0, v131, s[10:11]
	v_cndmask_b32_e64 v127, 0, v130, s[10:11]
	v_cndmask_b32_e64 v128, 0, v133, s[10:11]
	ds_read_b128 v[130:133], v99 offset:1024
	ds_read_b128 v[142:145], v99 offset:1040
	s_waitcnt lgkmcnt(2)
	v_cndmask_b32_e32 v146, 0, v139, vcc
	v_cndmask_b32_e32 v99, 0, v138, vcc
	v_lshlrev_b32_e32 v150, 16, v127
	v_lshlrev_b32_e32 v152, 16, v99
	v_lshlrev_b32_e32 v151, 16, v100
	v_lshlrev_b32_e32 v153, 16, v146
	v_pk_add_f32 v[150:151], v[150:151], v[152:153]
	v_lshlrev_b32_e32 v153, 16, v135
	v_lshlrev_b32_e32 v152, 16, v134
	v_pk_fma_f32 v[150:151], v[150:151], 0.5, v[152:153] op_sel_hi:[1,0,1] neg_lo:[0,0,1] neg_hi:[0,0,1]
	s_waitcnt lgkmcnt(1)
	v_mov_b32_e32 v158, v130
	v_mov_b32_e32 v159, v132
	v_pk_fma_f32 v[150:151], v[158:159], v[150:151], v[152:153]
	v_and_b32_e32 v154, 0xffff0000, v127
	v_and_b32_e32 v156, 0xffff0000, v99
	v_and_b32_e32 v155, 0xffff0000, v100
	v_and_b32_e32 v157, 0xffff0000, v146
	v_and_b32_sdwa v99, v151, v213 dst_sel:DWORD dst_unused:UNUSED_PAD src0_sel:WORD_1 src1_sel:DWORD
	v_and_b32_sdwa v100, v150, v213 dst_sel:DWORD dst_unused:UNUSED_PAD src0_sel:WORD_1 src1_sel:DWORD
	v_add3_u32 v100, v150, v100, s46
	v_add3_u32 v99, v151, v99, s46
	v_pk_add_f32 v[150:151], v[154:155], v[156:157]
	v_and_b32_e32 v135, 0xffff0000, v135
	v_and_b32_e32 v134, 0xffff0000, v134
	v_pk_fma_f32 v[150:151], v[150:151], 0.5, v[134:135] op_sel_hi:[1,0,1] neg_lo:[0,0,1] neg_hi:[0,0,1]
	v_mov_b32_e32 v132, v131
	v_pk_fma_f32 v[130:131], v[132:133], v[150:151], v[134:135]
	v_and_b32_e32 v101, 0xffff0000, v128
	v_lshlrev_b32_e32 v147, 16, v128
	v_and_b32_sdwa v128, v130, v213 dst_sel:DWORD dst_unused:UNUSED_PAD src0_sel:WORD_1 src1_sel:DWORD
	v_add3_u32 v128, v130, v128, s46
	v_cndmask_b32_e32 v148, 0, v140, vcc
	v_cndmask_b32_e32 v138, 0, v141, vcc
	v_and_b32_e32 v128, 0xffff0000, v128
	v_and_b32_e32 v139, 0xffff0000, v138
	v_lshlrev_b32_e32 v149, 16, v138
	v_or_b32_sdwa v130, v100, v128 dst_sel:DWORD dst_unused:UNUSED_PAD src0_sel:WORD_1 src1_sel:DWORD
	v_lshlrev_b32_e32 v100, 16, v125
	v_lshlrev_b32_e32 v138, 16, v148
	v_pk_add_f32 v[100:101], v[100:101], v[138:139]
	v_lshlrev_b32_e32 v132, 16, v136
	v_and_b32_e32 v133, 0xffff0000, v137
	s_waitcnt lgkmcnt(0)
	v_mov_b32_e32 v140, v143
	v_and_b32_sdwa v127, v131, v213 dst_sel:DWORD dst_unused:UNUSED_PAD src0_sel:WORD_1 src1_sel:DWORD
	v_and_b32_e32 v146, 0xffff0000, v125
	v_and_b32_e32 v148, 0xffff0000, v148
	v_pk_fma_f32 v[100:101], v[100:101], 0.5, v[132:133] op_sel_hi:[1,0,1] neg_lo:[0,0,1] neg_hi:[0,0,1]
	v_mov_b32_e32 v143, v145
	v_add3_u32 v127, v131, v127, s46
	v_pk_fma_f32 v[100:101], v[100:101], v[142:143], v[132:133]
	v_pk_add_f32 v[132:133], v[146:147], v[148:149]
	v_and_b32_e32 v134, 0xffff0000, v136
	v_lshlrev_b32_e32 v135, 16, v137
	v_mov_b32_e32 v141, v144
	v_and_b32_e32 v127, 0xffff0000, v127
	v_pk_fma_f32 v[132:133], v[132:133], 0.5, v[134:135] op_sel_hi:[1,0,1] neg_lo:[0,0,1] neg_hi:[0,0,1]
	v_or_b32_sdwa v131, v99, v127 dst_sel:DWORD dst_unused:UNUSED_PAD src0_sel:WORD_1 src1_sel:DWORD
	v_pk_fma_f32 v[132:133], v[132:133], v[140:141], v[134:135]
	v_cvt_pk_bf16_f32 v133, v133, v101
	v_and_b32_e32 v99, 15, v98
	v_cvt_pk_bf16_f32 v132, v100, v132
	v_or_b32_e32 v100, s5, v99
	ds_write_b128 v106, v[130:133] offset:24576
	v_and_b32_e32 v101, -16, v98
	v_lshlrev_b32_e32 v100, 7, v100
	s_waitcnt lgkmcnt(0)
	v_add3_u32 v100, 0, v100, v101
	ds_read_b128 v[130:133], v100 offset:16384
	ds_read_b128 v[134:137], v100 offset:16448
	s_waitcnt vmcnt(15) lgkmcnt(1)
	v_mfma_f32_16x16x32_bf16 v[66:69], v[130:133], v[66:69], 0
	s_waitcnt lgkmcnt(0)
	s_waitcnt vmcnt(14) lgkmcnt(0)
	v_mfma_f32_16x16x32_bf16 v[54:57], v[134:137], v[54:57], v[66:69]
	s_nop 5
	v_lshl_add_u32 v66, v99, 2, s7
	v_add_u32_e32 v68, 0x400, v66
	ds_read2_b32 v[66:67], v68 offset0:64 offset1:80
	s_waitcnt vmcnt(9)
	v_mfma_f32_16x16x32_bf16 v[50:53], v[130:133], v[50:53], 0
	v_lshrrev_b32_e32 v69, 2, v98
	v_and_b32_e32 v69, 0x1fffffc, v69
	v_add_lshl_u32 v69, v69, s5, 7
	s_waitcnt lgkmcnt(0)
	v_add_f32_e32 v54, v54, v66
	v_mul_f32_e32 v54, 0xbfb8aa3b, v54
	s_waitcnt vmcnt(8)
	v_mfma_f32_16x16x32_bf16 v[46:49], v[134:137], v[46:49], v[50:53]
	v_exp_f32_e32 v54, v54
	s_nop 1
	v_add_f32_e32 v51, v55, v66
	v_mul_f32_e32 v51, 0xbfb8aa3b, v51
	v_add_f32_e32 v52, v56, v66
	v_exp_f32_e32 v51, v51
	v_mul_f32_e32 v52, 0xbfb8aa3b, v52
	v_exp_f32_e32 v52, v52
	v_mfma_f32_16x16x32_bf16 v[58:61], v[130:133], v[58:61], 0
	v_lshlrev_b32_e32 v50, 1, v99
	v_add3_u32 v69, 0, v69, v50
	v_add_f32_e32 v50, 1.0, v54
	v_rcp_f32_e32 v50, v50
	v_add_f32_e32 v51, 1.0, v51
	v_rcp_f32_e32 v51, v51
	v_add_f32_e32 v52, 1.0, v52
	v_mfma_f32_16x16x32_bf16 v[58:61], v[134:137], v[62:65], v[58:61]
	v_rcp_f32_e32 v52, v52
	v_fma_mixlo_f16 v50, v50, s47, 0
	ds_write_b16 v69, v50 offset:16384
	v_fma_mixlo_f16 v50, v51, s47, 0
	ds_write_b16 v69, v50 offset:16512
	v_fma_mixlo_f16 v50, v52, s47, 0
	v_add_f32_e32 v51, v57, v66
	s_nop 0
	v_add_f32_e32 v52, v58, v67
	v_mul_f32_e32 v51, 0xbfb8aa3b, v51
	v_mul_f32_e32 v52, 0xbfb8aa3b, v52
	v_exp_f32_e32 v51, v51
	v_exp_f32_e32 v52, v52
	ds_write_b16 v69, v50 offset:16640
	v_mfma_f32_16x16x32_bf16 v[62:65], v[130:133], v[74:77], 0
	v_add_f32_e32 v50, 1.0, v51
	v_add_f32_e32 v51, 1.0, v52
	v_add_f32_e32 v52, v59, v67
	v_rcp_f32_e32 v50, v50
	v_mul_f32_e32 v52, 0xbfb8aa3b, v52
	v_rcp_f32_e32 v51, v51
	v_exp_f32_e32 v52, v52
	v_fma_mixlo_f16 v50, v50, s47, 0
	ds_write_b16 v69, v50 offset:16768
	v_fma_mixlo_f16 v50, v51, s47, 0
	v_add_f32_e32 v51, 1.0, v52
	v_add_f32_e32 v52, v60, v67
	v_rcp_f32_e32 v51, v51
	v_mul_f32_e32 v52, 0xbfb8aa3b, v52
	v_exp_f32_e32 v52, v52
	ds_write_b16 v69, v50 offset:16416
	v_fma_mixlo_f16 v50, v51, s47, 0
	ds_write_b16 v69, v50 offset:16544
	v_add_f32_e32 v50, 1.0, v52
	v_rcp_f32_e32 v52, v50
	v_add_f32_e32 v50, v61, v67
	v_mul_f32_e32 v50, 0xbfb8aa3b, v50
	v_exp_f32_e32 v53, v50
	ds_read2_b32 v[50:51], v68 offset0:96 offset1:112
	v_mfma_f32_16x16x32_bf16 v[62:65], v[134:137], v[70:73], v[62:65]
	v_fma_mixlo_f16 v52, v52, s47, 0
	ds_write_b16 v69, v52 offset:16672
	v_add_f32_e32 v52, 1.0, v53
	s_waitcnt lgkmcnt(1)
	v_add_f32_e32 v46, v46, v51
	v_mul_f32_e32 v46, 0xbfb8aa3b, v46
	s_nop 1
	v_add_f32_e32 v53, v62, v50
	v_exp_f32_e32 v46, v46
	v_mul_f32_e32 v53, 0xbfb8aa3b, v53
	v_exp_f32_e32 v53, v53
	v_add_f32_e32 v47, v47, v51
	v_add_f32_e32 v46, 1.0, v46
	v_add_f32_e32 v54, v63, v50
	v_rcp_f32_e32 v46, v46
	v_mul_f32_e32 v47, 0xbfb8aa3b, v47
	v_rcp_f32_e32 v52, v52
	v_mul_f32_e32 v54, 0xbfb8aa3b, v54
	v_add_f32_e32 v53, 1.0, v53
	v_exp_f32_e32 v47, v47
	v_exp_f32_e32 v54, v54
	v_rcp_f32_e32 v53, v53
	v_fma_mixlo_f16 v46, v46, s47, 0
	v_fma_mixlo_f16 v52, v52, s47, 0
	ds_write_b16 v69, v46 offset:16480
	v_add_f32_e32 v46, 1.0, v47
	v_add_f32_e32 v47, v48, v51
	v_add_f32_e32 v54, 1.0, v54
	ds_write_b16 v69, v52 offset:16800
	v_fma_mixlo_f16 v52, v53, s47, 0
	v_add_f32_e32 v53, v64, v50
	v_add_f32_e32 v50, v65, v50
	v_mul_f32_e32 v47, 0xbfb8aa3b, v47
	v_add_f32_e32 v48, v49, v51
	v_rcp_f32_e32 v54, v54
	v_mul_f32_e32 v53, 0xbfb8aa3b, v53
	v_mul_f32_e32 v50, 0xbfb8aa3b, v50
	v_exp_f32_e32 v47, v47
	v_mul_f32_e32 v48, 0xbfb8aa3b, v48
	v_exp_f32_e32 v53, v53
	v_exp_f32_e32 v50, v50
	v_exp_f32_e32 v48, v48
	ds_write_b16 v69, v52 offset:16448
	v_fma_mixlo_f16 v52, v54, s47, 0
	v_rcp_f32_e32 v46, v46
	v_add_f32_e32 v47, 1.0, v47
	ds_write_b16 v69, v52 offset:16576
	v_add_f32_e32 v52, 1.0, v53
	v_add_f32_e32 v50, 1.0, v50
	v_rcp_f32_e32 v47, v47
	v_add_f32_e32 v48, 1.0, v48
	v_rcp_f32_e32 v52, v52
	v_rcp_f32_e32 v50, v50
	v_rcp_f32_e32 v48, v48
	v_fma_mixlo_f16 v46, v46, s47, 0
	ds_write_b16 v69, v46 offset:16608
	v_fma_mixlo_f16 v46, v47, s47, 0
	v_fma_mixlo_f16 v52, v52, s47, 0
	v_fma_mixlo_f16 v50, v50, s47, 0
	ds_write_b16 v69, v46 offset:16736
	v_fma_mixlo_f16 v46, v48, s47, 0
	ds_write_b16 v69, v52 offset:16704
	ds_write_b16 v69, v50 offset:16832
	ds_write_b16 v69, v46 offset:16864
	ds_read_b128 v[46:49], v100 offset:24576
	ds_read_b128 v[50:53], v100 offset:24640
	s_waitcnt vmcnt(4) lgkmcnt(1)
	v_mfma_f32_16x16x32_bf16 v[54:57], v[46:49], v[82:85], 0
	s_waitcnt lgkmcnt(0)
	s_waitcnt lgkmcnt(0)
	v_mfma_f32_16x16x32_bf16 v[34:37], v[50:53], v[34:37], v[54:57]
	s_nop 5
	ds_read2_b32 v[54:55], v68 offset0:128 offset1:144
	v_mfma_f32_16x16x32_bf16 v[38:41], v[46:49], v[38:41], 0
	s_waitcnt lgkmcnt(0)
	v_add_f32_e32 v34, v34, v54
	v_mul_f32_e32 v34, 0xbfb8aa3b, v34
	v_exp_f32_e32 v34, v34
	v_add_f32_e32 v35, v35, v54
	v_mul_f32_e32 v35, 0xbfb8aa3b, v35
	v_exp_f32_e32 v35, v35
	v_add_f32_e32 v34, 1.0, v34
	v_rcp_f32_e32 v34, v34
	v_mfma_f32_16x16x32_bf16 v[38:41], v[50:53], v[42:45], v[38:41]
	v_cvt_f16_f32_e32 v34, v34
	s_waitcnt vmcnt(3)
	v_mfma_f32_16x16x32_bf16 v[42:45], v[46:49], v[78:81], 0
	ds_write_b16 v69, v34 offset:24576
	v_add_f32_e32 v34, 1.0, v35
	v_add_f32_e32 v35, v36, v54
	v_add_f32_e32 v36, v37, v54
	v_mul_f32_e32 v35, 0xbfb8aa3b, v35
	v_mul_f32_e32 v36, 0xbfb8aa3b, v36
	v_exp_f32_e32 v35, v35
	v_exp_f32_e32 v36, v36
	v_rcp_f32_e32 v34, v34
	v_add_f32_e32 v37, v38, v55
	v_add_f32_e32 v35, 1.0, v35
	v_add_f32_e32 v36, 1.0, v36
	v_mul_f32_e32 v37, 0xbfb8aa3b, v37
	v_cvt_f16_f32_e32 v34, v34
	v_rcp_f32_e32 v35, v35
	v_rcp_f32_e32 v36, v36
	v_exp_f32_e32 v37, v37
	ds_write_b16 v69, v34 offset:24704
	v_cvt_f16_f32_e32 v34, v35
	v_cvt_f16_f32_e32 v35, v36
	v_add_f32_e32 v36, 1.0, v37
	v_add_f32_e32 v37, v39, v55
	v_mul_f32_e32 v37, 0xbfb8aa3b, v37
	v_exp_f32_e32 v37, v37
	ds_write_b16 v69, v34 offset:24832
	ds_write_b16 v69, v35 offset:24960
	v_add_f32_e32 v35, v40, v55
	v_mul_f32_e32 v35, 0xbfb8aa3b, v35
	v_add_f32_e32 v34, 1.0, v37
	v_add_f32_e32 v37, v41, v55
	v_rcp_f32_e32 v36, v36
	v_exp_f32_e32 v35, v35
	v_mul_f32_e32 v37, 0xbfb8aa3b, v37
	v_exp_f32_e32 v37, v37
	v_cvt_f16_f32_e32 v36, v36
	v_rcp_f32_e32 v38, v34
	v_add_f32_e32 v34, 1.0, v35
	v_rcp_f32_e32 v39, v34
	v_add_f32_e32 v34, 1.0, v37
	v_rcp_f32_e32 v37, v34
	ds_read2_b32 v[34:35], v68 offset0:160 offset1:176
	s_waitcnt vmcnt(2)
	v_mfma_f32_16x16x32_bf16 v[42:45], v[50:53], v[94:97], v[42:45]
	ds_write_b16 v69, v36 offset:24608
	v_cvt_f16_f32_e32 v36, v38
	v_cvt_f16_f32_e32 v38, v39
	v_cvt_f16_f32_e32 v37, v37
	ds_write_b16 v69, v36 offset:24736
	ds_write_b16 v69, v38 offset:24864
	ds_write_b16 v69, v37 offset:24992
	s_waitcnt lgkmcnt(4)
	v_add_f32_e32 v39, v42, v34
	v_mul_f32_e32 v39, 0xbfb8aa3b, v39
	v_add_f32_e32 v37, v43, v34
	v_exp_f32_e32 v39, v39
	v_mul_f32_e32 v37, 0xbfb8aa3b, v37
	v_add_f32_e32 v38, v44, v34
	v_exp_f32_e32 v37, v37
	v_mul_f32_e32 v38, 0xbfb8aa3b, v38
	v_exp_f32_e32 v38, v38
	v_add_f32_e32 v36, 1.0, v39
	v_add_f32_e32 v34, v45, v34
	s_waitcnt vmcnt(1)
	v_mfma_f32_16x16x32_bf16 v[46:49], v[46:49], v[90:93], 0
	v_rcp_f32_e32 v36, v36
	v_add_f32_e32 v37, 1.0, v37
	v_mul_f32_e32 v34, 0xbfb8aa3b, v34
	v_rcp_f32_e32 v37, v37
	v_add_f32_e32 v38, 1.0, v38
	v_exp_f32_e32 v34, v34
	v_rcp_f32_e32 v38, v38
	s_waitcnt vmcnt(0)
	v_mfma_f32_16x16x32_bf16 v[46:49], v[50:53], v[86:89], v[46:49]
	v_cvt_f16_f32_e32 v36, v36
	v_cvt_f16_f32_e32 v37, v37
	v_add_f32_e32 v34, 1.0, v34
	v_cvt_f16_f32_e32 v38, v38
	v_rcp_f32_e32 v34, v34
	ds_write_b16 v69, v36 offset:24640
	ds_write_b16 v69, v37 offset:24768
	ds_write_b16 v69, v38 offset:24896
	v_add_f32_e32 v36, v46, v35
	v_add_f32_e32 v37, v47, v35
	v_mul_f32_e32 v36, 0xbfb8aa3b, v36
	v_mul_f32_e32 v37, 0xbfb8aa3b, v37
	v_cvt_f16_f32_e32 v34, v34
	v_exp_f32_e32 v36, v36
	v_exp_f32_e32 v37, v37
	ds_write_b16 v69, v34 offset:25024
	v_add_f32_e32 v34, 1.0, v36
	v_add_f32_e32 v36, 1.0, v37
	v_add_f32_e32 v37, v48, v35
	v_mul_f32_e32 v37, 0xbfb8aa3b, v37
	v_add_f32_e32 v35, v49, v35
	v_exp_f32_e32 v37, v37
	v_mul_f32_e32 v35, 0xbfb8aa3b, v35
	v_exp_f32_e32 v35, v35
	v_rcp_f32_e32 v34, v34
	v_rcp_f32_e32 v36, v36
	v_add_f32_e32 v37, 1.0, v37
	v_rcp_f32_e32 v37, v37
	v_add_f32_e32 v35, 1.0, v35
	v_rcp_f32_e32 v35, v35
	v_cvt_f16_f32_e32 v34, v34
	v_cvt_f16_f32_e32 v36, v36
	v_cvt_f16_f32_e32 v37, v37
	v_cvt_f16_f32_e32 v35, v35
	ds_write_b16 v69, v34 offset:24672
	ds_write_b16 v69, v36 offset:24800
	ds_write_b16 v69, v37 offset:24928
	ds_write_b16 v69, v35 offset:25056

.LBB0_436:
	s_waitcnt vmcnt(0)
	s_or_b64 s[10:11], s[82:83], s[56:57]
	s_and_b64 vcc, exec, s[10:11]
	s_waitcnt lgkmcnt(0)
	s_barrier
	s_cbranch_vccnz .LBB0_438
	v_mov_b32_e32 v98, v1
	v_readlane_b32 s10, v255, 25
	v_lshlrev_b32_e32 v34, 7, v98
	v_ashrrev_i32_e32 v36, 1, v98
	v_and_b32_e32 v106, 0x780, v34
	v_readlane_b32 s11, v255, 26
	v_and_b32_e32 v36, -8, v36
	v_ashrrev_i32_e32 v37, 31, v36
	v_lshl_add_u64 v[34:35], s[10:11], 0, v[106:107]
	v_lshl_add_u64 v[34:35], v[36:37], 1, v[34:35]
	s_mov_b32 s31, s41
	v_lshl_add_u64 v[34:35], v[34:35], 0, s[30:31]
	s_movk_i32 s10, 0x1000
	v_add_co_u32_e32 v36, vcc, s10, v34
	s_mov_b32 s10, 0x40000
	s_nop 0
	v_addc_co_u32_e32 v37, vcc, 0, v35, vcc
	v_add_co_u32_e32 v42, vcc, s10, v34
	s_add_i32 s14, 0, 0x22000
	s_lshl_b32 s15, s49, 6
	v_addc_co_u32_e32 v43, vcc, 0, v35, vcc
	s_mov_b32 s10, 0x41000
	s_sub_i32 s16, s63, s73
	v_add_co_u32_e32 v86, vcc, s10, v34
	s_and_b64 s[10:11], s[8:9], exec
	s_cselect_b32 s16, s15, s16
	s_add_i32 s17, s15, s0
	s_sub_i32 s18, s71, s17
	s_and_b64 s[10:11], s[8:9], exec
	v_and_b32_e32 v78, 7, v98
	v_ashrrev_i32_e32 v89, 3, v98
	s_cselect_b32 s10, s17, s18
	v_lshlrev_b32_e32 v106, 4, v78
	v_add_u32_e32 v94, s10, v89
	v_lshl_add_u32 v99, v78, 5, s14
	v_sub_u32_e32 v79, 7, v89
	v_add_u32_e32 v88, 0, v106
	v_subrev_u32_e32 v78, s16, v94
	v_cndmask_b32_e64 v79, v79, v89, s[8:9]
	v_mad_u64_u32 v[100:101], s[10:11], v78, s58, v[88:89]
	global_load_dwordx4 v[66:69], v[34:35], off
	global_load_dwordx4 v[54:57], v[34:35], off offset:64
	global_load_dwordx4 v[58:61], v[34:35], off offset:2048
	global_load_dwordx4 v[62:65], v[34:35], off offset:2112
	global_load_dwordx4 v[74:77], v[36:37], off
	global_load_dwordx4 v[70:73], v[36:37], off offset:64
	global_load_dwordx4 v[50:53], v[36:37], off offset:2048
	global_load_dwordx4 v[46:49], v[36:37], off offset:2112
	v_addc_co_u32_e32 v87, vcc, 0, v35, vcc
	global_load_dwordx4 v[34:37], v[42:43], off offset:64
	global_load_dwordx4 v[38:41], v[42:43], off offset:2048
	s_nop 0
	global_load_dwordx4 v[42:45], v[42:43], off offset:2112
	v_lshlrev_b32_e32 v158, 7, v79
	ds_read_b128 v[78:81], v100 offset:35200
	ds_read_b128 v[82:85], v100 offset:35840
	ds_read_b128 v[90:93], v100 offset:36480
	v_cmp_lt_i32_e64 s[10:11], 0, v94
	v_cmp_gt_i32_e32 vcc, s33, v94
	ds_read_b128 v[94:97], v99 offset:768
	s_waitcnt lgkmcnt(3)
	v_cndmask_b32_e64 v101, 0, v81, s[10:11]
	v_cndmask_b32_e64 v78, 0, v78, s[10:11]
	s_waitcnt lgkmcnt(1)
	v_cndmask_b32_e32 v81, 0, v90, vcc
	v_and_b32_e32 v90, 0xffff0000, v81
	v_and_b32_e32 v136, 0xffff0000, v78
	v_add_f32_e32 v90, v90, v136
	v_and_b32_e32 v140, 0xffff0000, v82
	v_fma_f32 v90, v90, 0.5, -v140
	ds_read_b128 v[136:139], v99 offset:784
	s_waitcnt lgkmcnt(1)
	v_fmac_f32_e32 v140, v95, v90
	v_add_f32_e32 v90, v140, v140
	v_lshlrev_b32_e32 v78, 16, v78
	v_lshlrev_b32_e32 v81, 16, v81
	v_mul_f32_e32 v90, 0x3fb8aa3b, v90
	v_add_f32_e32 v78, v81, v78
	v_lshlrev_b32_e32 v81, 16, v82
	v_exp_f32_e32 v90, v90
	v_fma_f32 v78, v78, 0.5, -v81
	v_fmac_f32_e32 v81, v94, v78
	v_add_f32_e32 v78, v81, v81
	v_cndmask_b32_e64 v79, 0, v79, s[10:11]
	v_mul_f32_e32 v78, 0x3fb8aa3b, v78
	v_cndmask_b32_e32 v82, 0, v91, vcc
	v_exp_f32_e32 v81, v78
	v_add_f32_e32 v78, 1.0, v90
	v_and_b32_e32 v90, 0xffff0000, v82
	v_and_b32_e32 v91, 0xffff0000, v79
	v_lshlrev_b32_e32 v79, 16, v79
	v_lshlrev_b32_e32 v82, 16, v82
	v_add_f32_e32 v79, v82, v79
	v_lshlrev_b32_e32 v82, 16, v83
	v_add_f32_e32 v90, v90, v91
	v_and_b32_e32 v91, 0xffff0000, v83
	v_fma_f32 v79, v79, 0.5, -v82
	v_fma_f32 v90, v90, 0.5, -v91
	v_fmac_f32_e32 v82, v96, v79
	v_fmac_f32_e32 v91, v97, v90
	v_add_f32_e32 v79, v82, v82
	v_add_f32_e32 v90, v91, v91
	v_mul_f32_e32 v79, 0x3fb8aa3b, v79
	v_mul_f32_e32 v90, 0x3fb8aa3b, v90
	v_exp_f32_e32 v83, v79
	v_exp_f32_e32 v90, v90
	v_add_f32_e32 v81, 1.0, v81
	v_rcp_f32_e32 v82, v81
	v_add_f32_e32 v81, 1.0, v83
	v_add_f32_e32 v79, 1.0, v90
	v_rcp_f32_e32 v83, v81
	v_rcp_f32_e32 v78, v78
	v_rcp_f32_e32 v79, v79
	v_cndmask_b32_e64 v90, 0, v80, s[10:11]
	v_pk_fma_f32 v[80:81], v[82:83], 2.0, 1.0 op_sel_hi:[1,0,0] neg_lo:[1,0,0] neg_hi:[1,0,0]
	v_cndmask_b32_e32 v91, 0, v92, vcc
	v_pk_fma_f32 v[78:79], v[78:79], 2.0, 1.0 op_sel_hi:[1,0,0] neg_lo:[1,0,0] neg_hi:[1,0,0]
	v_and_b32_sdwa v83, v80, v213 dst_sel:DWORD dst_unused:UNUSED_PAD src0_sel:WORD_1 src1_sel:DWORD
	v_add3_u32 v92, v80, v83, s46
	v_cvt_pk_bf16_f32 v79, v81, v79
	v_and_b32_sdwa v81, v78, v213 dst_sel:DWORD dst_unused:UNUSED_PAD src0_sel:WORD_1 src1_sel:DWORD
	v_add3_u32 v78, v78, v81, s46
	v_and_b32_e32 v80, 0xffff0000, v91
	v_and_b32_e32 v81, 0xffff0000, v90
	v_add_f32_e32 v80, v80, v81
	v_and_b32_e32 v81, 0xffff0000, v84
	v_fma_f32 v80, v80, 0.5, -v81
	s_waitcnt lgkmcnt(0)
	v_fmac_f32_e32 v81, v137, v80
	v_add_f32_e32 v80, v81, v81
	v_lshlrev_b32_e32 v81, 16, v90
	v_lshlrev_b32_e32 v82, 16, v91
	v_add_f32_e32 v81, v82, v81
	v_lshlrev_b32_e32 v82, 16, v84
	v_fma_f32 v81, v81, 0.5, -v82
	v_cndmask_b32_e32 v93, 0, v93, vcc
	v_fmac_f32_e32 v82, v136, v81
	v_add_f32_e32 v81, v82, v82
	v_and_b32_e32 v82, 0xffff0000, v93
	v_and_b32_e32 v83, 0xffff0000, v101
	v_add_f32_e32 v82, v82, v83
	v_and_b32_e32 v83, 0xffff0000, v85
	v_fma_f32 v82, v82, 0.5, -v83
	v_fmac_f32_e32 v83, v82, v139
	v_add_f32_e32 v82, v83, v83
	v_mul_f32_e32 v82, 0x3fb8aa3b, v82
	v_exp_f32_e32 v83, v82
	v_lshlrev_b32_e32 v82, 16, v101
	v_lshlrev_b32_e32 v84, 16, v93
	v_add_f32_e32 v82, v84, v82
	v_lshlrev_b32_e32 v84, 16, v85
	v_fma_f32 v82, v82, 0.5, -v84
	v_mul_f32_e32 v81, 0x3fb8aa3b, v81
	v_fmac_f32_e32 v84, v82, v138
	v_exp_f32_e32 v81, v81
	v_add_f32_e32 v82, v84, v84
	v_mul_f32_e32 v80, 0x3fb8aa3b, v80
	v_mul_f32_e32 v82, 0x3fb8aa3b, v82
	v_exp_f32_e32 v80, v80
	v_exp_f32_e32 v84, v82
	v_add_f32_e32 v81, 1.0, v81
	v_rcp_f32_e32 v82, v81
	v_add_f32_e32 v81, 1.0, v83
	v_add_f32_e32 v80, 1.0, v80
	v_rcp_f32_e32 v83, v81
	v_add_f32_e32 v81, 1.0, v84
	v_rcp_f32_e32 v80, v80
	v_rcp_f32_e32 v81, v81
	v_pk_fma_f32 v[82:83], v[82:83], 2.0, 1.0 op_sel_hi:[1,0,0] neg_lo:[1,0,0] neg_hi:[1,0,0]
	v_and_b32_e32 v78, 0xffff0000, v78
	v_pk_fma_f32 v[80:81], v[80:81], 2.0, 1.0 op_sel_hi:[1,0,0] neg_lo:[1,0,0] neg_hi:[1,0,0]
	v_add3_u32 v159, s34, v158, v106
	v_or_b32_sdwa v78, v78, v92 dst_sel:DWORD dst_unused:UNUSED_PAD src0_sel:DWORD src1_sel:WORD_1
	v_cvt_pk_bf16_f32 v81, v81, v83
	v_cvt_pk_bf16_f32 v80, v82, v80
	ds_write_b128 v159, v[78:81] offset:16384
	ds_read_b128 v[90:93], v100 offset:35328
	global_load_dwordx4 v[82:85], v[86:87], off offset:-4096
	global_load_dwordx4 v[78:81], v[86:87], off
	ds_read_b128 v[94:97], v100 offset:35968
	ds_read_b128 v[136:139], v100 offset:36608
	s_add_i32 s15, s15, s60
	s_sub_i32 s17, s71, s15
	s_waitcnt lgkmcnt(2)
	v_cndmask_b32_e64 v100, 0, v92, s[10:11]
	v_cndmask_b32_e64 v144, 0, v91, s[10:11]
	v_cndmask_b32_e64 v146, 0, v90, s[10:11]
	v_cndmask_b32_e64 v145, 0, v93, s[10:11]
	ds_read_b128 v[90:93], v99 offset:1024
	ds_read_b128 v[140:143], v99 offset:1040
	s_waitcnt lgkmcnt(2)
	v_cndmask_b32_e32 v155, 0, v137, vcc
	v_cndmask_b32_e32 v136, 0, v136, vcc
	v_and_b32_e32 v148, 0xffff0000, v146
	v_and_b32_e32 v150, 0xffff0000, v136
	v_and_b32_e32 v149, 0xffff0000, v144
	v_and_b32_e32 v151, 0xffff0000, v155
	v_pk_add_f32 v[148:149], v[148:149], v[150:151]
	v_and_b32_e32 v151, 0xffff0000, v95
	v_and_b32_e32 v150, 0xffff0000, v94
	v_pk_fma_f32 v[148:149], v[148:149], 0.5, v[150:151] op_sel_hi:[1,0,1] neg_lo:[0,0,1] neg_hi:[0,0,1]
	s_waitcnt lgkmcnt(1)
	v_mov_b32_e32 v156, v91
	v_mov_b32_e32 v157, v93
	v_pk_fma_f32 v[148:149], v[156:157], v[148:149], v[150:151]
	v_lshlrev_b32_e32 v152, 16, v146
	v_lshlrev_b32_e32 v154, 16, v136
	v_lshlrev_b32_e32 v153, 16, v144
	v_lshlrev_b32_e32 v155, 16, v155
	v_and_b32_sdwa v91, v149, v213 dst_sel:DWORD dst_unused:UNUSED_PAD src0_sel:WORD_1 src1_sel:DWORD
	v_and_b32_sdwa v93, v148, v213 dst_sel:DWORD dst_unused:UNUSED_PAD src0_sel:WORD_1 src1_sel:DWORD
	v_add3_u32 v91, v149, v91, s46
	v_add3_u32 v93, v148, v93, s46
	v_pk_add_f32 v[148:149], v[152:153], v[154:155]
	v_lshlrev_b32_e32 v95, 16, v95
	v_lshlrev_b32_e32 v94, 16, v94
	v_and_b32_e32 v136, 0xffff0000, v91
	v_pk_fma_f32 v[148:149], v[148:149], 0.5, v[94:95] op_sel_hi:[1,0,1] neg_lo:[0,0,1] neg_hi:[0,0,1]
	v_mov_b32_e32 v91, v92
	v_pk_fma_f32 v[90:91], v[90:91], v[148:149], v[94:95]
	v_cndmask_b32_e32 v160, 0, v138, vcc
	v_cndmask_b32_e32 v147, 0, v139, vcc
	v_and_b32_sdwa v94, v90, v213 dst_sel:DWORD dst_unused:UNUSED_PAD src0_sel:WORD_1 src1_sel:DWORD
	v_and_b32_e32 v101, 0xffff0000, v145
	v_and_b32_e32 v137, 0xffff0000, v147
	v_lshlrev_b32_e32 v145, 16, v145
	v_lshlrev_b32_e32 v147, 16, v147
	v_and_b32_e32 v93, 0xffff0000, v93
	v_and_b32_sdwa v92, v91, v213 dst_sel:DWORD dst_unused:UNUSED_PAD src0_sel:WORD_1 src1_sel:DWORD
	v_add3_u32 v90, v90, v94, s46
	v_and_b32_e32 v144, 0xffff0000, v100
	v_and_b32_e32 v146, 0xffff0000, v160
	v_add3_u32 v91, v91, v92, s46
	v_or_b32_sdwa v90, v93, v90 dst_sel:DWORD dst_unused:UNUSED_PAD src0_sel:DWORD src1_sel:WORD_1
	v_pk_add_f32 v[92:93], v[144:145], v[146:147]
	v_and_b32_e32 v94, 0xffff0000, v96
	v_lshlrev_b32_e32 v95, 16, v97
	s_waitcnt lgkmcnt(0)
	v_mov_b32_e32 v138, v141
	v_mov_b32_e32 v139, v142
	v_or_b32_sdwa v91, v136, v91 dst_sel:DWORD dst_unused:UNUSED_PAD src0_sel:DWORD src1_sel:WORD_1
	v_lshlrev_b32_e32 v100, 16, v100
	v_lshlrev_b32_e32 v136, 16, v160
	v_pk_fma_f32 v[92:93], v[92:93], 0.5, v[94:95] op_sel_hi:[1,0,1] neg_lo:[0,0,1] neg_hi:[0,0,1]
	v_lshlrev_b32_e32 v96, 16, v96
	v_pk_fma_f32 v[92:93], v[92:93], v[138:139], v[94:95]
	v_pk_add_f32 v[94:95], v[100:101], v[136:137]
	v_and_b32_e32 v97, 0xffff0000, v97
	v_pk_fma_f32 v[94:95], v[94:95], 0.5, v[96:97] op_sel_hi:[1,0,1] neg_lo:[0,0,1] neg_hi:[0,0,1]
	v_mov_b32_e32 v141, v143
	v_pk_fma_f32 v[94:95], v[94:95], v[140:141], v[96:97]
	s_and_b64 s[10:11], s[8:9], exec
	s_cselect_b32 s10, s15, s17
	v_add_u32_e32 v96, s10, v89
	v_cvt_pk_bf16_f32 v93, v93, v95
	v_cvt_pk_bf16_f32 v92, v94, v92
	v_subrev_u32_e32 v89, s16, v96
	ds_write_b128 v159, v[90:93] offset:24576
	v_mad_u64_u32 v[100:101], s[10:11], v89, s58, v[88:89]
	ds_read_b128 v[88:91], v100 offset:35200
	ds_read_b128 v[92:95], v100 offset:35840
	ds_read_b128 v[136:139], v100 offset:36480
	v_cmp_lt_i32_e64 s[10:11], 0, v96
	v_cmp_gt_i32_e32 vcc, s33, v96
	ds_read_b128 v[140:143], v99 offset:768
	ds_read_b128 v[144:147], v99 offset:784
	s_waitcnt lgkmcnt(4)
	v_cndmask_b32_e64 v97, 0, v91, s[10:11]
	v_cndmask_b32_e64 v88, 0, v88, s[10:11]
	s_waitcnt lgkmcnt(2)
	v_cndmask_b32_e32 v91, 0, v136, vcc
	v_and_b32_e32 v101, 0xffff0000, v91
	v_and_b32_e32 v136, 0xffff0000, v88
	v_add_f32_e32 v101, v101, v136
	v_and_b32_e32 v136, 0xffff0000, v92
	v_fma_f32 v101, v101, 0.5, -v136
	s_waitcnt lgkmcnt(1)
	v_fmac_f32_e32 v136, v141, v101
	v_add_f32_e32 v101, v136, v136
	v_lshlrev_b32_e32 v88, 16, v88
	v_lshlrev_b32_e32 v91, 16, v91
	v_mul_f32_e32 v101, 0x3fb8aa3b, v101
	v_add_f32_e32 v88, v91, v88
	v_lshlrev_b32_e32 v91, 16, v92
	v_exp_f32_e32 v101, v101
	v_fma_f32 v88, v88, 0.5, -v91
	v_fmac_f32_e32 v91, v140, v88
	v_add_f32_e32 v88, v91, v91
	v_cndmask_b32_e64 v89, 0, v89, s[10:11]
	v_mul_f32_e32 v88, 0x3fb8aa3b, v88
	v_cndmask_b32_e32 v92, 0, v137, vcc
	v_exp_f32_e32 v91, v88
	v_add_f32_e32 v88, 1.0, v101
	v_and_b32_e32 v101, 0xffff0000, v92
	v_and_b32_e32 v136, 0xffff0000, v89
	v_lshlrev_b32_e32 v89, 16, v89
	v_lshlrev_b32_e32 v92, 16, v92
	v_add_f32_e32 v89, v92, v89
	v_lshlrev_b32_e32 v92, 16, v93
	v_add_f32_e32 v101, v101, v136
	v_and_b32_e32 v136, 0xffff0000, v93
	v_fma_f32 v89, v89, 0.5, -v92
	v_fma_f32 v101, v101, 0.5, -v136
	v_fmac_f32_e32 v92, v142, v89
	v_fmac_f32_e32 v136, v143, v101
	v_add_f32_e32 v89, v92, v92
	v_add_f32_e32 v101, v136, v136
	v_mul_f32_e32 v89, 0x3fb8aa3b, v89
	v_mul_f32_e32 v101, 0x3fb8aa3b, v101
	v_exp_f32_e32 v93, v89
	v_exp_f32_e32 v101, v101
	v_add_f32_e32 v91, 1.0, v91
	v_rcp_f32_e32 v92, v91
	v_add_f32_e32 v91, 1.0, v93
	v_add_f32_e32 v89, 1.0, v101
	v_rcp_f32_e32 v93, v91
	v_rcp_f32_e32 v88, v88
	v_rcp_f32_e32 v89, v89
	v_cndmask_b32_e64 v101, 0, v90, s[10:11]
	v_pk_fma_f32 v[90:91], v[92:93], 2.0, 1.0 op_sel_hi:[1,0,0] neg_lo:[1,0,0] neg_hi:[1,0,0]
	v_cndmask_b32_e32 v136, 0, v138, vcc
	v_pk_fma_f32 v[88:89], v[88:89], 2.0, 1.0 op_sel_hi:[1,0,0] neg_lo:[1,0,0] neg_hi:[1,0,0]
	v_and_b32_sdwa v93, v90, v213 dst_sel:DWORD dst_unused:UNUSED_PAD src0_sel:WORD_1 src1_sel:DWORD
	v_add3_u32 v137, v90, v93, s46
	v_cvt_pk_bf16_f32 v89, v91, v89
	v_and_b32_sdwa v91, v88, v213 dst_sel:DWORD dst_unused:UNUSED_PAD src0_sel:WORD_1 src1_sel:DWORD
	v_add3_u32 v88, v88, v91, s46
	v_and_b32_e32 v90, 0xffff0000, v136
	v_and_b32_e32 v91, 0xffff0000, v101
	v_add_f32_e32 v90, v90, v91
	v_and_b32_e32 v91, 0xffff0000, v94
	v_fma_f32 v90, v90, 0.5, -v91
	s_waitcnt lgkmcnt(0)
	v_fmac_f32_e32 v91, v145, v90
	v_add_f32_e32 v90, v91, v91
	v_lshlrev_b32_e32 v91, 16, v101
	v_lshlrev_b32_e32 v92, 16, v136
	v_add_f32_e32 v91, v92, v91
	v_lshlrev_b32_e32 v92, 16, v94
	v_fma_f32 v91, v91, 0.5, -v92
	v_cndmask_b32_e32 v96, 0, v139, vcc
	v_fmac_f32_e32 v92, v144, v91
	v_add_f32_e32 v91, v92, v92
	v_and_b32_e32 v92, 0xffff0000, v96
	v_and_b32_e32 v93, 0xffff0000, v97
	v_add_f32_e32 v92, v92, v93
	v_and_b32_e32 v93, 0xffff0000, v95
	v_fma_f32 v92, v92, 0.5, -v93
	v_fmac_f32_e32 v93, v92, v147
	v_add_f32_e32 v92, v93, v93
	v_mul_f32_e32 v92, 0x3fb8aa3b, v92
	v_exp_f32_e32 v93, v92
	v_lshlrev_b32_e32 v92, 16, v97
	v_lshlrev_b32_e32 v94, 16, v96
	v_add_f32_e32 v92, v94, v92
	v_lshlrev_b32_e32 v94, 16, v95
	v_fma_f32 v92, v92, 0.5, -v94
	v_mul_f32_e32 v91, 0x3fb8aa3b, v91
	v_fmac_f32_e32 v94, v92, v146
	v_exp_f32_e32 v91, v91
	v_add_f32_e32 v92, v94, v94
	v_mul_f32_e32 v90, 0x3fb8aa3b, v90
	v_mul_f32_e32 v92, 0x3fb8aa3b, v92
	v_exp_f32_e32 v90, v90
	v_exp_f32_e32 v94, v92
	v_add_f32_e32 v91, 1.0, v91
	v_rcp_f32_e32 v92, v91
	v_add_f32_e32 v91, 1.0, v93
	v_add_f32_e32 v90, 1.0, v90
	v_rcp_f32_e32 v93, v91
	v_add_f32_e32 v91, 1.0, v94
	v_rcp_f32_e32 v90, v90
	v_rcp_f32_e32 v91, v91
	v_pk_fma_f32 v[92:93], v[92:93], 2.0, 1.0 op_sel_hi:[1,0,0] neg_lo:[1,0,0] neg_hi:[1,0,0]
	v_and_b32_e32 v88, 0xffff0000, v88
	v_pk_fma_f32 v[90:91], v[90:91], 2.0, 1.0 op_sel_hi:[1,0,0] neg_lo:[1,0,0] neg_hi:[1,0,0]
	v_add3_u32 v106, s61, v158, v106
	v_or_b32_sdwa v88, v88, v137 dst_sel:DWORD dst_unused:UNUSED_PAD src0_sel:DWORD src1_sel:WORD_1
	v_cvt_pk_bf16_f32 v91, v91, v93
	v_cvt_pk_bf16_f32 v90, v92, v90
	ds_write_b128 v106, v[88:91] offset:16384
	ds_read_b128 v[136:139], v100 offset:35328
	global_load_dwordx4 v[94:97], v[86:87], off offset:64
	global_load_dwordx4 v[90:93], v[86:87], off offset:2048
	s_nop 0
	global_load_dwordx4 v[86:89], v[86:87], off offset:2112
	ds_read_b128 v[140:143], v100 offset:35968
	ds_read_b128 v[144:147], v100 offset:36608
	s_waitcnt lgkmcnt(2)
	v_cndmask_b32_e64 v100, 0, v138, s[10:11]
	v_cndmask_b32_e64 v152, 0, v137, s[10:11]
	v_cndmask_b32_e64 v154, 0, v136, s[10:11]
	v_cndmask_b32_e64 v153, 0, v139, s[10:11]
	ds_read_b128 v[136:139], v99 offset:1024
	ds_read_b128 v[148:151], v99 offset:1040
	s_waitcnt lgkmcnt(2)
	v_cndmask_b32_e32 v163, 0, v145, vcc
	v_cndmask_b32_e32 v99, 0, v144, vcc
	v_and_b32_e32 v156, 0xffff0000, v154
	v_and_b32_e32 v158, 0xffff0000, v99
	v_and_b32_e32 v157, 0xffff0000, v152
	v_and_b32_e32 v159, 0xffff0000, v163
	v_pk_add_f32 v[156:157], v[156:157], v[158:159]
	v_and_b32_e32 v159, 0xffff0000, v141
	v_and_b32_e32 v158, 0xffff0000, v140
	v_pk_fma_f32 v[156:157], v[156:157], 0.5, v[158:159] op_sel_hi:[1,0,1] neg_lo:[0,0,1] neg_hi:[0,0,1]
	s_waitcnt lgkmcnt(1)
	v_mov_b32_e32 v164, v137
	v_mov_b32_e32 v165, v139
	v_pk_fma_f32 v[156:157], v[164:165], v[156:157], v[158:159]
	v_lshlrev_b32_e32 v160, 16, v154
	v_lshlrev_b32_e32 v162, 16, v99
	v_lshlrev_b32_e32 v161, 16, v152
	v_lshlrev_b32_e32 v163, 16, v163
	v_and_b32_sdwa v99, v157, v213 dst_sel:DWORD dst_unused:UNUSED_PAD src0_sel:WORD_1 src1_sel:DWORD
	v_and_b32_sdwa v137, v156, v213 dst_sel:DWORD dst_unused:UNUSED_PAD src0_sel:WORD_1 src1_sel:DWORD
	v_add3_u32 v99, v157, v99, s46
	v_add3_u32 v137, v156, v137, s46
	v_pk_add_f32 v[156:157], v[160:161], v[162:163]
	v_lshlrev_b32_e32 v141, 16, v141
	v_lshlrev_b32_e32 v140, 16, v140
	v_and_b32_e32 v139, 0xffff0000, v137
	v_pk_fma_f32 v[156:157], v[156:157], 0.5, v[140:141] op_sel_hi:[1,0,1] neg_lo:[0,0,1] neg_hi:[0,0,1]
	v_mov_b32_e32 v137, v138
	v_pk_fma_f32 v[136:137], v[136:137], v[156:157], v[140:141]
	v_cndmask_b32_e32 v168, 0, v146, vcc
	v_cndmask_b32_e32 v144, 0, v147, vcc
	v_and_b32_sdwa v140, v136, v213 dst_sel:DWORD dst_unused:UNUSED_PAD src0_sel:WORD_1 src1_sel:DWORD
	v_and_b32_e32 v101, 0xffff0000, v153
	v_lshlrev_b32_e32 v153, 16, v153
	v_lshlrev_b32_e32 v155, 16, v144
	v_and_b32_sdwa v138, v137, v213 dst_sel:DWORD dst_unused:UNUSED_PAD src0_sel:WORD_1 src1_sel:DWORD
	v_add3_u32 v136, v136, v140, s46
	v_and_b32_e32 v152, 0xffff0000, v100
	v_and_b32_e32 v154, 0xffff0000, v168
	v_add3_u32 v137, v137, v138, s46
	v_or_b32_sdwa v136, v139, v136 dst_sel:DWORD dst_unused:UNUSED_PAD src0_sel:DWORD src1_sel:WORD_1
	v_pk_add_f32 v[138:139], v[152:153], v[154:155]
	v_and_b32_e32 v140, 0xffff0000, v142
	v_lshlrev_b32_e32 v141, 16, v143
	v_and_b32_e32 v145, 0xffff0000, v144
	s_waitcnt lgkmcnt(0)
	v_mov_b32_e32 v146, v149
	v_mov_b32_e32 v147, v150
	v_lshlrev_b32_e32 v100, 16, v100
	v_lshlrev_b32_e32 v144, 16, v168
	v_pk_fma_f32 v[138:139], v[138:139], 0.5, v[140:141] op_sel_hi:[1,0,1] neg_lo:[0,0,1] neg_hi:[0,0,1]
	v_pk_add_f32 v[100:101], v[100:101], v[144:145]
	v_pk_fma_f32 v[138:139], v[138:139], v[146:147], v[140:141]
	v_lshlrev_b32_e32 v140, 16, v142
	v_and_b32_e32 v141, 0xffff0000, v143
	v_and_b32_e32 v99, 0xffff0000, v99
	v_pk_fma_f32 v[100:101], v[100:101], 0.5, v[140:141] op_sel_hi:[1,0,1] neg_lo:[0,0,1] neg_hi:[0,0,1]
	v_mov_b32_e32 v149, v151
	v_or_b32_sdwa v137, v99, v137 dst_sel:DWORD dst_unused:UNUSED_PAD src0_sel:DWORD src1_sel:WORD_1
	v_pk_fma_f32 v[100:101], v[100:101], v[148:149], v[140:141]
	v_cvt_pk_bf16_f32 v139, v139, v101
	v_and_b32_e32 v99, 15, v98
	v_cvt_pk_bf16_f32 v138, v100, v138
	v_or_b32_e32 v100, s0, v99
	ds_write_b128 v106, v[136:139] offset:24576
	v_and_b32_e32 v101, -16, v98
	v_lshlrev_b32_e32 v100, 7, v100
	s_waitcnt lgkmcnt(0)
	v_add3_u32 v100, 0, v100, v101
	ds_read_b128 v[136:139], v100 offset:16384
	ds_read_b128 v[140:143], v100 offset:16448
	s_waitcnt vmcnt(15) lgkmcnt(1)
	v_mfma_f32_16x16x32_bf16 v[66:69], v[136:139], v[66:69], 0
	s_waitcnt lgkmcnt(0)
	s_waitcnt vmcnt(14) lgkmcnt(0)
	v_mfma_f32_16x16x32_bf16 v[54:57], v[140:143], v[54:57], v[66:69]
	s_nop 5
	v_lshl_add_u32 v66, v99, 2, s14
	v_add_u32_e32 v68, 0x400, v66
	ds_read2_b32 v[66:67], v68 offset0:64 offset1:80
	s_waitcnt vmcnt(9)
	v_mfma_f32_16x16x32_bf16 v[50:53], v[136:139], v[50:53], 0
	v_lshrrev_b32_e32 v69, 2, v98
	v_and_b32_e32 v69, 0x1fffffc, v69
	v_add_lshl_u32 v69, v69, s0, 7
	s_waitcnt lgkmcnt(0)
	v_add_f32_e32 v54, v54, v66
	v_mul_f32_e32 v54, 0xbfb8aa3b, v54
	s_waitcnt vmcnt(8)
	v_mfma_f32_16x16x32_bf16 v[46:49], v[140:143], v[46:49], v[50:53]
	v_exp_f32_e32 v54, v54
	s_nop 1
	v_add_f32_e32 v51, v55, v66
	v_mul_f32_e32 v51, 0xbfb8aa3b, v51
	v_add_f32_e32 v52, v56, v66
	v_exp_f32_e32 v51, v51
	v_mul_f32_e32 v52, 0xbfb8aa3b, v52
	v_exp_f32_e32 v52, v52
	v_mfma_f32_16x16x32_bf16 v[58:61], v[136:139], v[58:61], 0
	v_lshlrev_b32_e32 v50, 1, v99
	v_add3_u32 v69, 0, v69, v50
	v_add_f32_e32 v50, 1.0, v54
	v_rcp_f32_e32 v50, v50
	v_add_f32_e32 v51, 1.0, v51
	v_rcp_f32_e32 v51, v51
	v_add_f32_e32 v52, 1.0, v52
	v_mfma_f32_16x16x32_bf16 v[58:61], v[140:143], v[62:65], v[58:61]
	v_rcp_f32_e32 v52, v52
	v_fma_mixlo_f16 v50, v50, s47, 0
	ds_write_b16 v69, v50 offset:16384
	v_fma_mixlo_f16 v50, v51, s47, 0
	ds_write_b16 v69, v50 offset:16512
	v_fma_mixlo_f16 v50, v52, s47, 0
	v_add_f32_e32 v51, v57, v66
	s_nop 0
	v_add_f32_e32 v52, v58, v67
	v_mul_f32_e32 v51, 0xbfb8aa3b, v51
	v_mul_f32_e32 v52, 0xbfb8aa3b, v52
	v_exp_f32_e32 v51, v51
	v_exp_f32_e32 v52, v52
	ds_write_b16 v69, v50 offset:16640
	v_mfma_f32_16x16x32_bf16 v[62:65], v[136:139], v[74:77], 0
	v_add_f32_e32 v50, 1.0, v51
	v_add_f32_e32 v51, 1.0, v52
	v_add_f32_e32 v52, v59, v67
	v_rcp_f32_e32 v50, v50
	v_mul_f32_e32 v52, 0xbfb8aa3b, v52
	v_rcp_f32_e32 v51, v51
	v_exp_f32_e32 v52, v52
	v_fma_mixlo_f16 v50, v50, s47, 0
	ds_write_b16 v69, v50 offset:16768
	v_fma_mixlo_f16 v50, v51, s47, 0
	v_add_f32_e32 v51, 1.0, v52
	v_add_f32_e32 v52, v60, v67
	v_rcp_f32_e32 v51, v51
	v_mul_f32_e32 v52, 0xbfb8aa3b, v52
	v_exp_f32_e32 v52, v52
	ds_write_b16 v69, v50 offset:16416
	v_fma_mixlo_f16 v50, v51, s47, 0
	ds_write_b16 v69, v50 offset:16544
	v_add_f32_e32 v50, 1.0, v52
	v_rcp_f32_e32 v52, v50
	v_add_f32_e32 v50, v61, v67
	v_mul_f32_e32 v50, 0xbfb8aa3b, v50
	v_exp_f32_e32 v53, v50
	ds_read2_b32 v[50:51], v68 offset0:96 offset1:112
	v_mfma_f32_16x16x32_bf16 v[62:65], v[140:143], v[70:73], v[62:65]
	v_fma_mixlo_f16 v52, v52, s47, 0
	ds_write_b16 v69, v52 offset:16672
	v_add_f32_e32 v52, 1.0, v53
	s_waitcnt lgkmcnt(1)
	v_add_f32_e32 v46, v46, v51
	v_mul_f32_e32 v46, 0xbfb8aa3b, v46
	s_nop 1
	v_add_f32_e32 v53, v62, v50
	v_exp_f32_e32 v46, v46
	v_mul_f32_e32 v53, 0xbfb8aa3b, v53
	v_exp_f32_e32 v53, v53
	v_add_f32_e32 v47, v47, v51
	v_add_f32_e32 v46, 1.0, v46
	v_add_f32_e32 v54, v63, v50
	v_rcp_f32_e32 v46, v46
	v_mul_f32_e32 v47, 0xbfb8aa3b, v47
	v_rcp_f32_e32 v52, v52
	v_mul_f32_e32 v54, 0xbfb8aa3b, v54
	v_add_f32_e32 v53, 1.0, v53
	v_exp_f32_e32 v47, v47
	v_exp_f32_e32 v54, v54
	v_rcp_f32_e32 v53, v53
	v_fma_mixlo_f16 v46, v46, s47, 0
	v_fma_mixlo_f16 v52, v52, s47, 0
	ds_write_b16 v69, v46 offset:16480
	v_add_f32_e32 v46, 1.0, v47
	v_add_f32_e32 v47, v48, v51
	v_add_f32_e32 v54, 1.0, v54
	ds_write_b16 v69, v52 offset:16800
	v_fma_mixlo_f16 v52, v53, s47, 0
	v_add_f32_e32 v53, v64, v50
	v_add_f32_e32 v50, v65, v50
	v_mul_f32_e32 v47, 0xbfb8aa3b, v47
	v_add_f32_e32 v48, v49, v51
	v_rcp_f32_e32 v54, v54
	v_mul_f32_e32 v53, 0xbfb8aa3b, v53
	v_mul_f32_e32 v50, 0xbfb8aa3b, v50
	v_exp_f32_e32 v47, v47
	v_mul_f32_e32 v48, 0xbfb8aa3b, v48
	v_exp_f32_e32 v53, v53
	v_exp_f32_e32 v50, v50
	v_exp_f32_e32 v48, v48
	ds_write_b16 v69, v52 offset:16448
	v_fma_mixlo_f16 v52, v54, s47, 0
	v_rcp_f32_e32 v46, v46
	v_add_f32_e32 v47, 1.0, v47
	ds_write_b16 v69, v52 offset:16576
	v_add_f32_e32 v52, 1.0, v53
	v_add_f32_e32 v50, 1.0, v50
	v_rcp_f32_e32 v47, v47
	v_add_f32_e32 v48, 1.0, v48
	v_rcp_f32_e32 v52, v52
	v_rcp_f32_e32 v50, v50
	v_rcp_f32_e32 v48, v48
	v_fma_mixlo_f16 v46, v46, s47, 0
	ds_write_b16 v69, v46 offset:16608
	v_fma_mixlo_f16 v46, v47, s47, 0
	v_fma_mixlo_f16 v52, v52, s47, 0
	v_fma_mixlo_f16 v50, v50, s47, 0
	ds_write_b16 v69, v46 offset:16736
	v_fma_mixlo_f16 v46, v48, s47, 0
	ds_write_b16 v69, v52 offset:16704
	ds_write_b16 v69, v50 offset:16832
	ds_write_b16 v69, v46 offset:16864
	ds_read_b128 v[46:49], v100 offset:24576
	ds_read_b128 v[50:53], v100 offset:24640
	s_waitcnt vmcnt(4) lgkmcnt(1)
	v_mfma_f32_16x16x32_bf16 v[54:57], v[46:49], v[82:85], 0
	s_waitcnt lgkmcnt(0)
	s_waitcnt lgkmcnt(0)
	v_mfma_f32_16x16x32_bf16 v[34:37], v[50:53], v[34:37], v[54:57]
	s_nop 5
	ds_read2_b32 v[54:55], v68 offset0:128 offset1:144
	v_mfma_f32_16x16x32_bf16 v[38:41], v[46:49], v[38:41], 0
	s_waitcnt lgkmcnt(0)
	v_add_f32_e32 v34, v34, v54
	v_mul_f32_e32 v34, 0xbfb8aa3b, v34
	v_exp_f32_e32 v34, v34
	v_add_f32_e32 v35, v35, v54
	v_mul_f32_e32 v35, 0xbfb8aa3b, v35
	v_exp_f32_e32 v35, v35
	v_add_f32_e32 v34, 1.0, v34
	v_rcp_f32_e32 v34, v34
	v_mfma_f32_16x16x32_bf16 v[38:41], v[50:53], v[42:45], v[38:41]
	v_cvt_f16_f32_e32 v34, v34
	s_waitcnt vmcnt(3)
	v_mfma_f32_16x16x32_bf16 v[42:45], v[46:49], v[78:81], 0
	ds_write_b16 v69, v34 offset:24576
	v_add_f32_e32 v34, 1.0, v35
	v_add_f32_e32 v35, v36, v54
	v_add_f32_e32 v36, v37, v54
	v_mul_f32_e32 v35, 0xbfb8aa3b, v35
	v_mul_f32_e32 v36, 0xbfb8aa3b, v36
	v_exp_f32_e32 v35, v35
	v_exp_f32_e32 v36, v36
	v_rcp_f32_e32 v34, v34
	v_add_f32_e32 v37, v38, v55
	v_add_f32_e32 v35, 1.0, v35
	v_add_f32_e32 v36, 1.0, v36
	v_mul_f32_e32 v37, 0xbfb8aa3b, v37
	v_cvt_f16_f32_e32 v34, v34
	v_rcp_f32_e32 v35, v35
	v_rcp_f32_e32 v36, v36
	v_exp_f32_e32 v37, v37
	ds_write_b16 v69, v34 offset:24704
	v_cvt_f16_f32_e32 v34, v35
	v_cvt_f16_f32_e32 v35, v36
	v_add_f32_e32 v36, 1.0, v37
	v_add_f32_e32 v37, v39, v55
	v_mul_f32_e32 v37, 0xbfb8aa3b, v37
	v_exp_f32_e32 v37, v37
	ds_write_b16 v69, v34 offset:24832
	ds_write_b16 v69, v35 offset:24960
	v_add_f32_e32 v35, v40, v55
	v_mul_f32_e32 v35, 0xbfb8aa3b, v35
	v_add_f32_e32 v34, 1.0, v37
	v_add_f32_e32 v37, v41, v55
	v_rcp_f32_e32 v36, v36
	v_exp_f32_e32 v35, v35
	v_mul_f32_e32 v37, 0xbfb8aa3b, v37
	v_exp_f32_e32 v37, v37
	v_cvt_f16_f32_e32 v36, v36
	v_rcp_f32_e32 v38, v34
	v_add_f32_e32 v34, 1.0, v35
	v_rcp_f32_e32 v39, v34
	v_add_f32_e32 v34, 1.0, v37
	v_rcp_f32_e32 v37, v34
	ds_read2_b32 v[34:35], v68 offset0:160 offset1:176
	s_waitcnt vmcnt(2)
	v_mfma_f32_16x16x32_bf16 v[42:45], v[50:53], v[94:97], v[42:45]
	ds_write_b16 v69, v36 offset:24608
	v_cvt_f16_f32_e32 v36, v38
	v_cvt_f16_f32_e32 v38, v39
	v_cvt_f16_f32_e32 v37, v37
	ds_write_b16 v69, v36 offset:24736
	ds_write_b16 v69, v38 offset:24864
	ds_write_b16 v69, v37 offset:24992
	s_waitcnt lgkmcnt(4)
	v_add_f32_e32 v39, v42, v34
	v_mul_f32_e32 v39, 0xbfb8aa3b, v39
	v_add_f32_e32 v37, v43, v34
	v_exp_f32_e32 v39, v39
	v_mul_f32_e32 v37, 0xbfb8aa3b, v37
	v_add_f32_e32 v38, v44, v34
	v_exp_f32_e32 v37, v37
	v_mul_f32_e32 v38, 0xbfb8aa3b, v38
	v_exp_f32_e32 v38, v38
	v_add_f32_e32 v36, 1.0, v39
	v_add_f32_e32 v34, v45, v34
	s_waitcnt vmcnt(1)
	v_mfma_f32_16x16x32_bf16 v[46:49], v[46:49], v[90:93], 0
	v_rcp_f32_e32 v36, v36
	v_add_f32_e32 v37, 1.0, v37
	v_mul_f32_e32 v34, 0xbfb8aa3b, v34
	v_rcp_f32_e32 v37, v37
	v_add_f32_e32 v38, 1.0, v38
	v_exp_f32_e32 v34, v34
	v_rcp_f32_e32 v38, v38
	s_waitcnt vmcnt(0)
	v_mfma_f32_16x16x32_bf16 v[46:49], v[50:53], v[86:89], v[46:49]
	v_cvt_f16_f32_e32 v36, v36
	v_cvt_f16_f32_e32 v37, v37
	v_add_f32_e32 v34, 1.0, v34
	v_cvt_f16_f32_e32 v38, v38
	v_rcp_f32_e32 v34, v34
	ds_write_b16 v69, v36 offset:24640
	ds_write_b16 v69, v37 offset:24768
	ds_write_b16 v69, v38 offset:24896
	v_add_f32_e32 v36, v46, v35
	v_add_f32_e32 v37, v47, v35
	v_mul_f32_e32 v36, 0xbfb8aa3b, v36
	v_mul_f32_e32 v37, 0xbfb8aa3b, v37
	v_cvt_f16_f32_e32 v34, v34
	v_exp_f32_e32 v36, v36
	v_exp_f32_e32 v37, v37
	ds_write_b16 v69, v34 offset:25024
	v_add_f32_e32 v34, 1.0, v36
	v_add_f32_e32 v36, 1.0, v37
	v_add_f32_e32 v37, v48, v35
	v_mul_f32_e32 v37, 0xbfb8aa3b, v37
	v_add_f32_e32 v35, v49, v35
	v_exp_f32_e32 v37, v37
	v_mul_f32_e32 v35, 0xbfb8aa3b, v35
	v_exp_f32_e32 v35, v35
	v_rcp_f32_e32 v34, v34
	v_rcp_f32_e32 v36, v36
	v_add_f32_e32 v37, 1.0, v37
	v_rcp_f32_e32 v37, v37
	v_add_f32_e32 v35, 1.0, v35
	v_rcp_f32_e32 v35, v35
	v_cvt_f16_f32_e32 v34, v34
	v_cvt_f16_f32_e32 v36, v36
	v_cvt_f16_f32_e32 v37, v37
	v_cvt_f16_f32_e32 v35, v35
	ds_write_b16 v69, v34 offset:24672
	ds_write_b16 v69, v36 offset:24800
	ds_write_b16 v69, v37 offset:24928
	ds_write_b16 v69, v35 offset:25056

.LBB0_585:
	v_add_u32_e32 v139, s2, v132
	s_waitcnt vmcnt(1)
	v_min_i32_e32 v134, 0x4fff, v139
	v_cmp_gt_i32_e32 vcc, s26, v139
	v_cmp_lt_i32_e64 s[4:5], s1, v139
	s_and_saveexec_b64 s[6:7], s[4:5]
	s_xor_b64 s[4:5], exec, s[6:7]
	v_add_u32_e32 v82, 0xfffff000, v134
	v_mov_b32_e32 v83, v111
	v_lshlrev_b64 v[82:83], 11, v[82:83]
	v_lshl_add_u64 v[82:83], s[18:19], 0, v[82:83]
	v_mov_b32_e32 v135, v111
	s_or_saveexec_b64 s[4:5], s[4:5]
	v_mov_b32_e32 v84, 0xfff
	s_xor_b64 exec, exec, s[4:5]
	v_ashrrev_i32_e32 v135, 31, v134
	v_lshlrev_b64 v[82:83], 11, v[134:135]
	v_lshl_add_u64 v[82:83], s[16:17], 0, v[82:83]
	v_mov_b32_e32 v84, 0xff
	s_or_b64 exec, exec, s[4:5]
	v_cndmask_b32_e32 v85, v1, v138, vcc
	v_lshl_add_u64 v[82:83], v[82:83], 0, v[110:111]
	v_and_b32_e32 v85, v85, v134
	global_load_dwordx4 v[90:93], v[82:83], off
	v_lshlrev_b64 v[82:83], 11, v[134:135]
	v_lshl_add_u64 v[86:87], v[114:115], 0, v[82:83]
	v_lshl_add_u64 v[82:83], v[116:117], 0, v[82:83]
	v_cmp_ne_u32_e32 vcc, 0, v85
	global_load_dwordx4 v[94:97], v[86:87], off
	s_nop 0
	global_load_dwordx4 v[86:89], v[82:83], off
	v_subbrev_co_u32_e32 v82, vcc, 0, v134, vcc
	v_cmp_lt_u32_e32 vcc, v85, v84
	v_ashrrev_i32_e32 v83, 31, v82
	v_lshlrev_b64 v[82:83], 11, v[82:83]
	v_addc_co_u32_e32 v84, vcc, 0, v134, vcc
	v_ashrrev_i32_e32 v85, 31, v84
	v_lshlrev_b64 v[84:85], 11, v[84:85]
	v_lshl_add_u64 v[82:83], v[116:117], 0, v[82:83]
	v_lshl_add_u64 v[84:85], v[116:117], 0, v[84:85]
	global_load_dwordx4 v[98:101], v[82:83], off
	global_load_dwordx4 v[102:105], v[84:85], off
	v_max_i32_e32 v84, 0x1000, v134
	v_add_u32_e32 v84, 0xfffff000, v84
	v_mov_b32_e32 v85, v111
	v_lshlrev_b64 v[82:83], 12, v[134:135]
	v_lshlrev_b64 v[84:85], 11, v[84:85]
	v_lshlrev_b64 v[134:135], 7, v[134:135]
	v_lshl_add_u64 v[82:83], v[118:119], 0, v[82:83]
	v_lshl_add_u64 v[106:107], v[120:121], 0, v[84:85]
	v_lshl_add_u64 v[134:135], v[122:123], 0, v[134:135]
	global_load_dwordx4 v[82:85], v[82:83], off
	s_nop 0
	global_load_dwordx4 v[106:109], v[106:107], off
	v_cmp_lt_i32_e64 s[6:7], s1, v132
	global_load_dwordx2 v[134:135], v[134:135], off
	s_waitcnt vmcnt(20)
	v_lshlrev_b32_e32 v140, 16, v38
	v_cndmask_b32_e64 v136, v138, v1, s[6:7]
	v_and_b32_e32 v137, v136, v132
	v_cmp_eq_u32_e32 vcc, 0, v137
	s_waitcnt vmcnt(19)
	v_lshlrev_b32_e32 v141, 16, v42
	v_cmp_eq_u32_e64 s[4:5], v137, v136
	v_cndmask_b32_e64 v140, v140, 0, vcc
	v_and_b32_e32 v137, 0xffff0000, v38
	v_cndmask_b32_e64 v136, v141, 0, s[4:5]
	v_add_f32_e32 v136, v140, v136
	v_and_b32_e32 v140, 0xffff0000, v42
	v_cndmask_b32_e64 v137, v137, 0, vcc
	v_cndmask_b32_e64 v140, v140, 0, s[4:5]
	v_add_f32_e32 v137, v137, v140
	v_mul_f32_e32 v140, 0.5, v137
	v_lshlrev_b32_e32 v143, 16, v27
	v_lshlrev_b32_e32 v142, 16, v26
	v_lshlrev_b32_e32 v145, 16, v31
	v_lshlrev_b32_e32 v144, 16, v30
	s_waitcnt vmcnt(17)
	v_lshlrev_b32_e32 v137, 16, v50
	v_lshlrev_b32_e32 v141, 16, v51
	v_pk_add_f32 v[142:143], v[144:145], v[142:143]
	v_cndmask_b32_e64 v145, 0, v141, s[6:7]
	v_cndmask_b32_e64 v144, 0, v137, s[6:7]
	v_pk_add_f32 v[142:143], v[144:145], v[142:143]
	v_and_b32_e32 v145, 0xffff0000, v27
	v_and_b32_e32 v144, 0xffff0000, v26
	v_and_b32_e32 v147, 0xffff0000, v31
	v_and_b32_e32 v146, 0xffff0000, v30
	v_and_b32_e32 v137, 0xffff0000, v51
	v_and_b32_e32 v141, 0xffff0000, v50
	v_pk_add_f32 v[144:145], v[146:147], v[144:145]
	v_cndmask_b32_e64 v147, 0, v137, s[6:7]
	v_cndmask_b32_e64 v146, 0, v141, s[6:7]
	v_pk_add_f32 v[144:145], v[146:147], v[144:145]
	v_lshlrev_b32_e32 v141, 16, v43
	v_pk_add_f32 v[146:147], v[142:143], v[144:145]
	v_cndmask_b32_e64 v141, v141, 0, s[4:5]
	v_add_f32_e32 v137, 0, v146
	v_add_f32_e32 v147, v147, v137
	v_lshlrev_b32_e32 v137, 16, v39
	v_cndmask_b32_e64 v137, v137, 0, vcc
	v_add_f32_e32 v137, v137, v141
	v_and_b32_e32 v141, 0xffff0000, v39
	v_and_b32_e32 v146, 0xffff0000, v43
	v_cndmask_b32_e64 v141, v141, 0, vcc
	v_cndmask_b32_e64 v146, v146, 0, s[4:5]
	v_add_f32_e32 v141, v141, v146
	v_lshlrev_b32_e32 v146, 16, v40
	v_lshlrev_b32_e32 v148, 16, v44
	v_cndmask_b32_e64 v146, v146, 0, vcc
	v_cndmask_b32_e64 v148, v148, 0, s[4:5]
	v_add_f32_e32 v146, v146, v148
	v_and_b32_e32 v148, 0xffff0000, v40
	v_and_b32_e32 v149, 0xffff0000, v44
	v_cndmask_b32_e64 v148, v148, 0, vcc
	v_cndmask_b32_e64 v149, v149, 0, s[4:5]
	v_lshlrev_b32_e32 v151, 16, v29
	v_lshlrev_b32_e32 v150, 16, v28
	v_lshlrev_b32_e32 v153, 16, v33
	v_lshlrev_b32_e32 v152, 16, v32
	v_add_f32_e32 v148, v148, v149
	v_pk_add_f32 v[150:151], v[152:153], v[150:151]
	v_lshlrev_b32_e32 v149, 16, v52
	v_lshlrev_b32_e32 v152, 16, v53
	v_cndmask_b32_e64 v153, 0, v152, s[6:7]
	v_cndmask_b32_e64 v152, 0, v149, s[6:7]
	v_pk_add_f32 v[150:151], v[152:153], v[150:151]
	v_and_b32_e32 v153, 0xffff0000, v29
	v_and_b32_e32 v152, 0xffff0000, v28
	v_and_b32_e32 v155, 0xffff0000, v33
	v_and_b32_e32 v154, 0xffff0000, v32
	v_pk_add_f32 v[152:153], v[154:155], v[152:153]
	v_and_b32_e32 v149, 0xffff0000, v53
	v_and_b32_e32 v154, 0xffff0000, v52
	v_cndmask_b32_e64 v155, 0, v149, s[6:7]
	v_cndmask_b32_e64 v154, 0, v154, s[6:7]
	v_pk_add_f32 v[152:153], v[154:155], v[152:153]
	v_lshlrev_b32_e32 v149, 16, v45
	v_pk_add_f32 v[154:155], v[150:151], v[152:153]
	v_cndmask_b32_e64 v149, v149, 0, s[4:5]
	v_add_f32_e32 v147, v154, v147
	v_add_f32_e32 v154, v155, v147
	v_lshlrev_b32_e32 v147, 16, v41
	v_and_b32_e32 v155, 0xffff0000, v45
	v_add_f32_dpp v154, v154, v154 quad_perm:[1,0,3,2] row_mask:0xf bank_mask:0xf bound_ctrl:1
	v_cndmask_b32_e64 v147, v147, 0, vcc
	v_cndmask_b32_e64 v155, v155, 0, s[4:5]
	v_add_f32_dpp v154, v154, v154 quad_perm:[2,3,0,1] row_mask:0xf bank_mask:0xf bound_ctrl:1
	v_add_f32_e32 v147, v147, v149
	v_and_b32_e32 v149, 0xffff0000, v41
	v_add_f32_dpp v154, v154, v154 row_half_mirror row_mask:0xf bank_mask:0xf bound_ctrl:1
	v_mul_f32_e32 v154, 0x3c800000, v154
	v_pk_add_f32 v[142:143], v[142:143], v[154:155] op_sel_hi:[1,0] neg_lo:[0,1] neg_hi:[0,1]
	v_pk_add_f32 v[144:145], v[144:145], v[154:155] op_sel_hi:[1,0] neg_lo:[0,1] neg_hi:[0,1]
	v_cndmask_b32_e64 v149, v149, 0, vcc
	v_mov_b32_e32 v160, v142
	v_mov_b32_e32 v161, v144
	v_mul_f32_e32 v146, 0.5, v146
	v_add_f32_e32 v149, v149, v155
	v_mul_f32_e32 v147, 0.5, v147
	v_pk_mul_f32 v[160:161], v[160:161], v[160:161]
	v_mov_b32_e32 v162, v145
	v_mov_b32_e32 v163, v143
	v_lshlrev_b32_e32 v169, 16, v37
	v_lshlrev_b32_e32 v168, 16, v36
	v_lshlrev_b32_e32 v155, 16, v49
	v_pk_mul_f32 v[162:163], v[162:163], v[162:163]
	v_pk_add_f32 v[146:147], v[146:147], v[168:169] neg_lo:[0,1] neg_hi:[0,1]
	v_pk_add_f32 v[150:151], v[150:151], v[154:155] op_sel_hi:[1,0] neg_lo:[0,1] neg_hi:[0,1]
	v_pk_add_f32 v[152:153], v[152:153], v[154:155] op_sel_hi:[1,0] neg_lo:[0,1] neg_hi:[0,1]
	v_add_f32_e32 v154, v160, v161
	v_mul_f32_e32 v148, 0.5, v148
	v_mul_f32_e32 v149, 0.5, v149
	v_and_b32_e32 v171, 0xffff0000, v37
	v_and_b32_e32 v170, 0xffff0000, v36
	v_pk_fma_f32 v[146:147], v[6:7], v[146:147], v[168:169]
	v_mov_b32_e32 v168, v152
	v_mov_b32_e32 v169, v150
	v_add_f32_e32 v154, v163, v154
	v_pk_add_f32 v[148:149], v[148:149], v[170:171] neg_lo:[0,1] neg_hi:[0,1]
	v_pk_mul_f32 v[168:169], v[168:169], v[168:169]
	v_add_f32_e32 v154, v162, v154
	v_pk_fma_f32 v[148:149], v[8:9], v[148:149], v[170:171]
	v_mov_b32_e32 v170, v153
	v_mov_b32_e32 v171, v151
	v_add_f32_e32 v154, v169, v154
	v_pk_mul_f32 v[170:171], v[170:171], v[170:171]
	v_add_f32_e32 v154, v168, v154
	v_add_f32_e32 v154, v171, v154
	v_add_f32_e32 v154, v170, v154
	v_mul_f32_e32 v136, 0.5, v136
	v_mul_f32_e32 v137, 0.5, v137
	v_add_f32_dpp v154, v154, v154 quad_perm:[1,0,3,2] row_mask:0xf bank_mask:0xf bound_ctrl:1
	v_lshlrev_b32_e32 v157, 16, v35
	v_lshlrev_b32_e32 v156, 16, v34
	v_add_f32_dpp v154, v154, v154 quad_perm:[2,3,0,1] row_mask:0xf bank_mask:0xf bound_ctrl:1
	v_pk_add_f32 v[136:137], v[136:137], v[156:157] neg_lo:[0,1] neg_hi:[0,1]
	v_mul_f32_e32 v141, 0.5, v141
	v_add_f32_dpp v154, v154, v154 row_half_mirror row_mask:0xf bank_mask:0xf bound_ctrl:1
	v_fmamk_f32 v154, v154, 0x3c800000, v133
	v_mul_f32_e32 v160, 0x4b800000, v154
	v_cmp_gt_f32_e32 vcc, s28, v154
	v_and_b32_e32 v159, 0xffff0000, v35
	v_and_b32_e32 v158, 0xffff0000, v34
	v_cndmask_b32_e32 v154, v154, v160, vcc
	v_rsq_f32_e32 v162, v154
	v_pk_fma_f32 v[136:137], v[2:3], v[136:137], v[156:157]
	s_waitcnt vmcnt(16)
	v_pk_add_f32 v[164:165], v[112:113], v[112:113] op_sel:[1,0] op_sel_hi:[1,0]
	v_pk_add_f32 v[140:141], v[140:141], v[158:159] neg_lo:[0,1] neg_hi:[0,1]
	v_mul_f32_e32 v163, 0x45800000, v162
	v_cndmask_b32_e32 v162, v162, v163, vcc
	v_pk_mul_f32 v[142:143], v[142:143], v[162:163] op_sel_hi:[1,0]
	v_pk_fma_f32 v[140:141], v[4:5], v[140:141], v[158:159]
	v_pk_fma_f32 v[142:143], v[18:19], v[142:143], v[22:23]
	v_and_b32_e32 v159, 0xffff0000, v47
	v_pk_fma_f32 v[136:137], v[164:165], v[136:137], v[142:143]
	v_pk_mul_f32 v[142:143], v[144:145], v[162:163] op_sel_hi:[1,0]
	v_pk_mul_f32 v[144:145], v[152:153], v[162:163] op_sel_hi:[1,0]
	v_pk_fma_f32 v[142:143], v[20:21], v[142:143], v[24:25]
	v_pk_fma_f32 v[144:145], v[12:13], v[144:145], v[16:17]
	v_pk_fma_f32 v[140:141], v[164:165], v[140:141], v[142:143]
	v_pk_mul_f32 v[142:143], v[150:151], v[162:163] op_sel_hi:[1,0]
	v_and_b32_e32 v158, 0xffff0000, v46
	v_and_b32_e32 v161, 0xffff0000, v49
	v_and_b32_e32 v160, 0xffff0000, v48
	v_pk_fma_f32 v[142:143], v[10:11], v[142:143], v[14:15]
	v_pk_fma_f32 v[144:145], v[164:165], v[148:149], v[144:145]
	v_lshlrev_b32_e32 v157, 16, v47
	v_lshlrev_b32_e32 v156, 16, v46
	v_lshlrev_b32_e32 v154, 16, v48
	v_pk_mul_f32 v[140:141], v[140:141], v[158:159]
	v_pk_fma_f32 v[142:143], v[164:165], v[146:147], v[142:143]
	v_pk_mul_f32 v[144:145], v[144:145], v[160:161]
	v_pk_mul_f32 v[136:137], v[136:137], v[156:157]
	v_pk_mul_f32 v[142:143], v[142:143], v[154:155]
	v_cvt_pk_bf16_f32 v143, v143, v145
	v_cvt_pk_bf16_f32 v142, v142, v144
	v_cvt_pk_bf16_f32 v141, v137, v141
	v_cvt_pk_bf16_f32 v140, v136, v140
	v_lshl_add_u64 v[136:137], v[130:131], 0, v[124:125]
	global_store_dwordx4 v[136:137], v[140:143], off
	v_add_u32_e32 v136, s0, v132
	v_cmp_lt_i32_e32 vcc, s9, v136
	s_and_saveexec_b64 s[4:5], vcc
	s_xor_b64 s[4:5], exec, s[4:5]
	v_add_u32_e32 v140, s8, v132
	s_andn2_saveexec_b64 s[22:23], s[4:5]
	s_cbranch_execz .LBB0_584
	v_add_u32_e32 v140, s8, v132
	v_min_i32_e32 v112, 0x4fff, v140
	v_cmp_gt_i32_e32 vcc, s26, v140
	v_cmp_lt_i32_e64 s[4:5], s1, v140
	s_and_saveexec_b64 s[6:7], s[4:5]
	s_xor_b64 s[4:5], exec, s[6:7]
	v_add_u32_e32 v26, 0xfffff000, v112
	v_mov_b32_e32 v27, v111
	v_lshlrev_b64 v[26:27], 11, v[26:27]
	v_lshl_add_u64 v[26:27], s[18:19], 0, v[26:27]
	v_mov_b32_e32 v113, v111
	s_or_saveexec_b64 s[4:5], s[4:5]
	v_mov_b32_e32 v38, 0xfff
	s_xor_b64 exec, exec, s[4:5]
	v_ashrrev_i32_e32 v113, 31, v112
	v_lshlrev_b64 v[26:27], 11, v[112:113]
	v_lshl_add_u64 v[26:27], s[16:17], 0, v[26:27]
	v_mov_b32_e32 v38, 0xff
	s_or_b64 exec, exec, s[4:5]
	v_cndmask_b32_e32 v28, v1, v138, vcc
	v_and_b32_e32 v39, v28, v112
	v_cmp_ne_u32_e32 vcc, 0, v39
	v_max_i32_e32 v48, 0x1000, v112
	v_add_u32_e32 v48, 0xfffff000, v48
	v_subbrev_co_u32_e32 v40, vcc, 0, v112, vcc
	v_cmp_lt_u32_e32 vcc, v39, v38
	v_ashrrev_i32_e32 v41, 31, v40
	v_mov_b32_e32 v49, v111
	v_addc_co_u32_e32 v38, vcc, 0, v112, vcc
	v_ashrrev_i32_e32 v39, 31, v38
	v_lshlrev_b64 v[30:31], 11, v[112:113]
	v_lshlrev_b64 v[40:41], 11, v[40:41]
	v_lshlrev_b64 v[38:39], 11, v[38:39]
	v_lshlrev_b64 v[46:47], 12, v[112:113]
	v_lshlrev_b64 v[48:49], 11, v[48:49]
	v_lshlrev_b64 v[112:113], 7, v[112:113]
	v_lshl_add_u64 v[26:27], v[26:27], 0, v[110:111]
	v_lshl_add_u64 v[32:33], v[114:115], 0, v[30:31]
	v_lshl_add_u64 v[34:35], v[116:117], 0, v[30:31]
	v_lshl_add_u64 v[40:41], v[116:117], 0, v[40:41]
	v_lshl_add_u64 v[42:43], v[116:117], 0, v[38:39]
	v_lshl_add_u64 v[46:47], v[118:119], 0, v[46:47]
	v_lshl_add_u64 v[50:51], v[120:121], 0, v[48:49]
	v_lshl_add_u64 v[112:113], v[122:123], 0, v[112:113]
	global_load_dwordx4 v[26:29], v[26:27], off
	s_nop 0
	global_load_dwordx4 v[30:33], v[32:33], off
	s_nop 0
	global_load_dwordx4 v[34:37], v[34:35], off
	s_nop 0
	global_load_dwordx4 v[38:41], v[40:41], off
	s_nop 0
	global_load_dwordx4 v[42:45], v[42:43], off
	s_nop 0
	global_load_dwordx4 v[46:49], v[46:47], off
	s_nop 0
	global_load_dwordx4 v[50:53], v[50:51], off
	v_cmp_lt_i32_e64 s[6:7], s1, v136
	global_load_dwordx2 v[112:113], v[112:113], off
	s_waitcnt vmcnt(20)
	v_lshlrev_b32_e32 v142, 16, v78
	v_cndmask_b32_e64 v137, v138, v1, s[6:7]
	v_and_b32_e32 v141, v137, v136
	v_cmp_eq_u32_e32 vcc, 0, v141
	v_lshlrev_b32_e32 v143, 16, v74
	v_cmp_eq_u32_e64 s[4:5], v141, v137
	v_cndmask_b32_e64 v142, v142, 0, vcc
	v_and_b32_e32 v141, 0xffff0000, v78
	v_cndmask_b32_e64 v137, v143, 0, s[4:5]
	v_add_f32_e32 v137, v142, v137
	v_and_b32_e32 v142, 0xffff0000, v74
	v_cndmask_b32_e64 v141, v141, 0, vcc
	v_cndmask_b32_e64 v142, v142, 0, s[4:5]
	v_add_f32_e32 v141, v141, v142
	v_mul_f32_e32 v142, 0.5, v137
	v_mul_f32_e32 v144, 0.5, v141
	s_waitcnt vmcnt(17)
	v_lshlrev_b32_e32 v147, 16, v63
	v_lshlrev_b32_e32 v146, 16, v62
	v_lshlrev_b32_e32 v149, 16, v71
	v_lshlrev_b32_e32 v148, 16, v70
	v_lshlrev_b32_e32 v137, 16, v54
	v_lshlrev_b32_e32 v141, 16, v55
	v_pk_add_f32 v[146:147], v[148:149], v[146:147]
	v_cndmask_b32_e64 v149, 0, v141, s[6:7]
	v_cndmask_b32_e64 v148, 0, v137, s[6:7]
	v_pk_add_f32 v[146:147], v[146:147], v[148:149]
	v_and_b32_e32 v149, 0xffff0000, v63
	v_and_b32_e32 v148, 0xffff0000, v62
	v_and_b32_e32 v151, 0xffff0000, v71
	v_and_b32_e32 v150, 0xffff0000, v70
	v_and_b32_e32 v141, 0xffff0000, v54
	v_pk_add_f32 v[148:149], v[150:151], v[148:149]
	v_and_b32_e32 v137, 0xffff0000, v55
	v_cndmask_b32_e64 v150, 0, v141, s[6:7]
	v_lshlrev_b32_e32 v141, 16, v79
	v_lshlrev_b32_e32 v143, 16, v75
	v_cndmask_b32_e64 v151, 0, v137, s[6:7]
	v_cndmask_b32_e64 v141, v141, 0, vcc
	v_cndmask_b32_e64 v143, v143, 0, s[4:5]
	v_pk_add_f32 v[148:149], v[148:149], v[150:151]
	v_add_f32_e32 v141, v141, v143
	v_and_b32_e32 v143, 0xffff0000, v79
	v_and_b32_e32 v145, 0xffff0000, v75
	v_pk_add_f32 v[150:151], v[146:147], v[148:149]
	v_cndmask_b32_e64 v143, v143, 0, vcc
	v_cndmask_b32_e64 v145, v145, 0, s[4:5]
	v_add_f32_e32 v137, 0, v150
	v_add_f32_e32 v145, v143, v145
	v_mul_f32_e32 v143, 0.5, v141
	v_lshlrev_b32_e32 v141, 16, v80
	v_lshlrev_b32_e32 v150, 16, v76
	v_cndmask_b32_e64 v141, v141, 0, vcc
	v_cndmask_b32_e64 v150, v150, 0, s[4:5]
	v_add_f32_e32 v137, v151, v137
	v_add_f32_e32 v141, v141, v150
	v_and_b32_e32 v150, 0xffff0000, v80
	v_and_b32_e32 v151, 0xffff0000, v76
	v_cndmask_b32_e64 v150, v150, 0, vcc
	v_cndmask_b32_e64 v151, v151, 0, s[4:5]
	v_add_f32_e32 v151, v150, v151
	v_mul_f32_e32 v150, 0.5, v141
	v_mul_f32_e32 v152, 0.5, v151
	v_lshlrev_b32_e32 v155, 16, v65
	v_lshlrev_b32_e32 v154, 16, v64
	v_lshlrev_b32_e32 v157, 16, v73
	v_lshlrev_b32_e32 v156, 16, v72
	v_lshlrev_b32_e32 v141, 16, v56
	v_lshlrev_b32_e32 v151, 16, v57
	v_pk_add_f32 v[154:155], v[156:157], v[154:155]
	v_cndmask_b32_e64 v157, 0, v151, s[6:7]
	v_cndmask_b32_e64 v156, 0, v141, s[6:7]
	v_pk_add_f32 v[154:155], v[154:155], v[156:157]
	v_and_b32_e32 v157, 0xffff0000, v65
	v_and_b32_e32 v156, 0xffff0000, v64
	v_and_b32_e32 v159, 0xffff0000, v73
	v_and_b32_e32 v158, 0xffff0000, v72
	v_and_b32_e32 v141, 0xffff0000, v57
	v_and_b32_e32 v151, 0xffff0000, v56
	v_pk_add_f32 v[156:157], v[158:159], v[156:157]
	v_cndmask_b32_e64 v159, 0, v141, s[6:7]
	v_cndmask_b32_e64 v158, 0, v151, s[6:7]
	v_pk_add_f32 v[156:157], v[156:157], v[158:159]
	v_lshlrev_b32_e32 v141, 16, v81
	v_pk_add_f32 v[158:159], v[154:155], v[156:157]
	v_lshlrev_b32_e32 v151, 16, v77
	v_add_f32_e32 v137, v158, v137
	v_add_f32_e32 v137, v159, v137
	v_cndmask_b32_e64 v141, v141, 0, vcc
	v_cndmask_b32_e64 v151, v151, 0, s[4:5]
	v_add_f32_dpp v137, v137, v137 quad_perm:[1,0,3,2] row_mask:0xf bank_mask:0xf bound_ctrl:1
	v_add_f32_e32 v141, v141, v151
	v_and_b32_e32 v151, 0xffff0000, v81
	v_add_f32_dpp v137, v137, v137 quad_perm:[2,3,0,1] row_mask:0xf bank_mask:0xf bound_ctrl:1
	v_and_b32_e32 v153, 0xffff0000, v77
	v_cndmask_b32_e64 v151, v151, 0, vcc
	v_add_f32_dpp v137, v137, v137 row_half_mirror row_mask:0xf bank_mask:0xf bound_ctrl:1
	v_mul_f32_e32 v158, 0x3c800000, v137
	v_pk_add_f32 v[146:147], v[146:147], v[158:159] op_sel_hi:[1,0] neg_lo:[0,1] neg_hi:[0,1]
	v_pk_add_f32 v[148:149], v[148:149], v[158:159] op_sel_hi:[1,0] neg_lo:[0,1] neg_hi:[0,1]
	v_cndmask_b32_e64 v153, v153, 0, s[4:5]
	v_mov_b32_e32 v164, v146
	v_mov_b32_e32 v165, v148
	v_add_f32_e32 v153, v151, v153
	v_mul_f32_e32 v151, 0.5, v141
	v_pk_mul_f32 v[164:165], v[164:165], v[164:165]
	v_mov_b32_e32 v168, v149
	v_mov_b32_e32 v169, v147
	v_lshlrev_b32_e32 v173, 16, v69
	v_lshlrev_b32_e32 v172, 16, v68
	v_lshlrev_b32_e32 v159, 16, v61
	v_pk_mul_f32 v[168:169], v[168:169], v[168:169]
	v_pk_add_f32 v[150:151], v[150:151], v[172:173] neg_lo:[0,1] neg_hi:[0,1]
	v_pk_add_f32 v[154:155], v[154:155], v[158:159] op_sel_hi:[1,0] neg_lo:[0,1] neg_hi:[0,1]
	v_pk_add_f32 v[156:157], v[156:157], v[158:159] op_sel_hi:[1,0] neg_lo:[0,1] neg_hi:[0,1]
	v_add_f32_e32 v137, v164, v165
	v_mul_f32_e32 v153, 0.5, v153
	v_and_b32_e32 v175, 0xffff0000, v69
	v_and_b32_e32 v174, 0xffff0000, v68
	v_pk_fma_f32 v[150:151], v[6:7], v[150:151], v[172:173]
	v_mov_b32_e32 v172, v156
	v_mov_b32_e32 v173, v154
	v_add_f32_e32 v137, v169, v137
	v_pk_add_f32 v[152:153], v[152:153], v[174:175] neg_lo:[0,1] neg_hi:[0,1]
	v_pk_mul_f32 v[172:173], v[172:173], v[172:173]
	v_add_f32_e32 v137, v168, v137
	v_pk_fma_f32 v[152:153], v[8:9], v[152:153], v[174:175]
	v_mov_b32_e32 v174, v157
	v_mov_b32_e32 v175, v155
	v_add_f32_e32 v137, v173, v137
	v_pk_mul_f32 v[174:175], v[174:175], v[174:175]
	v_add_f32_e32 v137, v172, v137
	v_add_f32_e32 v137, v175, v137
	v_add_f32_e32 v137, v174, v137
	v_lshlrev_b32_e32 v161, 16, v67
	v_lshlrev_b32_e32 v160, 16, v66
	v_add_f32_dpp v137, v137, v137 quad_perm:[1,0,3,2] row_mask:0xf bank_mask:0xf bound_ctrl:1
	v_pk_add_f32 v[142:143], v[142:143], v[160:161] neg_lo:[0,1] neg_hi:[0,1]
	v_mul_f32_e32 v145, 0.5, v145
	v_add_f32_dpp v137, v137, v137 quad_perm:[2,3,0,1] row_mask:0xf bank_mask:0xf bound_ctrl:1
	v_and_b32_e32 v163, 0xffff0000, v67
	v_and_b32_e32 v162, 0xffff0000, v66
	v_add_f32_dpp v137, v137, v137 row_half_mirror row_mask:0xf bank_mask:0xf bound_ctrl:1
	v_fmamk_f32 v137, v137, 0x3c800000, v133
	v_mul_f32_e32 v141, 0x4b800000, v137
	v_cmp_gt_f32_e32 vcc, s28, v137
	v_pk_fma_f32 v[142:143], v[2:3], v[142:143], v[160:161]
	v_pk_add_f32 v[170:171], v[128:129], v[128:129] op_sel:[0,1] op_sel_hi:[0,1]
	v_cndmask_b32_e32 v137, v137, v141, vcc
	v_rsq_f32_e32 v137, v137
	v_pk_add_f32 v[144:145], v[144:145], v[162:163] neg_lo:[0,1] neg_hi:[0,1]
	v_and_b32_e32 v165, 0xffff0000, v61
	v_pk_fma_f32 v[144:145], v[4:5], v[144:145], v[162:163]
	v_mul_f32_e32 v141, 0x45800000, v137
	v_cndmask_b32_e32 v168, v137, v141, vcc
	v_pk_mul_f32 v[146:147], v[146:147], v[168:169] op_sel_hi:[1,0]
	v_and_b32_e32 v164, 0xffff0000, v60
	v_pk_fma_f32 v[146:147], v[18:19], v[146:147], v[22:23]
	v_and_b32_e32 v163, 0xffff0000, v59
	v_pk_fma_f32 v[142:143], v[170:171], v[142:143], v[146:147]
	v_pk_mul_f32 v[146:147], v[148:149], v[168:169] op_sel_hi:[1,0]
	v_pk_mul_f32 v[148:149], v[156:157], v[168:169] op_sel_hi:[1,0]
	v_pk_fma_f32 v[146:147], v[20:21], v[146:147], v[24:25]
	v_pk_fma_f32 v[148:149], v[12:13], v[148:149], v[16:17]
	v_pk_fma_f32 v[144:145], v[170:171], v[144:145], v[146:147]
	v_pk_mul_f32 v[146:147], v[154:155], v[168:169] op_sel_hi:[1,0]
	v_pk_fma_f32 v[148:149], v[170:171], v[152:153], v[148:149]
	v_pk_fma_f32 v[146:147], v[10:11], v[146:147], v[14:15]
	v_and_b32_e32 v162, 0xffff0000, v58
	v_lshlrev_b32_e32 v158, 16, v60
	v_pk_fma_f32 v[146:147], v[170:171], v[150:151], v[146:147]
	v_pk_mul_f32 v[148:149], v[148:149], v[164:165]
	v_lshlrev_b32_e32 v161, 16, v59
	v_lshlrev_b32_e32 v160, 16, v58
	v_pk_mul_f32 v[144:145], v[144:145], v[162:163]
	v_pk_mul_f32 v[146:147], v[146:147], v[158:159]
	v_pk_mul_f32 v[142:143], v[142:143], v[160:161]
	v_cvt_pk_bf16_f32 v143, v143, v145
	v_cvt_pk_bf16_f32 v142, v142, v144
	v_cvt_pk_bf16_f32 v145, v147, v149
	v_ashrrev_i32_e32 v137, 31, v136
	v_lshlrev_b64 v[136:137], 12, v[136:137]
	v_cvt_pk_bf16_f32 v144, v146, v148
	v_lshl_add_u64 v[136:137], v[118:119], 0, v[136:137]
	v_cmp_gt_i32_e32 vcc, s30, v139
	global_store_dwordx4 v[136:137], v[142:145], off
	s_and_saveexec_b64 s[24:25], vcc
	s_cbranch_execz .LBB0_583
	v_add_u32_e32 v54, s3, v132
	v_min_i32_e32 v128, 0x4fff, v54
	v_cmp_gt_i32_e32 vcc, s26, v54
	v_cmp_lt_i32_e64 s[4:5], s1, v54
	s_and_saveexec_b64 s[6:7], s[4:5]
	s_xor_b64 s[4:5], exec, s[6:7]
	v_add_u32_e32 v54, 0xfffff000, v128
	v_mov_b32_e32 v55, v111
	v_lshlrev_b64 v[54:55], 11, v[54:55]
	v_lshl_add_u64 v[54:55], s[18:19], 0, v[54:55]
	v_mov_b32_e32 v129, v111
	s_or_saveexec_b64 s[4:5], s[4:5]
	v_mov_b32_e32 v56, 0xfff
	s_xor_b64 exec, exec, s[4:5]
	s_cbranch_execz .LBB0_582
	v_ashrrev_i32_e32 v129, 31, v128
	v_lshlrev_b64 v[54:55], 11, v[128:129]
	v_lshl_add_u64 v[54:55], s[16:17], 0, v[54:55]
	v_mov_b32_e32 v56, 0xff
	s_branch .LBB0_582

.LBB0_781:
	v_and_b32_e32 v1, 1, v1
	v_add_u32_e32 v134, 12, v132
	v_cmp_eq_u32_e32 vcc, 0, v1
	v_pk_mul_f32 v[126:127], v[126:127], s[12:13] op_sel_hi:[1,0]
	v_lshlrev_b64 v[136:137], 11, v[136:137]
	v_cndmask_b32_e32 v1, v134, v132, vcc
	v_add_u32_e32 v134, v1, v130
	v_lshl_add_u64 v[136:137], v[170:171], 0, v[136:137]
	v_pk_mul_f32 v[170:171], v[124:125], s[12:13] op_sel_hi:[1,0]
	v_pk_mul_f32 v[124:125], v[122:123], s[12:13] op_sel_hi:[1,0]
	v_cvt_pk_bf16_f32 v122, v126, v127
	v_pk_mul_f32 v[128:129], v[128:129], s[12:13] op_sel_hi:[1,0]
	v_cvt_pk_bf16_f32 v124, v124, v125
	v_cvt_pk_bf16_f32 v123, v128, v129
	v_ashrrev_i32_e32 v135, 31, v134
	v_cvt_pk_bf16_f32 v125, v170, v171
	v_lshl_add_u64 v[136:137], v[134:135], 1, v[136:137]
	v_permlane16_swap_b32_e32 v122, v124
	v_permlane16_swap_b32_e32 v123, v125
	v_pk_mul_f32 v[118:119], v[118:119], s[12:13] op_sel_hi:[1,0]
	global_store_dwordx4 v[136:137], v[122:125], off
	s_nop 1
	v_pk_mul_f32 v[122:123], v[116:117], s[12:13] op_sel_hi:[1,0]
	v_pk_mul_f32 v[116:117], v[114:115], s[12:13] op_sel_hi:[1,0]
	v_cvt_pk_bf16_f32 v114, v118, v119
	v_mov_b32_e32 v124, v107
	v_mov_b32_e32 v125, v111
	v_mov_b32_e32 v118, v106
	v_mov_b32_e32 v119, v110
	v_pk_mul_f32 v[124:125], v[124:125], v[124:125]
	v_mov_b32_e32 v126, v99
	v_pk_fma_f32 v[118:119], v[118:119], v[118:119], v[124:125]
	v_mov_b32_e32 v124, v108
	v_mov_b32_e32 v125, v112
	v_pk_fma_f32 v[118:119], v[124:125], v[124:125], v[118:119]
	v_mov_b32_e32 v124, v109
	v_mov_b32_e32 v125, v113
	v_mov_b32_e32 v127, v103
	v_pk_fma_f32 v[118:119], v[124:125], v[124:125], v[118:119]
	v_mov_b32_e32 v124, v98
	v_mov_b32_e32 v125, v102
	v_pk_mul_f32 v[126:127], v[126:127], v[126:127]
	v_bfe_u32 v115, v117, 16, 1
	v_pk_fma_f32 v[124:125], v[124:125], v[124:125], v[126:127]
	v_mov_b32_e32 v126, v100
	v_mov_b32_e32 v127, v104
	v_pk_fma_f32 v[124:125], v[126:127], v[126:127], v[124:125]
	v_mov_b32_e32 v126, v101
	v_mov_b32_e32 v127, v105
	v_add3_u32 v115, v117, v115, s61
	v_pk_fma_f32 v[124:125], v[126:127], v[126:127], v[124:125]
	v_add_f32_e32 v117, v118, v119
	v_add_f32_e32 v117, v125, v117
	v_add_f32_e32 v117, v124, v117
	ds_bpermute_b32 v118, v173, v117
	v_bfe_u32 v1, v116, 16, 1
	v_add3_u32 v1, v116, v1, s61
	v_pk_mul_f32 v[120:121], v[120:121], s[12:13] op_sel_hi:[1,0]
	v_lshrrev_b32_e32 v1, 16, v1
	v_and_or_b32 v116, v115, s62, v1
	s_waitcnt lgkmcnt(0)
	v_add_f32_e32 v118, v117, v118
	ds_bpermute_b32 v119, v175, v118
	v_cvt_pk_bf16_f32 v115, v120, v121
	v_cvt_pk_bf16_f32 v117, v122, v123
	s_waitcnt lgkmcnt(0)
	v_add_f32_e32 v1, v118, v119
	v_fmamk_f32 v1, v1, 0x3c800000, v179
	v_mul_f32_e32 v118, 0x4b800000, v1
	v_cmp_gt_f32_e32 vcc, s71, v1
	v_permlane16_swap_b32_e32 v114, v116
	s_nop 0
	v_cndmask_b32_e32 v1, v1, v118, vcc
	v_rsq_f32_e32 v1, v1
	v_permlane16_swap_b32_e32 v115, v117
	global_store_dwordx4 v[136:137], v[114:117], off offset:64
	v_mul_f32_e32 v118, 0x45800000, v1
	ds_read_b128 v[114:117], v174
	v_cndmask_b32_e32 v122, v1, v118, vcc
	ds_read_b128 v[118:121], v174 offset:64
	v_pk_mul_f32 v[110:111], v[110:111], v[122:123] op_sel_hi:[1,0]
	v_pk_mul_f32 v[112:113], v[112:113], v[122:123] op_sel_hi:[1,0]
	v_pk_mul_f32 v[106:107], v[106:107], v[122:123] op_sel_hi:[1,0]
	v_pk_mul_f32 v[108:109], v[108:109], v[122:123] op_sel_hi:[1,0]
	s_waitcnt lgkmcnt(0)
	v_pk_mul_f32 v[112:113], v[116:117], v[112:113]
	v_pk_mul_f32 v[110:111], v[114:115], v[110:111]
	v_pk_mul_f32 v[108:109], v[120:121], v[108:109]
	ds_read_b128 v[114:117], v174 offset:128
	v_pk_mul_f32 v[106:107], v[118:119], v[106:107]
	ds_read_b128 v[118:121], v174 offset:192
	v_pk_mul_f32 v[102:103], v[102:103], v[122:123] op_sel_hi:[1,0]
	v_pk_mul_f32 v[104:105], v[104:105], v[122:123] op_sel_hi:[1,0]
	v_pk_mul_f32 v[98:99], v[98:99], v[122:123] op_sel_hi:[1,0]
	v_pk_mul_f32 v[100:101], v[100:101], v[122:123] op_sel_hi:[1,0]
	s_waitcnt lgkmcnt(0)
	v_pk_mul_f32 v[104:105], v[116:117], v[104:105]
	v_pk_mul_f32 v[102:103], v[114:115], v[102:103]
	v_pk_mul_f32 v[100:101], v[120:121], v[100:101]
	v_pk_mul_f32 v[98:99], v[118:119], v[98:99]
	s_and_b64 vcc, exec, s[6:7]
	v_add_u32_e32 v114, 16, v168
	s_cbranch_vccnz .LBB0_827
	v_ashrrev_i32_e32 v115, 31, v114
	v_lshlrev_b64 v[116:117], 12, v[114:115]
	v_lshl_add_u64 v[116:117], s[20:21], 0, v[116:117]
	v_lshl_add_u64 v[116:117], v[130:131], 2, v[116:117]
	v_lshl_add_u64 v[116:117], v[132:133], 2, v[116:117]
	global_store_dwordx4 v[116:117], v[110:113], off
	global_store_dwordx4 v[116:117], v[106:109], off offset:64
	global_store_dwordx4 v[116:117], v[102:105], off offset:128
	global_store_dwordx4 v[116:117], v[98:101], off offset:192
	s_and_b64 vcc, exec, s[8:9]
	s_cbranch_vccz .LBB0_828

.LBB0_835:
	v_pk_mul_f32 v[110:111], v[110:111], s[12:13] op_sel_hi:[1,0]
	v_lshlrev_b64 v[114:115], 11, v[114:115]
	v_lshl_add_u64 v[114:115], v[116:117], 0, v[114:115]
	v_pk_mul_f32 v[116:117], v[108:109], s[12:13] op_sel_hi:[1,0]
	v_pk_mul_f32 v[108:109], v[106:107], s[12:13] op_sel_hi:[1,0]
	v_cvt_pk_bf16_f32 v106, v110, v111
	v_pk_mul_f32 v[112:113], v[112:113], s[12:13] op_sel_hi:[1,0]
	v_cvt_pk_bf16_f32 v108, v108, v109
	v_cvt_pk_bf16_f32 v107, v112, v113
	v_cvt_pk_bf16_f32 v109, v116, v117
	v_lshl_add_u64 v[114:115], v[134:135], 1, v[114:115]
	v_permlane16_swap_b32_e32 v106, v108
	v_permlane16_swap_b32_e32 v107, v109
	v_pk_mul_f32 v[102:103], v[102:103], s[12:13] op_sel_hi:[1,0]
	global_store_dwordx4 v[114:115], v[106:109], off
	s_nop 1
	v_pk_mul_f32 v[106:107], v[100:101], s[12:13] op_sel_hi:[1,0]
	v_pk_mul_f32 v[100:101], v[98:99], s[12:13] op_sel_hi:[1,0]
	v_cvt_pk_bf16_f32 v98, v102, v103
	v_mov_b32_e32 v108, v91
	v_mov_b32_e32 v109, v95
	v_mov_b32_e32 v102, v90
	v_mov_b32_e32 v103, v94
	v_pk_mul_f32 v[108:109], v[108:109], v[108:109]
	v_mov_b32_e32 v110, v83
	v_pk_fma_f32 v[102:103], v[102:103], v[102:103], v[108:109]
	v_mov_b32_e32 v108, v92
	v_mov_b32_e32 v109, v96
	v_pk_fma_f32 v[102:103], v[108:109], v[108:109], v[102:103]
	v_mov_b32_e32 v108, v93
	v_mov_b32_e32 v109, v97
	v_mov_b32_e32 v111, v87
	v_pk_fma_f32 v[102:103], v[108:109], v[108:109], v[102:103]
	v_mov_b32_e32 v108, v82
	v_mov_b32_e32 v109, v86
	v_pk_mul_f32 v[110:111], v[110:111], v[110:111]
	v_bfe_u32 v99, v101, 16, 1
	v_pk_fma_f32 v[108:109], v[108:109], v[108:109], v[110:111]
	v_mov_b32_e32 v110, v84
	v_mov_b32_e32 v111, v88
	v_pk_fma_f32 v[108:109], v[110:111], v[110:111], v[108:109]
	v_mov_b32_e32 v110, v85
	v_mov_b32_e32 v111, v89
	v_add3_u32 v99, v101, v99, s61
	v_pk_fma_f32 v[108:109], v[110:111], v[110:111], v[108:109]
	v_add_f32_e32 v101, v102, v103
	v_add_f32_e32 v101, v109, v101
	v_add_f32_e32 v101, v108, v101
	ds_bpermute_b32 v102, v173, v101
	v_bfe_u32 v1, v100, 16, 1
	v_add3_u32 v1, v100, v1, s61
	v_pk_mul_f32 v[104:105], v[104:105], s[12:13] op_sel_hi:[1,0]
	v_lshrrev_b32_e32 v1, 16, v1
	v_and_or_b32 v100, v99, s62, v1
	s_waitcnt lgkmcnt(0)
	v_add_f32_e32 v102, v101, v102
	ds_bpermute_b32 v103, v175, v102
	v_cvt_pk_bf16_f32 v99, v104, v105
	v_cvt_pk_bf16_f32 v101, v106, v107
	s_waitcnt lgkmcnt(0)
	v_add_f32_e32 v1, v102, v103
	v_fmamk_f32 v1, v1, 0x3c800000, v179
	v_mul_f32_e32 v102, 0x4b800000, v1
	v_cmp_gt_f32_e32 vcc, s71, v1
	v_permlane16_swap_b32_e32 v98, v100
	s_nop 0
	v_cndmask_b32_e32 v1, v1, v102, vcc
	v_rsq_f32_e32 v1, v1
	v_permlane16_swap_b32_e32 v99, v101
	global_store_dwordx4 v[114:115], v[98:101], off offset:64
	v_mul_f32_e32 v102, 0x45800000, v1
	ds_read_b128 v[98:101], v174
	v_cndmask_b32_e32 v106, v1, v102, vcc
	ds_read_b128 v[102:105], v174 offset:64
	v_pk_mul_f32 v[94:95], v[94:95], v[106:107] op_sel_hi:[1,0]
	v_pk_mul_f32 v[96:97], v[96:97], v[106:107] op_sel_hi:[1,0]
	v_pk_mul_f32 v[90:91], v[90:91], v[106:107] op_sel_hi:[1,0]
	v_pk_mul_f32 v[92:93], v[92:93], v[106:107] op_sel_hi:[1,0]
	s_waitcnt lgkmcnt(0)
	v_pk_mul_f32 v[96:97], v[100:101], v[96:97]
	v_pk_mul_f32 v[94:95], v[98:99], v[94:95]
	v_pk_mul_f32 v[92:93], v[104:105], v[92:93]
	ds_read_b128 v[98:101], v174 offset:128
	v_pk_mul_f32 v[90:91], v[102:103], v[90:91]
	ds_read_b128 v[102:105], v174 offset:192
	v_pk_mul_f32 v[86:87], v[86:87], v[106:107] op_sel_hi:[1,0]
	v_pk_mul_f32 v[88:89], v[88:89], v[106:107] op_sel_hi:[1,0]
	v_pk_mul_f32 v[82:83], v[82:83], v[106:107] op_sel_hi:[1,0]
	v_pk_mul_f32 v[84:85], v[84:85], v[106:107] op_sel_hi:[1,0]
	s_waitcnt lgkmcnt(0)
	v_pk_mul_f32 v[88:89], v[100:101], v[88:89]
	v_pk_mul_f32 v[86:87], v[98:99], v[86:87]
	v_pk_mul_f32 v[84:85], v[104:105], v[84:85]
	v_pk_mul_f32 v[82:83], v[102:103], v[82:83]
	s_and_b64 vcc, exec, s[6:7]
	v_add_u32_e32 v98, 32, v168
	s_cbranch_vccnz .LBB0_839
	v_ashrrev_i32_e32 v99, 31, v98
	v_lshlrev_b64 v[100:101], 12, v[98:99]
	v_lshl_add_u64 v[100:101], s[20:21], 0, v[100:101]
	v_lshl_add_u64 v[100:101], v[130:131], 2, v[100:101]
	v_lshl_add_u64 v[100:101], v[132:133], 2, v[100:101]
	global_store_dwordx4 v[100:101], v[94:97], off
	global_store_dwordx4 v[100:101], v[90:93], off offset:64
	global_store_dwordx4 v[100:101], v[86:89], off offset:128
	global_store_dwordx4 v[100:101], v[82:85], off offset:192
	s_and_b64 vcc, exec, s[8:9]
	s_cbranch_vccz .LBB0_840

.LBB0_847:
	v_pk_mul_f32 v[94:95], v[94:95], s[12:13] op_sel_hi:[1,0]
	v_lshlrev_b64 v[98:99], 11, v[98:99]
	v_lshl_add_u64 v[98:99], v[100:101], 0, v[98:99]
	v_pk_mul_f32 v[100:101], v[92:93], s[12:13] op_sel_hi:[1,0]
	v_pk_mul_f32 v[92:93], v[90:91], s[12:13] op_sel_hi:[1,0]
	v_cvt_pk_bf16_f32 v90, v94, v95
	v_pk_mul_f32 v[96:97], v[96:97], s[12:13] op_sel_hi:[1,0]
	v_cvt_pk_bf16_f32 v92, v92, v93
	v_cvt_pk_bf16_f32 v91, v96, v97
	v_cvt_pk_bf16_f32 v93, v100, v101
	v_lshl_add_u64 v[98:99], v[134:135], 1, v[98:99]
	v_permlane16_swap_b32_e32 v90, v92
	v_permlane16_swap_b32_e32 v91, v93
	v_pk_mul_f32 v[86:87], v[86:87], s[12:13] op_sel_hi:[1,0]
	global_store_dwordx4 v[98:99], v[90:93], off
	s_nop 1
	v_pk_mul_f32 v[90:91], v[84:85], s[12:13] op_sel_hi:[1,0]
	v_pk_mul_f32 v[84:85], v[82:83], s[12:13] op_sel_hi:[1,0]
	v_cvt_pk_bf16_f32 v82, v86, v87
	v_mov_b32_e32 v92, v75
	v_mov_b32_e32 v93, v79
	v_mov_b32_e32 v86, v74
	v_mov_b32_e32 v87, v78
	v_pk_mul_f32 v[92:93], v[92:93], v[92:93]
	v_mov_b32_e32 v94, v67
	v_pk_fma_f32 v[86:87], v[86:87], v[86:87], v[92:93]
	v_mov_b32_e32 v92, v76
	v_mov_b32_e32 v93, v80
	v_pk_fma_f32 v[86:87], v[92:93], v[92:93], v[86:87]
	v_mov_b32_e32 v92, v77
	v_mov_b32_e32 v93, v81
	v_mov_b32_e32 v95, v71
	v_pk_fma_f32 v[86:87], v[92:93], v[92:93], v[86:87]
	v_mov_b32_e32 v92, v66
	v_mov_b32_e32 v93, v70
	v_pk_mul_f32 v[94:95], v[94:95], v[94:95]
	v_bfe_u32 v83, v85, 16, 1
	v_pk_fma_f32 v[92:93], v[92:93], v[92:93], v[94:95]
	v_mov_b32_e32 v94, v68
	v_mov_b32_e32 v95, v72
	v_pk_fma_f32 v[92:93], v[94:95], v[94:95], v[92:93]
	v_mov_b32_e32 v94, v69
	v_mov_b32_e32 v95, v73
	v_add3_u32 v83, v85, v83, s61
	v_pk_fma_f32 v[92:93], v[94:95], v[94:95], v[92:93]
	v_add_f32_e32 v85, v86, v87
	v_add_f32_e32 v85, v93, v85
	v_add_f32_e32 v85, v92, v85
	ds_bpermute_b32 v86, v173, v85
	v_bfe_u32 v1, v84, 16, 1
	v_add3_u32 v1, v84, v1, s61
	v_pk_mul_f32 v[88:89], v[88:89], s[12:13] op_sel_hi:[1,0]
	v_lshrrev_b32_e32 v1, 16, v1
	v_and_or_b32 v84, v83, s62, v1
	s_waitcnt lgkmcnt(0)
	v_add_f32_e32 v86, v85, v86
	ds_bpermute_b32 v87, v175, v86
	v_cvt_pk_bf16_f32 v83, v88, v89
	v_cvt_pk_bf16_f32 v85, v90, v91
	s_waitcnt lgkmcnt(0)
	v_add_f32_e32 v1, v86, v87
	v_fmamk_f32 v1, v1, 0x3c800000, v179
	v_mul_f32_e32 v86, 0x4b800000, v1
	v_cmp_gt_f32_e32 vcc, s71, v1
	v_permlane16_swap_b32_e32 v82, v84
	s_nop 0
	v_cndmask_b32_e32 v1, v1, v86, vcc
	v_rsq_f32_e32 v1, v1
	v_permlane16_swap_b32_e32 v83, v85
	global_store_dwordx4 v[98:99], v[82:85], off offset:64
	v_mul_f32_e32 v86, 0x45800000, v1
	ds_read_b128 v[82:85], v174
	v_cndmask_b32_e32 v90, v1, v86, vcc
	ds_read_b128 v[86:89], v174 offset:64
	v_pk_mul_f32 v[78:79], v[78:79], v[90:91] op_sel_hi:[1,0]
	v_pk_mul_f32 v[80:81], v[80:81], v[90:91] op_sel_hi:[1,0]
	v_pk_mul_f32 v[74:75], v[74:75], v[90:91] op_sel_hi:[1,0]
	v_pk_mul_f32 v[76:77], v[76:77], v[90:91] op_sel_hi:[1,0]
	s_waitcnt lgkmcnt(0)
	v_pk_mul_f32 v[80:81], v[84:85], v[80:81]
	v_pk_mul_f32 v[78:79], v[82:83], v[78:79]
	v_pk_mul_f32 v[76:77], v[88:89], v[76:77]
	ds_read_b128 v[82:85], v174 offset:128
	v_pk_mul_f32 v[74:75], v[86:87], v[74:75]
	ds_read_b128 v[86:89], v174 offset:192
	v_pk_mul_f32 v[70:71], v[70:71], v[90:91] op_sel_hi:[1,0]
	v_pk_mul_f32 v[72:73], v[72:73], v[90:91] op_sel_hi:[1,0]
	v_pk_mul_f32 v[66:67], v[66:67], v[90:91] op_sel_hi:[1,0]
	v_pk_mul_f32 v[68:69], v[68:69], v[90:91] op_sel_hi:[1,0]
	s_waitcnt lgkmcnt(0)
	v_pk_mul_f32 v[72:73], v[84:85], v[72:73]
	v_pk_mul_f32 v[70:71], v[82:83], v[70:71]
	v_pk_mul_f32 v[68:69], v[88:89], v[68:69]
	v_pk_mul_f32 v[66:67], v[86:87], v[66:67]
	s_and_b64 vcc, exec, s[6:7]
	v_add_u32_e32 v82, 48, v168
	s_cbranch_vccnz .LBB0_851
	v_ashrrev_i32_e32 v83, 31, v82
	v_lshlrev_b64 v[84:85], 12, v[82:83]
	v_lshl_add_u64 v[84:85], s[20:21], 0, v[84:85]
	v_lshl_add_u64 v[84:85], v[130:131], 2, v[84:85]
	v_lshl_add_u64 v[84:85], v[132:133], 2, v[84:85]
	global_store_dwordx4 v[84:85], v[78:81], off
	global_store_dwordx4 v[84:85], v[74:77], off offset:64
	global_store_dwordx4 v[84:85], v[70:73], off offset:128
	global_store_dwordx4 v[84:85], v[66:69], off offset:192
	s_and_b64 vcc, exec, s[8:9]
	s_cbranch_vccz .LBB0_852

.LBB0_859:
	v_pk_mul_f32 v[78:79], v[78:79], s[12:13] op_sel_hi:[1,0]
	v_lshlrev_b64 v[82:83], 11, v[82:83]
	v_lshl_add_u64 v[82:83], v[84:85], 0, v[82:83]
	v_pk_mul_f32 v[84:85], v[76:77], s[12:13] op_sel_hi:[1,0]
	v_pk_mul_f32 v[76:77], v[74:75], s[12:13] op_sel_hi:[1,0]
	v_cvt_pk_bf16_f32 v74, v78, v79
	v_pk_mul_f32 v[80:81], v[80:81], s[12:13] op_sel_hi:[1,0]
	v_cvt_pk_bf16_f32 v76, v76, v77
	v_cvt_pk_bf16_f32 v75, v80, v81
	v_cvt_pk_bf16_f32 v77, v84, v85
	v_lshl_add_u64 v[82:83], v[134:135], 1, v[82:83]
	v_permlane16_swap_b32_e32 v74, v76
	v_permlane16_swap_b32_e32 v75, v77
	v_pk_mul_f32 v[70:71], v[70:71], s[12:13] op_sel_hi:[1,0]
	global_store_dwordx4 v[82:83], v[74:77], off
	s_nop 1
	v_pk_mul_f32 v[74:75], v[68:69], s[12:13] op_sel_hi:[1,0]
	v_pk_mul_f32 v[68:69], v[66:67], s[12:13] op_sel_hi:[1,0]
	v_cvt_pk_bf16_f32 v66, v70, v71
	v_mov_b32_e32 v76, v59
	v_mov_b32_e32 v77, v63
	v_mov_b32_e32 v70, v58
	v_mov_b32_e32 v71, v62
	v_pk_mul_f32 v[76:77], v[76:77], v[76:77]
	v_mov_b32_e32 v78, v51
	v_pk_fma_f32 v[70:71], v[70:71], v[70:71], v[76:77]
	v_mov_b32_e32 v76, v60
	v_mov_b32_e32 v77, v64
	v_pk_fma_f32 v[70:71], v[76:77], v[76:77], v[70:71]
	v_mov_b32_e32 v76, v61
	v_mov_b32_e32 v77, v65
	v_mov_b32_e32 v79, v55
	v_pk_fma_f32 v[70:71], v[76:77], v[76:77], v[70:71]
	v_mov_b32_e32 v76, v50
	v_mov_b32_e32 v77, v54
	v_pk_mul_f32 v[78:79], v[78:79], v[78:79]
	v_bfe_u32 v67, v69, 16, 1
	v_pk_fma_f32 v[76:77], v[76:77], v[76:77], v[78:79]
	v_mov_b32_e32 v78, v52
	v_mov_b32_e32 v79, v56
	v_pk_fma_f32 v[76:77], v[78:79], v[78:79], v[76:77]
	v_mov_b32_e32 v78, v53
	v_mov_b32_e32 v79, v57
	v_add3_u32 v67, v69, v67, s61
	v_pk_fma_f32 v[76:77], v[78:79], v[78:79], v[76:77]
	v_add_f32_e32 v69, v70, v71
	v_add_f32_e32 v69, v77, v69
	v_add_f32_e32 v69, v76, v69
	ds_bpermute_b32 v70, v173, v69
	v_bfe_u32 v1, v68, 16, 1
	v_add3_u32 v1, v68, v1, s61
	v_pk_mul_f32 v[72:73], v[72:73], s[12:13] op_sel_hi:[1,0]
	v_lshrrev_b32_e32 v1, 16, v1
	v_and_or_b32 v68, v67, s62, v1
	s_waitcnt lgkmcnt(0)
	v_add_f32_e32 v70, v69, v70
	ds_bpermute_b32 v71, v175, v70
	v_cvt_pk_bf16_f32 v67, v72, v73
	v_cvt_pk_bf16_f32 v69, v74, v75
	s_waitcnt lgkmcnt(0)
	v_add_f32_e32 v1, v70, v71
	v_fmamk_f32 v1, v1, 0x3c800000, v179
	v_mul_f32_e32 v70, 0x4b800000, v1
	v_cmp_gt_f32_e32 vcc, s71, v1
	v_permlane16_swap_b32_e32 v66, v68
	s_nop 0
	v_cndmask_b32_e32 v1, v1, v70, vcc
	v_rsq_f32_e32 v1, v1
	v_permlane16_swap_b32_e32 v67, v69
	global_store_dwordx4 v[82:83], v[66:69], off offset:64
	ds_read_b128 v[68:71], v174
	ds_read_b128 v[72:75], v174 offset:64
	v_mul_f32_e32 v67, 0x45800000, v1
	v_cndmask_b32_e32 v76, v1, v67, vcc
	v_pk_mul_f32 v[62:63], v[62:63], v[76:77] op_sel_hi:[1,0]
	v_pk_mul_f32 v[64:65], v[64:65], v[76:77] op_sel_hi:[1,0]
	v_pk_mul_f32 v[58:59], v[58:59], v[76:77] op_sel_hi:[1,0]
	v_pk_mul_f32 v[60:61], v[60:61], v[76:77] op_sel_hi:[1,0]
	s_waitcnt lgkmcnt(0)
	v_pk_mul_f32 v[64:65], v[70:71], v[64:65]
	v_pk_mul_f32 v[62:63], v[68:69], v[62:63]
	v_pk_mul_f32 v[60:61], v[74:75], v[60:61]
	ds_read_b128 v[68:71], v174 offset:128
	v_pk_mul_f32 v[58:59], v[72:73], v[58:59]
	ds_read_b128 v[72:75], v174 offset:192
	v_pk_mul_f32 v[54:55], v[54:55], v[76:77] op_sel_hi:[1,0]
	v_pk_mul_f32 v[56:57], v[56:57], v[76:77] op_sel_hi:[1,0]
	v_pk_mul_f32 v[50:51], v[50:51], v[76:77] op_sel_hi:[1,0]
	v_pk_mul_f32 v[52:53], v[52:53], v[76:77] op_sel_hi:[1,0]
	v_add_u32_e32 v66, 0x80, v168
	s_waitcnt lgkmcnt(0)
	v_pk_mul_f32 v[56:57], v[70:71], v[56:57]
	v_pk_mul_f32 v[54:55], v[68:69], v[54:55]
	v_pk_mul_f32 v[52:53], v[74:75], v[52:53]
	s_and_b64 vcc, exec, s[6:7]
	v_pk_mul_f32 v[50:51], v[72:73], v[50:51]
	s_cbranch_vccnz .LBB0_863
	v_ashrrev_i32_e32 v67, 31, v66
	v_lshlrev_b64 v[68:69], 12, v[66:67]
	v_lshl_add_u64 v[68:69], s[20:21], 0, v[68:69]
	v_lshl_add_u64 v[68:69], v[130:131], 2, v[68:69]
	v_lshl_add_u64 v[68:69], v[132:133], 2, v[68:69]
	global_store_dwordx4 v[68:69], v[62:65], off
	global_store_dwordx4 v[68:69], v[58:61], off offset:64
	global_store_dwordx4 v[68:69], v[54:57], off offset:128
	global_store_dwordx4 v[68:69], v[50:53], off offset:192
	s_and_b64 vcc, exec, s[8:9]
	s_cbranch_vccz .LBB0_864

.LBB0_871:
	v_pk_mul_f32 v[62:63], v[62:63], s[12:13] op_sel_hi:[1,0]
	v_lshlrev_b64 v[66:67], 11, v[66:67]
	v_lshl_add_u64 v[66:67], v[68:69], 0, v[66:67]
	v_pk_mul_f32 v[68:69], v[60:61], s[12:13] op_sel_hi:[1,0]
	v_pk_mul_f32 v[60:61], v[58:59], s[12:13] op_sel_hi:[1,0]
	v_cvt_pk_bf16_f32 v58, v62, v63
	v_pk_mul_f32 v[64:65], v[64:65], s[12:13] op_sel_hi:[1,0]
	v_cvt_pk_bf16_f32 v60, v60, v61
	v_cvt_pk_bf16_f32 v59, v64, v65
	v_cvt_pk_bf16_f32 v61, v68, v69
	v_lshl_add_u64 v[66:67], v[134:135], 1, v[66:67]
	v_permlane16_swap_b32_e32 v58, v60
	v_permlane16_swap_b32_e32 v59, v61
	v_pk_mul_f32 v[54:55], v[54:55], s[12:13] op_sel_hi:[1,0]
	global_store_dwordx4 v[66:67], v[58:61], off
	s_nop 1
	v_pk_mul_f32 v[58:59], v[52:53], s[12:13] op_sel_hi:[1,0]
	v_pk_mul_f32 v[52:53], v[50:51], s[12:13] op_sel_hi:[1,0]
	v_cvt_pk_bf16_f32 v50, v54, v55
	v_mov_b32_e32 v60, v43
	v_mov_b32_e32 v61, v47
	v_mov_b32_e32 v54, v42
	v_mov_b32_e32 v55, v46
	v_pk_mul_f32 v[60:61], v[60:61], v[60:61]
	v_mov_b32_e32 v62, v35
	v_pk_fma_f32 v[54:55], v[54:55], v[54:55], v[60:61]
	v_mov_b32_e32 v60, v44
	v_mov_b32_e32 v61, v48
	v_pk_fma_f32 v[54:55], v[60:61], v[60:61], v[54:55]
	v_mov_b32_e32 v60, v45
	v_mov_b32_e32 v61, v49
	v_mov_b32_e32 v63, v39
	v_pk_fma_f32 v[54:55], v[60:61], v[60:61], v[54:55]
	v_mov_b32_e32 v60, v34
	v_mov_b32_e32 v61, v38
	v_pk_mul_f32 v[62:63], v[62:63], v[62:63]
	v_bfe_u32 v51, v53, 16, 1
	v_pk_fma_f32 v[60:61], v[60:61], v[60:61], v[62:63]
	v_mov_b32_e32 v62, v36
	v_mov_b32_e32 v63, v40
	v_pk_fma_f32 v[60:61], v[62:63], v[62:63], v[60:61]
	v_mov_b32_e32 v62, v37
	v_mov_b32_e32 v63, v41
	v_add3_u32 v51, v53, v51, s61
	v_pk_fma_f32 v[60:61], v[62:63], v[62:63], v[60:61]
	v_add_f32_e32 v53, v54, v55
	v_add_f32_e32 v53, v61, v53
	v_add_f32_e32 v53, v60, v53
	ds_bpermute_b32 v54, v173, v53
	v_bfe_u32 v1, v52, 16, 1
	v_add3_u32 v1, v52, v1, s61
	v_pk_mul_f32 v[56:57], v[56:57], s[12:13] op_sel_hi:[1,0]
	v_lshrrev_b32_e32 v1, 16, v1
	v_and_or_b32 v52, v51, s62, v1
	s_waitcnt lgkmcnt(0)
	v_add_f32_e32 v54, v53, v54
	ds_bpermute_b32 v55, v175, v54
	v_cvt_pk_bf16_f32 v51, v56, v57
	v_cvt_pk_bf16_f32 v53, v58, v59
	s_waitcnt lgkmcnt(0)
	v_add_f32_e32 v1, v54, v55
	v_fmamk_f32 v1, v1, 0x3c800000, v179
	v_mul_f32_e32 v54, 0x4b800000, v1
	v_cmp_gt_f32_e32 vcc, s71, v1
	v_permlane16_swap_b32_e32 v50, v52
	s_nop 0
	v_cndmask_b32_e32 v1, v1, v54, vcc
	v_rsq_f32_e32 v1, v1
	v_permlane16_swap_b32_e32 v51, v53
	global_store_dwordx4 v[66:67], v[50:53], off offset:64
	v_mul_f32_e32 v54, 0x45800000, v1
	ds_read_b128 v[50:53], v174
	v_cndmask_b32_e32 v58, v1, v54, vcc
	ds_read_b128 v[54:57], v174 offset:64
	v_pk_mul_f32 v[46:47], v[46:47], v[58:59] op_sel_hi:[1,0]
	v_pk_mul_f32 v[48:49], v[48:49], v[58:59] op_sel_hi:[1,0]
	v_pk_mul_f32 v[42:43], v[42:43], v[58:59] op_sel_hi:[1,0]
	v_pk_mul_f32 v[44:45], v[44:45], v[58:59] op_sel_hi:[1,0]
	s_waitcnt lgkmcnt(0)
	v_pk_mul_f32 v[48:49], v[52:53], v[48:49]
	v_pk_mul_f32 v[46:47], v[50:51], v[46:47]
	v_pk_mul_f32 v[44:45], v[56:57], v[44:45]
	ds_read_b128 v[50:53], v174 offset:128
	v_pk_mul_f32 v[42:43], v[54:55], v[42:43]
	ds_read_b128 v[54:57], v174 offset:192
	v_pk_mul_f32 v[38:39], v[38:39], v[58:59] op_sel_hi:[1,0]
	v_pk_mul_f32 v[40:41], v[40:41], v[58:59] op_sel_hi:[1,0]
	v_pk_mul_f32 v[34:35], v[34:35], v[58:59] op_sel_hi:[1,0]
	v_pk_mul_f32 v[36:37], v[36:37], v[58:59] op_sel_hi:[1,0]
	s_waitcnt lgkmcnt(0)
	v_pk_mul_f32 v[40:41], v[52:53], v[40:41]
	v_pk_mul_f32 v[38:39], v[50:51], v[38:39]
	v_pk_mul_f32 v[36:37], v[56:57], v[36:37]
	v_pk_mul_f32 v[34:35], v[54:55], v[34:35]
	s_and_b64 vcc, exec, s[6:7]
	v_add_u32_e32 v50, 0x90, v168
	s_cbranch_vccnz .LBB0_875
	v_ashrrev_i32_e32 v51, 31, v50
	v_lshlrev_b64 v[52:53], 12, v[50:51]
	v_lshl_add_u64 v[52:53], s[20:21], 0, v[52:53]
	v_lshl_add_u64 v[52:53], v[130:131], 2, v[52:53]
	v_lshl_add_u64 v[52:53], v[132:133], 2, v[52:53]
	global_store_dwordx4 v[52:53], v[46:49], off
	global_store_dwordx4 v[52:53], v[42:45], off offset:64
	global_store_dwordx4 v[52:53], v[38:41], off offset:128
	global_store_dwordx4 v[52:53], v[34:37], off offset:192
	s_and_b64 vcc, exec, s[8:9]
	s_cbranch_vccz .LBB0_876

.LBB0_883:
	v_pk_mul_f32 v[46:47], v[46:47], s[12:13] op_sel_hi:[1,0]
	v_lshlrev_b64 v[50:51], 11, v[50:51]
	v_lshl_add_u64 v[50:51], v[52:53], 0, v[50:51]
	v_pk_mul_f32 v[52:53], v[44:45], s[12:13] op_sel_hi:[1,0]
	v_pk_mul_f32 v[44:45], v[42:43], s[12:13] op_sel_hi:[1,0]
	v_cvt_pk_bf16_f32 v42, v46, v47
	v_pk_mul_f32 v[48:49], v[48:49], s[12:13] op_sel_hi:[1,0]
	v_cvt_pk_bf16_f32 v44, v44, v45
	v_cvt_pk_bf16_f32 v43, v48, v49
	v_cvt_pk_bf16_f32 v45, v52, v53
	v_lshl_add_u64 v[50:51], v[134:135], 1, v[50:51]
	v_permlane16_swap_b32_e32 v42, v44
	v_permlane16_swap_b32_e32 v43, v45
	v_pk_mul_f32 v[38:39], v[38:39], s[12:13] op_sel_hi:[1,0]
	global_store_dwordx4 v[50:51], v[42:45], off
	s_nop 1
	v_pk_mul_f32 v[42:43], v[36:37], s[12:13] op_sel_hi:[1,0]
	v_pk_mul_f32 v[36:37], v[34:35], s[12:13] op_sel_hi:[1,0]
	v_cvt_pk_bf16_f32 v34, v38, v39
	v_mov_b32_e32 v44, v27
	v_mov_b32_e32 v45, v31
	v_mov_b32_e32 v38, v26
	v_mov_b32_e32 v39, v30
	v_pk_mul_f32 v[44:45], v[44:45], v[44:45]
	v_mov_b32_e32 v46, v19
	v_pk_fma_f32 v[38:39], v[38:39], v[38:39], v[44:45]
	v_mov_b32_e32 v44, v28
	v_mov_b32_e32 v45, v32
	v_pk_fma_f32 v[38:39], v[44:45], v[44:45], v[38:39]
	v_mov_b32_e32 v44, v29
	v_mov_b32_e32 v45, v33
	v_mov_b32_e32 v47, v23
	v_pk_fma_f32 v[38:39], v[44:45], v[44:45], v[38:39]
	v_mov_b32_e32 v44, v18
	v_mov_b32_e32 v45, v22
	v_pk_mul_f32 v[46:47], v[46:47], v[46:47]
	v_bfe_u32 v35, v37, 16, 1
	v_pk_fma_f32 v[44:45], v[44:45], v[44:45], v[46:47]
	v_mov_b32_e32 v46, v20
	v_mov_b32_e32 v47, v24
	v_pk_fma_f32 v[44:45], v[46:47], v[46:47], v[44:45]
	v_mov_b32_e32 v46, v21
	v_mov_b32_e32 v47, v25
	v_add3_u32 v35, v37, v35, s61
	v_pk_fma_f32 v[44:45], v[46:47], v[46:47], v[44:45]
	v_add_f32_e32 v37, v38, v39
	v_add_f32_e32 v37, v45, v37
	v_add_f32_e32 v37, v44, v37
	ds_bpermute_b32 v38, v173, v37
	v_bfe_u32 v1, v36, 16, 1
	v_add3_u32 v1, v36, v1, s61
	v_pk_mul_f32 v[40:41], v[40:41], s[12:13] op_sel_hi:[1,0]
	v_lshrrev_b32_e32 v1, 16, v1
	v_and_or_b32 v36, v35, s62, v1
	s_waitcnt lgkmcnt(0)
	v_add_f32_e32 v38, v37, v38
	ds_bpermute_b32 v39, v175, v38
	v_cvt_pk_bf16_f32 v35, v40, v41
	v_cvt_pk_bf16_f32 v37, v42, v43
	s_waitcnt lgkmcnt(0)
	v_add_f32_e32 v1, v38, v39
	v_fmamk_f32 v1, v1, 0x3c800000, v179
	v_mul_f32_e32 v38, 0x4b800000, v1
	v_cmp_gt_f32_e32 vcc, s71, v1
	v_permlane16_swap_b32_e32 v34, v36
	s_nop 0
	v_cndmask_b32_e32 v1, v1, v38, vcc
	v_rsq_f32_e32 v1, v1
	v_permlane16_swap_b32_e32 v35, v37
	global_store_dwordx4 v[50:51], v[34:37], off offset:64
	v_mul_f32_e32 v38, 0x45800000, v1
	ds_read_b128 v[34:37], v174
	v_cndmask_b32_e32 v42, v1, v38, vcc
	ds_read_b128 v[38:41], v174 offset:64
	v_pk_mul_f32 v[30:31], v[30:31], v[42:43] op_sel_hi:[1,0]
	v_pk_mul_f32 v[32:33], v[32:33], v[42:43] op_sel_hi:[1,0]
	v_pk_mul_f32 v[26:27], v[26:27], v[42:43] op_sel_hi:[1,0]
	v_pk_mul_f32 v[28:29], v[28:29], v[42:43] op_sel_hi:[1,0]
	s_waitcnt lgkmcnt(0)
	v_pk_mul_f32 v[32:33], v[36:37], v[32:33]
	v_pk_mul_f32 v[30:31], v[34:35], v[30:31]
	v_pk_mul_f32 v[28:29], v[40:41], v[28:29]
	ds_read_b128 v[34:37], v174 offset:128
	v_pk_mul_f32 v[26:27], v[38:39], v[26:27]
	ds_read_b128 v[38:41], v174 offset:192
	v_pk_mul_f32 v[22:23], v[22:23], v[42:43] op_sel_hi:[1,0]
	v_pk_mul_f32 v[24:25], v[24:25], v[42:43] op_sel_hi:[1,0]
	v_pk_mul_f32 v[18:19], v[18:19], v[42:43] op_sel_hi:[1,0]
	v_pk_mul_f32 v[20:21], v[20:21], v[42:43] op_sel_hi:[1,0]
	s_waitcnt lgkmcnt(0)
	v_pk_mul_f32 v[24:25], v[36:37], v[24:25]
	v_pk_mul_f32 v[22:23], v[34:35], v[22:23]
	v_pk_mul_f32 v[20:21], v[40:41], v[20:21]
	v_pk_mul_f32 v[18:19], v[38:39], v[18:19]
	s_and_b64 vcc, exec, s[6:7]
	v_add_u32_e32 v34, 0xa0, v168
	s_cbranch_vccnz .LBB0_887
	v_ashrrev_i32_e32 v35, 31, v34
	v_lshlrev_b64 v[36:37], 12, v[34:35]
	v_lshl_add_u64 v[36:37], s[20:21], 0, v[36:37]
	v_lshl_add_u64 v[36:37], v[130:131], 2, v[36:37]
	v_lshl_add_u64 v[36:37], v[132:133], 2, v[36:37]
	global_store_dwordx4 v[36:37], v[30:33], off
	global_store_dwordx4 v[36:37], v[26:29], off offset:64
	global_store_dwordx4 v[36:37], v[22:25], off offset:128
	global_store_dwordx4 v[36:37], v[18:21], off offset:192
	s_and_b64 vcc, exec, s[8:9]
	s_cbranch_vccz .LBB0_888

.LBB0_895:
	v_pk_mul_f32 v[30:31], v[30:31], s[12:13] op_sel_hi:[1,0]
	v_lshlrev_b64 v[34:35], 11, v[34:35]
	v_lshl_add_u64 v[34:35], v[36:37], 0, v[34:35]
	v_pk_mul_f32 v[36:37], v[28:29], s[12:13] op_sel_hi:[1,0]
	v_pk_mul_f32 v[28:29], v[26:27], s[12:13] op_sel_hi:[1,0]
	v_cvt_pk_bf16_f32 v26, v30, v31
	v_pk_mul_f32 v[32:33], v[32:33], s[12:13] op_sel_hi:[1,0]
	v_cvt_pk_bf16_f32 v28, v28, v29
	v_cvt_pk_bf16_f32 v27, v32, v33
	v_cvt_pk_bf16_f32 v29, v36, v37
	v_lshl_add_u64 v[34:35], v[134:135], 1, v[34:35]
	v_permlane16_swap_b32_e32 v26, v28
	v_permlane16_swap_b32_e32 v27, v29
	v_pk_mul_f32 v[22:23], v[22:23], s[12:13] op_sel_hi:[1,0]
	global_store_dwordx4 v[34:35], v[26:29], off
	s_nop 1
	v_pk_mul_f32 v[26:27], v[20:21], s[12:13] op_sel_hi:[1,0]
	v_pk_mul_f32 v[20:21], v[18:19], s[12:13] op_sel_hi:[1,0]
	v_cvt_pk_bf16_f32 v18, v22, v23
	v_mov_b32_e32 v28, v11
	v_mov_b32_e32 v29, v15
	v_mov_b32_e32 v22, v10
	v_mov_b32_e32 v23, v14
	v_pk_mul_f32 v[28:29], v[28:29], v[28:29]
	v_mov_b32_e32 v30, v3
	v_pk_fma_f32 v[22:23], v[22:23], v[22:23], v[28:29]
	v_mov_b32_e32 v28, v12
	v_mov_b32_e32 v29, v16
	v_pk_fma_f32 v[22:23], v[28:29], v[28:29], v[22:23]
	v_mov_b32_e32 v28, v13
	v_mov_b32_e32 v29, v17
	v_mov_b32_e32 v31, v7
	v_pk_fma_f32 v[22:23], v[28:29], v[28:29], v[22:23]
	v_mov_b32_e32 v28, v2
	v_mov_b32_e32 v29, v6
	v_pk_mul_f32 v[30:31], v[30:31], v[30:31]
	v_bfe_u32 v19, v21, 16, 1
	v_pk_fma_f32 v[28:29], v[28:29], v[28:29], v[30:31]
	v_mov_b32_e32 v30, v4
	v_mov_b32_e32 v31, v8
	v_pk_fma_f32 v[28:29], v[30:31], v[30:31], v[28:29]
	v_mov_b32_e32 v30, v5
	v_mov_b32_e32 v31, v9
	v_add3_u32 v19, v21, v19, s61
	v_pk_fma_f32 v[28:29], v[30:31], v[30:31], v[28:29]
	v_add_f32_e32 v21, v22, v23
	v_add_f32_e32 v21, v29, v21
	v_add_f32_e32 v21, v28, v21
	ds_bpermute_b32 v22, v173, v21
	v_bfe_u32 v1, v20, 16, 1
	v_add3_u32 v1, v20, v1, s61
	v_pk_mul_f32 v[24:25], v[24:25], s[12:13] op_sel_hi:[1,0]
	v_lshrrev_b32_e32 v1, 16, v1
	v_and_or_b32 v20, v19, s62, v1
	s_waitcnt lgkmcnt(0)
	v_add_f32_e32 v22, v21, v22
	ds_bpermute_b32 v23, v175, v22
	v_cvt_pk_bf16_f32 v19, v24, v25
	v_cvt_pk_bf16_f32 v21, v26, v27
	s_waitcnt lgkmcnt(0)
	v_add_f32_e32 v1, v22, v23
	v_fmamk_f32 v1, v1, 0x3c800000, v179
	v_mul_f32_e32 v22, 0x4b800000, v1
	v_cmp_gt_f32_e32 vcc, s71, v1
	v_permlane16_swap_b32_e32 v18, v20
	s_nop 0
	v_cndmask_b32_e32 v1, v1, v22, vcc
	v_rsq_f32_e32 v1, v1
	v_permlane16_swap_b32_e32 v19, v21
	global_store_dwordx4 v[34:35], v[18:21], off offset:64
	v_mul_f32_e32 v22, 0x45800000, v1
	ds_read_b128 v[18:21], v174
	v_cndmask_b32_e32 v26, v1, v22, vcc
	ds_read_b128 v[22:25], v174 offset:64
	v_pk_mul_f32 v[14:15], v[14:15], v[26:27] op_sel_hi:[1,0]
	v_pk_mul_f32 v[16:17], v[16:17], v[26:27] op_sel_hi:[1,0]
	v_pk_mul_f32 v[10:11], v[10:11], v[26:27] op_sel_hi:[1,0]
	v_pk_mul_f32 v[12:13], v[12:13], v[26:27] op_sel_hi:[1,0]
	s_waitcnt lgkmcnt(0)
	v_pk_mul_f32 v[16:17], v[20:21], v[16:17]
	v_pk_mul_f32 v[14:15], v[18:19], v[14:15]
	v_pk_mul_f32 v[12:13], v[24:25], v[12:13]
	ds_read_b128 v[18:21], v174 offset:128
	v_pk_mul_f32 v[10:11], v[22:23], v[10:11]
	ds_read_b128 v[22:25], v174 offset:192
	v_pk_mul_f32 v[6:7], v[6:7], v[26:27] op_sel_hi:[1,0]
	v_pk_mul_f32 v[8:9], v[8:9], v[26:27] op_sel_hi:[1,0]
	v_pk_mul_f32 v[2:3], v[2:3], v[26:27] op_sel_hi:[1,0]
	v_pk_mul_f32 v[4:5], v[4:5], v[26:27] op_sel_hi:[1,0]
	s_waitcnt lgkmcnt(0)
	v_pk_mul_f32 v[8:9], v[20:21], v[8:9]
	v_pk_mul_f32 v[6:7], v[18:19], v[6:7]
	v_pk_mul_f32 v[4:5], v[24:25], v[4:5]
	v_pk_mul_f32 v[2:3], v[22:23], v[2:3]
	s_and_b64 vcc, exec, s[6:7]
	v_add_u32_e32 v18, 0xb0, v168
	s_cbranch_vccnz .LBB0_899
	v_ashrrev_i32_e32 v19, 31, v18
	v_lshlrev_b64 v[20:21], 12, v[18:19]
	v_lshl_add_u64 v[20:21], s[20:21], 0, v[20:21]
	v_lshl_add_u64 v[20:21], v[130:131], 2, v[20:21]
	v_lshl_add_u64 v[20:21], v[132:133], 2, v[20:21]
	global_store_dwordx4 v[20:21], v[14:17], off
	global_store_dwordx4 v[20:21], v[10:13], off offset:64
	global_store_dwordx4 v[20:21], v[6:9], off offset:128
	global_store_dwordx4 v[20:21], v[2:5], off offset:192
	s_and_b64 vcc, exec, s[8:9]
	s_cbranch_vccz .LBB0_900

.LBB0_1070:
	s_lshl_b32 s8, s8, 8
	v_lshl_add_u32 v208, v153, 5, s8
	v_lshlrev_b32_e32 v209, 2, v1
	s_lshl_b32 s9, s30, 8
	v_lshlrev_b32_e32 v130, 6, v152
	v_add_u32_e32 v196, v208, v209
	v_add3_u32 v192, v154, s9, v130
	v_lshl_add_u64 v[130:131], s[54:55], 2, v[166:167]
	v_ashrrev_i32_e32 v197, 31, v196
	v_lshl_add_u64 v[130:131], v[196:197], 2, v[130:131]
	v_lshl_add_u64 v[194:195], v[130:131], 0, s[42:43]
	s_cmp_lt_i32 s3, 0
	s_mov_b64 s[8:9], -1
	s_cbranch_scc0 .LBB0_1072
	v_ashrrev_i32_e32 v193, 31, v192
	v_lshl_add_u64 v[150:151], v[196:197], 2, s[12:13]
	v_lshlrev_b64 v[130:131], 12, v[192:193]
	v_lshl_add_u64 v[164:165], v[150:151], 0, v[130:131]
	global_load_dwordx4 v[156:159], v[164:165], off
	global_load_dwordx4 v[142:145], v[194:195], off
	global_load_dwordx4 v[138:141], v[194:195], off offset:64
	global_load_dwordx4 v[160:163], v[164:165], off offset:64
	global_load_dwordx4 v[134:137], v[194:195], off offset:512
	global_load_dwordx4 v[130:133], v[194:195], off offset:576
	v_and_b32_e32 v146, 1, v1
	v_add_u32_e32 v147, 12, v209
	v_cmp_eq_u32_e32 vcc, 0, v146
	v_lshlrev_b64 v[148:149], 11, v[192:193]
	v_lshl_add_u64 v[198:199], v[176:177], 0, v[148:149]
	v_cndmask_b32_e32 v146, v147, v209, vcc
	v_add_u32_e32 v146, v146, v208
	v_ashrrev_i32_e32 v147, 31, v146
	v_lshlrev_b64 v[148:149], 1, v[146:147]
	v_lshl_add_u64 v[198:199], v[198:199], 0, v[148:149]
	s_mov_b64 s[8:9], 0
	s_mov_b64 s[52:53], -1
	s_waitcnt vmcnt(0)
	v_pk_fma_f32 v[158:159], v[64:65], v[144:145], v[158:159]
	v_pk_fma_f32 v[156:157], v[62:63], v[142:143], v[156:157]
	v_pk_fma_f32 v[162:163], v[60:61], v[140:141], v[162:163]
	v_pk_fma_f32 v[160:161], v[58:59], v[138:139], v[160:161]
	v_cvt_pk_bf16_f32 v156, v156, v157
	v_bfe_u32 v210, v160, 16, 1
	v_bfe_u32 v211, v161, 16, 1
	v_bfe_u32 v212, v158, 16, 1
	v_bfe_u32 v214, v162, 16, 1
	v_bfe_u32 v213, v159, 16, 1
	v_bfe_u32 v215, v163, 16, 1
	v_add3_u32 v157, v160, v210, s66
	v_add3_u32 v160, v161, v211, s66
	v_add3_u32 v158, v158, v212, s66
	v_add3_u32 v161, v162, v214, s66
	v_add3_u32 v159, v159, v213, s66
	v_add3_u32 v162, v163, v215, s66
	v_lshrrev_b32_e32 v157, 16, v157
	v_lshrrev_b32_e32 v163, 16, v158
	v_lshrrev_b32_e32 v161, 16, v161
	v_and_or_b32 v158, v160, s67, v157
	v_and_or_b32 v157, v159, s67, v163
	v_and_or_b32 v159, v162, s67, v161
	v_permlane16_swap_b32_e32 v156, v158
	s_nop 0
	v_permlane16_swap_b32_e32 v157, v159
	global_store_dwordx4 v[198:199], v[156:159], off
	global_load_dwordx4 v[156:159], v[164:165], off offset:512
	s_nop 0
	global_load_dwordx4 v[160:163], v[164:165], off offset:576
	v_add_u32_e32 v164, 16, v192
	v_ashrrev_i32_e32 v165, 31, v164
	v_lshlrev_b64 v[210:211], 12, v[164:165]
	v_lshl_add_u64 v[210:211], v[150:151], 0, v[210:211]
	v_lshlrev_b64 v[164:165], 11, v[164:165]
	v_lshl_add_u64 v[164:165], v[176:177], 0, v[164:165]
	v_lshl_add_u64 v[164:165], v[164:165], 0, v[148:149]
	s_waitcnt vmcnt(1)
	v_pk_fma_f32 v[158:159], v[32:33], v[136:137], v[158:159]
	v_pk_fma_f32 v[156:157], v[30:31], v[134:135], v[156:157]
	s_waitcnt vmcnt(0)
	v_pk_fma_f32 v[162:163], v[28:29], v[132:133], v[162:163]
	v_pk_fma_f32 v[160:161], v[26:27], v[130:131], v[160:161]
	v_cvt_pk_bf16_f32 v156, v156, v157
	v_bfe_u32 v212, v160, 16, 1
	v_bfe_u32 v213, v161, 16, 1
	v_bfe_u32 v214, v158, 16, 1
	v_bfe_u32 v216, v162, 16, 1
	v_bfe_u32 v215, v159, 16, 1
	v_bfe_u32 v217, v163, 16, 1
	v_add3_u32 v157, v160, v212, s66
	v_add3_u32 v160, v161, v213, s66
	v_add3_u32 v158, v158, v214, s66
	v_add3_u32 v161, v162, v216, s66
	v_add3_u32 v159, v159, v215, s66
	v_add3_u32 v162, v163, v217, s66
	v_lshrrev_b32_e32 v157, 16, v157
	v_lshrrev_b32_e32 v163, 16, v158
	v_lshrrev_b32_e32 v161, 16, v161
	v_and_or_b32 v158, v160, s67, v157
	v_and_or_b32 v157, v159, s67, v163
	v_and_or_b32 v159, v162, s67, v161
	v_permlane16_swap_b32_e32 v156, v158
	s_nop 0
	v_permlane16_swap_b32_e32 v157, v159
	global_store_dwordx4 v[198:199], v[156:159], off offset:256
	global_load_dwordx4 v[156:159], v[210:211], off
	s_nop 0
	global_load_dwordx4 v[160:163], v[210:211], off offset:64
	s_waitcnt vmcnt(1)
	v_pk_fma_f32 v[158:159], v[56:57], v[144:145], v[158:159]
	v_pk_fma_f32 v[156:157], v[54:55], v[142:143], v[156:157]
	s_waitcnt vmcnt(0)
	v_pk_fma_f32 v[162:163], v[52:53], v[140:141], v[162:163]
	v_pk_fma_f32 v[160:161], v[50:51], v[138:139], v[160:161]
	v_cvt_pk_bf16_f32 v156, v156, v157
	v_bfe_u32 v198, v160, 16, 1
	v_bfe_u32 v199, v161, 16, 1
	v_bfe_u32 v212, v158, 16, 1
	v_bfe_u32 v214, v162, 16, 1
	v_bfe_u32 v213, v159, 16, 1
	v_bfe_u32 v215, v163, 16, 1
	v_add3_u32 v157, v160, v198, s66
	v_add3_u32 v160, v161, v199, s66
	v_add3_u32 v158, v158, v212, s66
	v_add3_u32 v161, v162, v214, s66
	v_add3_u32 v159, v159, v213, s66
	v_add3_u32 v162, v163, v215, s66
	v_lshrrev_b32_e32 v157, 16, v157
	v_lshrrev_b32_e32 v163, 16, v158
	v_lshrrev_b32_e32 v161, 16, v161
	v_and_or_b32 v158, v160, s67, v157
	v_and_or_b32 v157, v159, s67, v163
	v_and_or_b32 v159, v162, s67, v161
	v_permlane16_swap_b32_e32 v156, v158
	s_nop 0
	v_permlane16_swap_b32_e32 v157, v159
	global_store_dwordx4 v[164:165], v[156:159], off
	global_load_dwordx4 v[156:159], v[210:211], off offset:512
	s_nop 0
	global_load_dwordx4 v[160:163], v[210:211], off offset:576
	v_add_u32_e32 v198, 32, v192
	v_ashrrev_i32_e32 v199, 31, v198
	v_lshlrev_b64 v[210:211], 12, v[198:199]
	v_lshl_add_u64 v[210:211], v[150:151], 0, v[210:211]
	s_waitcnt vmcnt(1)
	v_pk_fma_f32 v[158:159], v[24:25], v[136:137], v[158:159]
	v_pk_fma_f32 v[156:157], v[22:23], v[134:135], v[156:157]
	s_waitcnt vmcnt(0)
	v_pk_fma_f32 v[162:163], v[20:21], v[132:133], v[162:163]
	v_pk_fma_f32 v[160:161], v[18:19], v[130:131], v[160:161]
	v_cvt_pk_bf16_f32 v156, v156, v157
	v_bfe_u32 v212, v160, 16, 1
	v_bfe_u32 v213, v161, 16, 1
	v_bfe_u32 v214, v158, 16, 1
	v_bfe_u32 v216, v162, 16, 1
	v_bfe_u32 v215, v159, 16, 1
	v_bfe_u32 v217, v163, 16, 1
	v_add3_u32 v157, v160, v212, s66
	v_add3_u32 v160, v161, v213, s66
	v_add3_u32 v158, v158, v214, s66
	v_add3_u32 v161, v162, v216, s66
	v_add3_u32 v159, v159, v215, s66
	v_add3_u32 v162, v163, v217, s66
	v_lshrrev_b32_e32 v157, 16, v157
	v_lshrrev_b32_e32 v163, 16, v158
	v_lshrrev_b32_e32 v161, 16, v161
	v_and_or_b32 v158, v160, s67, v157
	v_and_or_b32 v157, v159, s67, v163
	v_and_or_b32 v159, v162, s67, v161
	v_permlane16_swap_b32_e32 v156, v158
	s_nop 0
	v_permlane16_swap_b32_e32 v157, v159
	global_store_dwordx4 v[164:165], v[156:159], off offset:256
	global_load_dwordx4 v[156:159], v[210:211], off
	s_nop 0
	global_load_dwordx4 v[160:163], v[210:211], off offset:64
	v_lshlrev_b64 v[164:165], 11, v[198:199]
	v_lshl_add_u64 v[164:165], v[176:177], 0, v[164:165]
	v_lshl_add_u64 v[164:165], v[164:165], 0, v[148:149]
	s_waitcnt vmcnt(1)
	v_pk_fma_f32 v[158:159], v[48:49], v[144:145], v[158:159]
	v_pk_fma_f32 v[156:157], v[46:47], v[142:143], v[156:157]
	s_waitcnt vmcnt(0)
	v_pk_fma_f32 v[162:163], v[44:45], v[140:141], v[162:163]
	v_pk_fma_f32 v[160:161], v[42:43], v[138:139], v[160:161]
	v_cvt_pk_bf16_f32 v156, v156, v157
	v_bfe_u32 v198, v160, 16, 1
	v_bfe_u32 v199, v161, 16, 1
	v_bfe_u32 v212, v158, 16, 1
	v_bfe_u32 v214, v162, 16, 1
	v_bfe_u32 v213, v159, 16, 1
	v_bfe_u32 v215, v163, 16, 1
	v_add3_u32 v157, v160, v198, s66
	v_add3_u32 v160, v161, v199, s66
	v_add3_u32 v158, v158, v212, s66
	v_add3_u32 v161, v162, v214, s66
	v_add3_u32 v159, v159, v213, s66
	v_add3_u32 v162, v163, v215, s66
	v_lshrrev_b32_e32 v157, 16, v157
	v_lshrrev_b32_e32 v163, 16, v158
	v_lshrrev_b32_e32 v161, 16, v161
	v_and_or_b32 v158, v160, s67, v157
	v_and_or_b32 v157, v159, s67, v163
	v_and_or_b32 v159, v162, s67, v161
	v_permlane16_swap_b32_e32 v156, v158
	s_nop 0
	v_permlane16_swap_b32_e32 v157, v159
	global_store_dwordx4 v[164:165], v[156:159], off
	global_load_dwordx4 v[156:159], v[210:211], off offset:512
	s_nop 0
	global_load_dwordx4 v[160:163], v[210:211], off offset:576
	v_add_u32_e32 v198, 48, v192
	v_ashrrev_i32_e32 v199, 31, v198
	v_lshlrev_b64 v[210:211], 12, v[198:199]
	v_lshl_add_u64 v[210:211], v[150:151], 0, v[210:211]
	s_waitcnt vmcnt(1)
	v_pk_fma_f32 v[158:159], v[16:17], v[136:137], v[158:159]
	v_pk_fma_f32 v[156:157], v[14:15], v[134:135], v[156:157]
	s_waitcnt vmcnt(0)
	v_pk_fma_f32 v[162:163], v[12:13], v[132:133], v[162:163]
	v_pk_fma_f32 v[160:161], v[10:11], v[130:131], v[160:161]
	v_cvt_pk_bf16_f32 v156, v156, v157
	v_bfe_u32 v212, v160, 16, 1
	v_bfe_u32 v213, v161, 16, 1
	v_bfe_u32 v214, v158, 16, 1
	v_bfe_u32 v216, v162, 16, 1
	v_bfe_u32 v215, v159, 16, 1
	v_bfe_u32 v217, v163, 16, 1
	v_add3_u32 v157, v160, v212, s66
	v_add3_u32 v160, v161, v213, s66
	v_add3_u32 v158, v158, v214, s66
	v_add3_u32 v161, v162, v216, s66
	v_add3_u32 v159, v159, v215, s66
	v_add3_u32 v162, v163, v217, s66
	v_lshrrev_b32_e32 v157, 16, v157
	v_lshrrev_b32_e32 v163, 16, v158
	v_lshrrev_b32_e32 v161, 16, v161
	v_and_or_b32 v158, v160, s67, v157
	v_and_or_b32 v157, v159, s67, v163
	v_and_or_b32 v159, v162, s67, v161
	v_permlane16_swap_b32_e32 v156, v158
	s_nop 0
	v_permlane16_swap_b32_e32 v157, v159
	global_store_dwordx4 v[164:165], v[156:159], off offset:256
	global_load_dwordx4 v[156:159], v[210:211], off
	s_nop 0
	global_load_dwordx4 v[160:163], v[210:211], off offset:64
	v_lshlrev_b64 v[164:165], 11, v[198:199]
	v_lshl_add_u64 v[164:165], v[176:177], 0, v[164:165]
	v_lshl_add_u64 v[164:165], v[164:165], 0, v[148:149]
	v_add_u32_e32 v198, 0x80, v192
	v_ashrrev_i32_e32 v199, 31, v198
	s_waitcnt vmcnt(1)
	v_pk_fma_f32 v[144:145], v[40:41], v[144:145], v[158:159]
	v_pk_fma_f32 v[142:143], v[38:39], v[142:143], v[156:157]
	s_waitcnt vmcnt(0)
	v_pk_fma_f32 v[140:141], v[36:37], v[140:141], v[162:163]
	v_pk_fma_f32 v[138:139], v[34:35], v[138:139], v[160:161]
	v_bfe_u32 v157, v138, 16, 1
	v_bfe_u32 v158, v139, 16, 1
	v_cvt_pk_bf16_f32 v141, v140, v141
	v_add3_u32 v138, v138, v157, s66
	v_add3_u32 v139, v139, v158, s66
	v_lshrrev_b32_e32 v155, 16, v138
	v_cvt_pk_bf16_f32 v138, v142, v143
	v_and_or_b32 v140, v139, s67, v155
	v_cvt_pk_bf16_f32 v139, v144, v145
	s_nop 0
	v_permlane16_swap_b32_e32 v138, v140
	s_nop 0
	v_permlane16_swap_b32_e32 v139, v141
	global_store_dwordx4 v[164:165], v[138:141], off
	global_load_dwordx4 v[138:141], v[210:211], off offset:512
	s_nop 0
	global_load_dwordx4 v[142:145], v[210:211], off offset:576
	v_lshlrev_b64 v[156:157], 12, v[198:199]
	v_lshl_add_u64 v[210:211], v[150:151], 0, v[156:157]
	s_waitcnt vmcnt(1)
	v_pk_fma_f32 v[136:137], v[8:9], v[136:137], v[140:141]
	v_pk_fma_f32 v[134:135], v[6:7], v[134:135], v[138:139]
	s_waitcnt vmcnt(0)
	v_pk_fma_f32 v[132:133], v[4:5], v[132:133], v[144:145]
	v_pk_fma_f32 v[130:131], v[2:3], v[130:131], v[142:143]
	v_bfe_u32 v140, v130, 16, 1
	v_bfe_u32 v141, v131, 16, 1
	v_cvt_pk_bf16_f32 v133, v132, v133
	v_add3_u32 v130, v130, v140, s66
	v_add3_u32 v131, v131, v141, s66
	v_lshrrev_b32_e32 v138, 16, v130
	v_cvt_pk_bf16_f32 v130, v134, v135
	v_and_or_b32 v132, v131, s67, v138
	v_cvt_pk_bf16_f32 v131, v136, v137
	s_nop 0
	v_permlane16_swap_b32_e32 v130, v132
	s_nop 0
	v_permlane16_swap_b32_e32 v131, v133
	global_store_dwordx4 v[164:165], v[130:133], off offset:256
	global_load_dwordx4 v[156:159], v[210:211], off
	global_load_dwordx4 v[142:145], v[194:195], off
	global_load_dwordx4 v[138:141], v[194:195], off offset:64
	global_load_dwordx4 v[160:163], v[210:211], off offset:64
	v_lshlrev_b64 v[130:131], 11, v[198:199]
	v_lshl_add_u64 v[130:131], v[176:177], 0, v[130:131]
	v_lshl_add_u64 v[164:165], v[130:131], 0, v[148:149]
	global_load_dwordx4 v[134:137], v[194:195], off offset:512
	global_load_dwordx4 v[130:133], v[194:195], off offset:576
	s_waitcnt vmcnt(4)
	v_pk_fma_f32 v[158:159], v[128:129], v[144:145], v[158:159]
	v_pk_fma_f32 v[156:157], v[126:127], v[142:143], v[156:157]
	s_waitcnt vmcnt(2)
	v_pk_fma_f32 v[162:163], v[124:125], v[140:141], v[162:163]
	v_pk_fma_f32 v[160:161], v[122:123], v[138:139], v[160:161]
	v_cvt_pk_bf16_f32 v156, v156, v157
	v_bfe_u32 v198, v160, 16, 1
	v_bfe_u32 v199, v161, 16, 1
	v_bfe_u32 v212, v158, 16, 1
	v_bfe_u32 v214, v162, 16, 1
	v_bfe_u32 v213, v159, 16, 1
	v_bfe_u32 v215, v163, 16, 1
	v_add3_u32 v157, v160, v198, s66
	v_add3_u32 v160, v161, v199, s66
	v_add3_u32 v158, v158, v212, s66
	v_add3_u32 v161, v162, v214, s66
	v_add3_u32 v159, v159, v213, s66
	v_add3_u32 v162, v163, v215, s66
	v_lshrrev_b32_e32 v157, 16, v157
	v_lshrrev_b32_e32 v163, 16, v158
	v_lshrrev_b32_e32 v161, 16, v161
	v_and_or_b32 v158, v160, s67, v157
	v_and_or_b32 v157, v159, s67, v163
	v_and_or_b32 v159, v162, s67, v161
	v_permlane16_swap_b32_e32 v156, v158
	s_nop 0
	v_permlane16_swap_b32_e32 v157, v159
	global_store_dwordx4 v[164:165], v[156:159], off
	global_load_dwordx4 v[156:159], v[210:211], off offset:512
	s_nop 0
	global_load_dwordx4 v[160:163], v[210:211], off offset:576
	v_add_u32_e32 v198, 0x90, v192
	v_ashrrev_i32_e32 v199, 31, v198
	v_lshlrev_b64 v[210:211], 12, v[198:199]
	v_lshl_add_u64 v[210:211], v[150:151], 0, v[210:211]
	s_waitcnt vmcnt(1)
	v_pk_fma_f32 v[158:159], v[96:97], v[136:137], v[158:159]
	v_pk_fma_f32 v[156:157], v[94:95], v[134:135], v[156:157]
	s_waitcnt vmcnt(0)
	v_pk_fma_f32 v[162:163], v[92:93], v[132:133], v[162:163]
	v_pk_fma_f32 v[160:161], v[90:91], v[130:131], v[160:161]
	v_cvt_pk_bf16_f32 v156, v156, v157
	v_bfe_u32 v212, v160, 16, 1
	v_bfe_u32 v213, v161, 16, 1
	v_bfe_u32 v214, v158, 16, 1
	v_bfe_u32 v216, v162, 16, 1
	v_bfe_u32 v215, v159, 16, 1
	v_bfe_u32 v217, v163, 16, 1
	v_add3_u32 v157, v160, v212, s66
	v_add3_u32 v160, v161, v213, s66
	v_add3_u32 v158, v158, v214, s66
	v_add3_u32 v161, v162, v216, s66
	v_add3_u32 v159, v159, v215, s66
	v_add3_u32 v162, v163, v217, s66
	v_lshrrev_b32_e32 v157, 16, v157
	v_lshrrev_b32_e32 v163, 16, v158
	v_lshrrev_b32_e32 v161, 16, v161
	v_and_or_b32 v158, v160, s67, v157
	v_and_or_b32 v157, v159, s67, v163
	v_and_or_b32 v159, v162, s67, v161
	v_permlane16_swap_b32_e32 v156, v158
	s_nop 0
	v_permlane16_swap_b32_e32 v157, v159
	global_store_dwordx4 v[164:165], v[156:159], off offset:256
	global_load_dwordx4 v[156:159], v[210:211], off
	s_nop 0
	global_load_dwordx4 v[160:163], v[210:211], off offset:64
	v_lshlrev_b64 v[164:165], 11, v[198:199]
	v_lshl_add_u64 v[164:165], v[176:177], 0, v[164:165]
	v_lshl_add_u64 v[164:165], v[164:165], 0, v[148:149]
	s_waitcnt vmcnt(1)
	v_pk_fma_f32 v[158:159], v[120:121], v[144:145], v[158:159]
	v_pk_fma_f32 v[156:157], v[118:119], v[142:143], v[156:157]
	s_waitcnt vmcnt(0)
	v_pk_fma_f32 v[162:163], v[116:117], v[140:141], v[162:163]
	v_pk_fma_f32 v[160:161], v[114:115], v[138:139], v[160:161]
	v_cvt_pk_bf16_f32 v156, v156, v157
	v_bfe_u32 v198, v160, 16, 1
	v_bfe_u32 v199, v161, 16, 1
	v_bfe_u32 v212, v158, 16, 1
	v_bfe_u32 v214, v162, 16, 1
	v_bfe_u32 v213, v159, 16, 1
	v_bfe_u32 v215, v163, 16, 1
	v_add3_u32 v157, v160, v198, s66
	v_add3_u32 v160, v161, v199, s66
	v_add3_u32 v158, v158, v212, s66
	v_add3_u32 v161, v162, v214, s66
	v_add3_u32 v159, v159, v213, s66
	v_add3_u32 v162, v163, v215, s66
	v_lshrrev_b32_e32 v157, 16, v157
	v_lshrrev_b32_e32 v163, 16, v158
	v_lshrrev_b32_e32 v161, 16, v161
	v_and_or_b32 v158, v160, s67, v157
	v_and_or_b32 v157, v159, s67, v163
	v_and_or_b32 v159, v162, s67, v161
	v_permlane16_swap_b32_e32 v156, v158
	s_nop 0
	v_permlane16_swap_b32_e32 v157, v159
	global_store_dwordx4 v[164:165], v[156:159], off
	global_load_dwordx4 v[156:159], v[210:211], off offset:512
	s_nop 0
	global_load_dwordx4 v[160:163], v[210:211], off offset:576
	v_add_u32_e32 v198, 0xa0, v192
	v_ashrrev_i32_e32 v199, 31, v198
	v_lshlrev_b64 v[210:211], 12, v[198:199]
	v_lshl_add_u64 v[210:211], v[150:151], 0, v[210:211]
	s_waitcnt vmcnt(1)
	v_pk_fma_f32 v[158:159], v[88:89], v[136:137], v[158:159]
	v_pk_fma_f32 v[156:157], v[86:87], v[134:135], v[156:157]
	s_waitcnt vmcnt(0)
	v_pk_fma_f32 v[162:163], v[84:85], v[132:133], v[162:163]
	v_pk_fma_f32 v[160:161], v[82:83], v[130:131], v[160:161]
	v_cvt_pk_bf16_f32 v156, v156, v157
	v_bfe_u32 v212, v160, 16, 1
	v_bfe_u32 v213, v161, 16, 1
	v_bfe_u32 v214, v158, 16, 1
	v_bfe_u32 v216, v162, 16, 1
	v_bfe_u32 v215, v159, 16, 1
	v_bfe_u32 v217, v163, 16, 1
	v_add3_u32 v157, v160, v212, s66
	v_add3_u32 v160, v161, v213, s66
	v_add3_u32 v158, v158, v214, s66
	v_add3_u32 v161, v162, v216, s66
	v_add3_u32 v159, v159, v215, s66
	v_add3_u32 v162, v163, v217, s66
	v_lshrrev_b32_e32 v157, 16, v157
	v_lshrrev_b32_e32 v163, 16, v158
	v_lshrrev_b32_e32 v161, 16, v161
	v_and_or_b32 v158, v160, s67, v157
	v_and_or_b32 v157, v159, s67, v163
	v_and_or_b32 v159, v162, s67, v161
	v_permlane16_swap_b32_e32 v156, v158
	s_nop 0
	v_permlane16_swap_b32_e32 v157, v159
	global_store_dwordx4 v[164:165], v[156:159], off offset:256
	global_load_dwordx4 v[156:159], v[210:211], off
	s_nop 0
	global_load_dwordx4 v[160:163], v[210:211], off offset:64
	v_lshlrev_b64 v[164:165], 11, v[198:199]
	v_lshl_add_u64 v[164:165], v[176:177], 0, v[164:165]
	v_lshl_add_u64 v[164:165], v[164:165], 0, v[148:149]
	s_waitcnt vmcnt(1)
	v_pk_fma_f32 v[158:159], v[112:113], v[144:145], v[158:159]
	v_pk_fma_f32 v[156:157], v[110:111], v[142:143], v[156:157]
	s_waitcnt vmcnt(0)
	v_pk_fma_f32 v[162:163], v[108:109], v[140:141], v[162:163]
	v_pk_fma_f32 v[160:161], v[106:107], v[138:139], v[160:161]
	v_cvt_pk_bf16_f32 v156, v156, v157
	v_bfe_u32 v198, v160, 16, 1
	v_bfe_u32 v199, v161, 16, 1
	v_bfe_u32 v212, v158, 16, 1
	v_bfe_u32 v214, v162, 16, 1
	v_bfe_u32 v213, v159, 16, 1
	v_bfe_u32 v215, v163, 16, 1
	v_add3_u32 v157, v160, v198, s66
	v_add3_u32 v160, v161, v199, s66
	v_add3_u32 v158, v158, v212, s66
	v_add3_u32 v161, v162, v214, s66
	v_add3_u32 v159, v159, v213, s66
	v_add3_u32 v162, v163, v215, s66
	v_lshrrev_b32_e32 v157, 16, v157
	v_lshrrev_b32_e32 v163, 16, v158
	v_lshrrev_b32_e32 v161, 16, v161
	v_and_or_b32 v158, v160, s67, v157
	v_and_or_b32 v157, v159, s67, v163
	v_and_or_b32 v159, v162, s67, v161
	v_permlane16_swap_b32_e32 v156, v158
	s_nop 0
	v_permlane16_swap_b32_e32 v157, v159
	global_store_dwordx4 v[164:165], v[156:159], off
	global_load_dwordx4 v[156:159], v[210:211], off offset:512
	s_nop 0
	global_load_dwordx4 v[160:163], v[210:211], off offset:576
	v_add_u32_e32 v198, 0xb0, v192
	v_ashrrev_i32_e32 v199, 31, v198
	v_lshlrev_b64 v[210:211], 12, v[198:199]
	v_lshl_add_u64 v[150:151], v[150:151], 0, v[210:211]
	s_waitcnt vmcnt(1)
	v_pk_fma_f32 v[158:159], v[80:81], v[136:137], v[158:159]
	v_pk_fma_f32 v[156:157], v[78:79], v[134:135], v[156:157]
	s_waitcnt vmcnt(0)
	v_pk_fma_f32 v[162:163], v[76:77], v[132:133], v[162:163]
	v_pk_fma_f32 v[160:161], v[74:75], v[130:131], v[160:161]
	v_cvt_pk_bf16_f32 v156, v156, v157
	v_bfe_u32 v210, v160, 16, 1
	v_bfe_u32 v211, v161, 16, 1
	v_bfe_u32 v212, v158, 16, 1
	v_bfe_u32 v214, v162, 16, 1
	v_bfe_u32 v213, v159, 16, 1
	v_bfe_u32 v215, v163, 16, 1
	v_add3_u32 v157, v160, v210, s66
	v_add3_u32 v160, v161, v211, s66
	v_add3_u32 v158, v158, v212, s66
	v_add3_u32 v161, v162, v214, s66
	v_add3_u32 v159, v159, v213, s66
	v_add3_u32 v162, v163, v215, s66
	v_lshrrev_b32_e32 v157, 16, v157
	v_lshrrev_b32_e32 v163, 16, v158
	v_lshrrev_b32_e32 v161, 16, v161
	v_and_or_b32 v158, v160, s67, v157
	v_and_or_b32 v157, v159, s67, v163
	v_and_or_b32 v159, v162, s67, v161
	v_permlane16_swap_b32_e32 v156, v158
	s_nop 0
	v_permlane16_swap_b32_e32 v157, v159
	global_store_dwordx4 v[164:165], v[156:159], off offset:256
	global_load_dwordx4 v[156:159], v[150:151], off
	s_nop 0
	global_load_dwordx4 v[160:163], v[150:151], off offset:64
	v_lshlrev_b64 v[164:165], 11, v[198:199]
	v_lshl_add_u64 v[164:165], v[176:177], 0, v[164:165]
	v_lshl_add_u64 v[148:149], v[164:165], 0, v[148:149]
	s_waitcnt vmcnt(1)
	v_pk_fma_f32 v[144:145], v[104:105], v[144:145], v[158:159]
	v_pk_fma_f32 v[142:143], v[102:103], v[142:143], v[156:157]
	s_waitcnt vmcnt(0)
	v_pk_fma_f32 v[140:141], v[100:101], v[140:141], v[162:163]
	v_pk_fma_f32 v[138:139], v[98:99], v[138:139], v[160:161]
	v_bfe_u32 v157, v138, 16, 1
	v_bfe_u32 v158, v139, 16, 1
	v_cvt_pk_bf16_f32 v141, v140, v141
	v_add3_u32 v138, v138, v157, s66
	v_add3_u32 v139, v139, v158, s66
	v_lshrrev_b32_e32 v155, 16, v138
	v_cvt_pk_bf16_f32 v138, v142, v143
	v_and_or_b32 v140, v139, s67, v155
	v_cvt_pk_bf16_f32 v139, v144, v145
	s_nop 0
	v_permlane16_swap_b32_e32 v138, v140
	s_nop 0
	v_permlane16_swap_b32_e32 v139, v141
	global_store_dwordx4 v[148:149], v[138:141], off
	global_load_dwordx4 v[140:143], v[150:151], off offset:512
	s_nop 0
	global_load_dwordx4 v[148:151], v[150:151], off offset:576
	v_lshlrev_b64 v[138:139], 10, v[198:199]
	s_waitcnt vmcnt(1)
	v_pk_fma_f32 v[136:137], v[72:73], v[136:137], v[142:143]
	v_pk_fma_f32 v[134:135], v[70:71], v[134:135], v[140:141]
	s_waitcnt vmcnt(0)
	v_pk_fma_f32 v[132:133], v[68:69], v[132:133], v[150:151]
	v_pk_fma_f32 v[130:131], v[66:67], v[130:131], v[148:149]
	v_bfe_u32 v142, v130, 16, 1
	v_bfe_u32 v143, v131, 16, 1
	v_cvt_pk_bf16_f32 v133, v132, v133
	v_add3_u32 v130, v130, v142, s66
	v_add3_u32 v131, v131, v143, s66
	v_lshrrev_b32_e32 v140, 16, v130
	v_cvt_pk_bf16_f32 v130, v134, v135
	v_and_or_b32 v132, v131, s67, v140
	v_cvt_pk_bf16_f32 v131, v136, v137
	s_nop 0
	v_permlane16_swap_b32_e32 v130, v132
	s_nop 0
	v_permlane16_swap_b32_e32 v131, v133

.LBB0_1086:
	s_andn2_b64 vcc, exec, s[30:31]
	s_cbranch_vccnz .LBB0_1088
	s_lshl_b32 s30, s72, 2
	s_or_b32 s31, s47, s30
	s_mul_i32 s31, s31, 0x18000
	s_add_i32 s31, s31, s45
	s_add_i32 s47, s31, 0x10000
	buffer_load_dwordx4 v[74:77], v193, s[8:11], s47 offen
	s_add_i32 s47, s31, 0x10400
	buffer_load_dwordx4 v[78:81], v193, s[8:11], s47 offen
	s_add_i32 s47, s31, 0x10800
	buffer_load_dwordx4 v[82:85], v193, s[8:11], s47 offen
	s_add_i32 s47, s31, 0x10c00
	buffer_load_dwordx4 v[86:89], v193, s[8:11], s47 offen
	s_add_i32 s47, s31, 0x11000
	buffer_load_dwordx4 v[90:93], v193, s[8:11], s47 offen
	s_add_i32 s47, s31, 0x11400
	buffer_load_dwordx4 v[94:97], v193, s[8:11], s47 offen
	s_add_i32 s47, s31, 0x11800
	s_add_i32 s31, s31, 0x11c00
	buffer_load_dwordx4 v[70:73], v193, s[8:11], s47 offen
	buffer_load_dwordx4 v[66:69], v193, s[8:11], s31 offen
	s_or_b32 s31, s30, s3
	s_mul_i32 s31, s31, 0x18000
	s_add_i32 s31, s31, s45
	s_add_i32 s47, s31, 0x38000
	s_add_i32 s3, s3, -1
	s_and_b32 s3, s3, 3
	s_or_b32 s3, s3, s30
	s_mul_i32 s3, s3, 0x18000
	s_add_i32 s3, s45, s3
	s_or_b32 s30, s3, 0x400
	v_and_b32_e32 v1, 1, v1
	v_cmp_eq_u32_e32 vcc, 0, v1
	s_waitcnt vmcnt(7)
	v_cvt_f32_f16_e32 v100, v76
	v_cvt_f32_f16_sdwa v101, v76 dst_sel:DWORD dst_unused:UNUSED_PAD src0_sel:WORD_1
	v_cvt_f32_f16_e32 v76, v77
	v_cvt_f32_f16_sdwa v77, v77 dst_sel:DWORD dst_unused:UNUSED_PAD src0_sel:WORD_1
	s_waitcnt vmcnt(6)
	v_cvt_f32_f16_e32 v102, v78
	v_cvt_f32_f16_sdwa v103, v78 dst_sel:DWORD dst_unused:UNUSED_PAD src0_sel:WORD_1
	v_cvt_f32_f16_e32 v78, v79
	v_cvt_f32_f16_sdwa v79, v79 dst_sel:DWORD dst_unused:UNUSED_PAD src0_sel:WORD_1
	v_cvt_f32_f16_e32 v104, v80
	v_cvt_f32_f16_sdwa v105, v80 dst_sel:DWORD dst_unused:UNUSED_PAD src0_sel:WORD_1
	v_cvt_f32_f16_e32 v80, v81
	v_cvt_f32_f16_sdwa v81, v81 dst_sel:DWORD dst_unused:UNUSED_PAD src0_sel:WORD_1
	s_waitcnt vmcnt(5)
	v_cvt_f32_f16_e32 v106, v82
	v_cvt_f32_f16_sdwa v107, v82 dst_sel:DWORD dst_unused:UNUSED_PAD src0_sel:WORD_1
	v_cvt_f32_f16_e32 v82, v83
	v_cvt_f32_f16_sdwa v83, v83 dst_sel:DWORD dst_unused:UNUSED_PAD src0_sel:WORD_1
	v_cvt_f32_f16_e32 v108, v84
	v_cvt_f32_f16_sdwa v109, v84 dst_sel:DWORD dst_unused:UNUSED_PAD src0_sel:WORD_1
	v_cvt_f32_f16_e32 v84, v85
	v_cvt_f32_f16_sdwa v85, v85 dst_sel:DWORD dst_unused:UNUSED_PAD src0_sel:WORD_1
	s_waitcnt vmcnt(4)
	v_cvt_f32_f16_e32 v110, v86
	v_cvt_f32_f16_sdwa v111, v86 dst_sel:DWORD dst_unused:UNUSED_PAD src0_sel:WORD_1
	v_cvt_f32_f16_e32 v86, v87
	v_cvt_f32_f16_sdwa v87, v87 dst_sel:DWORD dst_unused:UNUSED_PAD src0_sel:WORD_1
	v_cvt_f32_f16_e32 v112, v88
	v_cvt_f32_f16_sdwa v113, v88 dst_sel:DWORD dst_unused:UNUSED_PAD src0_sel:WORD_1
	v_cvt_f32_f16_e32 v88, v89
	v_cvt_f32_f16_sdwa v89, v89 dst_sel:DWORD dst_unused:UNUSED_PAD src0_sel:WORD_1
	s_waitcnt vmcnt(3)
	v_cvt_f32_f16_e32 v114, v90
	v_cvt_f32_f16_sdwa v115, v90 dst_sel:DWORD dst_unused:UNUSED_PAD src0_sel:WORD_1
	v_cvt_f32_f16_e32 v90, v91
	v_cvt_f32_f16_sdwa v91, v91 dst_sel:DWORD dst_unused:UNUSED_PAD src0_sel:WORD_1
	v_cvt_f32_f16_e32 v116, v92
	v_cvt_f32_f16_sdwa v117, v92 dst_sel:DWORD dst_unused:UNUSED_PAD src0_sel:WORD_1
	v_cvt_f32_f16_e32 v92, v93
	v_cvt_f32_f16_sdwa v93, v93 dst_sel:DWORD dst_unused:UNUSED_PAD src0_sel:WORD_1
	v_cvt_f32_f16_e32 v98, v74
	v_cvt_f32_f16_sdwa v99, v74 dst_sel:DWORD dst_unused:UNUSED_PAD src0_sel:WORD_1
	v_cvt_f32_f16_e32 v74, v75
	v_cvt_f32_f16_sdwa v75, v75 dst_sel:DWORD dst_unused:UNUSED_PAD src0_sel:WORD_1
	v_pk_add_f32 v[60:61], v[60:61], v[76:77]
	v_pk_add_f32 v[56:57], v[56:57], v[78:79]
	v_pk_add_f32 v[76:77], v[52:53], v[80:81]
	v_pk_add_f32 v[80:81], v[48:49], v[82:83]
	v_pk_add_f32 v[78:79], v[46:47], v[106:107]
	v_pk_add_f32 v[84:85], v[44:45], v[84:85]
	v_pk_add_f32 v[82:83], v[42:43], v[108:109]
	v_pk_add_f32 v[48:49], v[40:41], v[86:87]
	v_pk_add_f32 v[46:47], v[38:39], v[110:111]
	v_pk_add_f32 v[44:45], v[36:37], v[88:89]
	v_pk_add_f32 v[42:43], v[34:35], v[112:113]
	v_pk_add_f32 v[36:37], v[32:33], v[90:91]
	v_pk_add_f32 v[34:35], v[30:31], v[114:115]
	v_pk_add_f32 v[40:41], v[28:29], v[92:93]
	v_pk_add_f32 v[38:39], v[26:27], v[116:117]
	s_waitcnt vmcnt(1)
	v_cvt_f32_f16_e32 v26, v70
	v_cvt_f32_f16_sdwa v27, v70 dst_sel:DWORD dst_unused:UNUSED_PAD src0_sel:WORD_1
	v_cvt_f32_f16_e32 v28, v71
	v_cvt_f32_f16_sdwa v29, v71 dst_sel:DWORD dst_unused:UNUSED_PAD src0_sel:WORD_1
	v_cvt_f32_f16_e32 v30, v72
	v_cvt_f32_f16_e32 v32, v73
	v_cvt_f32_f16_sdwa v33, v73 dst_sel:DWORD dst_unused:UNUSED_PAD src0_sel:WORD_1
	v_cvt_f32_f16_sdwa v31, v72 dst_sel:DWORD dst_unused:UNUSED_PAD src0_sel:WORD_1
	v_pk_add_f32 v[64:65], v[64:65], v[74:75]
	v_pk_add_f32 v[62:63], v[62:63], v[98:99]
	v_pk_add_f32 v[58:59], v[58:59], v[100:101]
	v_cvt_f32_f16_e32 v118, v94
	v_cvt_f32_f16_sdwa v119, v94 dst_sel:DWORD dst_unused:UNUSED_PAD src0_sel:WORD_1
	v_cvt_f32_f16_e32 v94, v95
	v_cvt_f32_f16_sdwa v95, v95 dst_sel:DWORD dst_unused:UNUSED_PAD src0_sel:WORD_1
	v_cvt_f32_f16_e32 v120, v96
	v_cvt_f32_f16_sdwa v121, v96 dst_sel:DWORD dst_unused:UNUSED_PAD src0_sel:WORD_1
	v_cvt_f32_f16_e32 v96, v97
	v_cvt_f32_f16_sdwa v97, v97 dst_sel:DWORD dst_unused:UNUSED_PAD src0_sel:WORD_1
	v_pk_add_f32 v[54:55], v[54:55], v[102:103]
	v_pk_add_f32 v[74:75], v[50:51], v[104:105]
	v_pk_add_f32 v[16:17], v[16:17], v[28:29]
	v_pk_add_f32 v[14:15], v[14:15], v[26:27]
	v_pk_add_f32 v[12:13], v[12:13], v[32:33]
	v_pk_add_f32 v[10:11], v[10:11], v[30:31]
	s_waitcnt vmcnt(0)
	v_cvt_f32_f16_e32 v26, v66
	v_cvt_f32_f16_sdwa v27, v66 dst_sel:DWORD dst_unused:UNUSED_PAD src0_sel:WORD_1
	v_cvt_f32_f16_e32 v28, v67
	v_cvt_f32_f16_sdwa v29, v67 dst_sel:DWORD dst_unused:UNUSED_PAD src0_sel:WORD_1
	v_cvt_f32_f16_e32 v30, v68
	v_cvt_f32_f16_e32 v32, v69
	v_cvt_f32_f16_sdwa v33, v69 dst_sel:DWORD dst_unused:UNUSED_PAD src0_sel:WORD_1
	v_cvt_f32_f16_sdwa v31, v68 dst_sel:DWORD dst_unused:UNUSED_PAD src0_sel:WORD_1
	v_pk_add_f32 v[24:25], v[24:25], v[94:95]
	v_pk_add_f32 v[22:23], v[22:23], v[118:119]
	v_pk_add_f32 v[20:21], v[20:21], v[96:97]
	v_pk_add_f32 v[18:19], v[18:19], v[120:121]
	v_pk_add_f32 v[8:9], v[8:9], v[28:29]
	v_pk_add_f32 v[6:7], v[6:7], v[26:27]
	v_pk_add_f32 v[4:5], v[4:5], v[32:33]
	v_pk_add_f32 v[2:3], v[2:3], v[30:31]
	s_nop 0
	buffer_load_dwordx4 v[26:29], v193, s[8:11], s47 offen
	s_add_i32 s47, s31, 0x38400
	buffer_load_dwordx4 v[30:33], v193, s[8:11], s47 offen
	s_add_i32 s47, s31, 0x38800
	buffer_load_dwordx4 v[70:73], v193, s[8:11], s47 offen
	s_add_i32 s47, s31, 0x38c00
	buffer_load_dwordx4 v[88:91], v193, s[8:11], s47 offen
	s_add_i32 s47, s31, 0x39000
	buffer_load_dwordx4 v[98:101], v193, s[8:11], s47 offen
	s_add_i32 s47, s31, 0x39400
	buffer_load_dwordx4 v[102:105], v193, s[8:11], s47 offen
	s_add_i32 s47, s31, 0x39800
	s_add_i32 s31, s31, 0x39c00
	buffer_load_dwordx4 v[66:69], v193, s[8:11], s47 offen
	buffer_load_dwordx4 v[50:53], v193, s[8:11], s31 offen
	s_waitcnt vmcnt(7)
	v_cvt_f32_f16_e32 v86, v26
	v_cvt_f32_f16_sdwa v87, v26 dst_sel:DWORD dst_unused:UNUSED_PAD src0_sel:WORD_1
	s_waitcnt vmcnt(6)
	v_cvt_f32_f16_e32 v110, v30
	v_cvt_f32_f16_sdwa v111, v30 dst_sel:DWORD dst_unused:UNUSED_PAD src0_sel:WORD_1
	v_cvt_f32_f16_e32 v30, v31
	v_cvt_f32_f16_sdwa v31, v31 dst_sel:DWORD dst_unused:UNUSED_PAD src0_sel:WORD_1
	v_cvt_f32_f16_e32 v112, v32
	v_cvt_f32_f16_sdwa v113, v32 dst_sel:DWORD dst_unused:UNUSED_PAD src0_sel:WORD_1
	v_cvt_f32_f16_e32 v32, v33
	v_cvt_f32_f16_sdwa v33, v33 dst_sel:DWORD dst_unused:UNUSED_PAD src0_sel:WORD_1
	v_cvt_f32_f16_e32 v26, v27
	v_cvt_f32_f16_sdwa v27, v27 dst_sel:DWORD dst_unused:UNUSED_PAD src0_sel:WORD_1
	v_cvt_f32_f16_e32 v92, v28
	v_cvt_f32_f16_sdwa v93, v28 dst_sel:DWORD dst_unused:UNUSED_PAD src0_sel:WORD_1
	v_cvt_f32_f16_e32 v28, v29
	v_cvt_f32_f16_sdwa v29, v29 dst_sel:DWORD dst_unused:UNUSED_PAD src0_sel:WORD_1
	s_waitcnt vmcnt(4)
	v_cvt_f32_f16_e32 v118, v88
	v_cvt_f32_f16_sdwa v119, v88 dst_sel:DWORD dst_unused:UNUSED_PAD src0_sel:WORD_1
	v_cvt_f32_f16_e32 v120, v89
	v_cvt_f32_f16_sdwa v121, v89 dst_sel:DWORD dst_unused:UNUSED_PAD src0_sel:WORD_1
	v_pk_add_f32 v[88:89], v[56:57], v[30:31]
	v_pk_add_f32 v[56:57], v[76:77], v[32:33]
	v_cvt_f32_f16_e32 v30, v90
	v_cvt_f32_f16_e32 v32, v91
	v_cvt_f32_f16_sdwa v33, v91 dst_sel:DWORD dst_unused:UNUSED_PAD src0_sel:WORD_1
	v_cvt_f32_f16_sdwa v31, v90 dst_sel:DWORD dst_unused:UNUSED_PAD src0_sel:WORD_1
	v_pk_add_f32 v[108:109], v[64:65], v[26:27]
	v_pk_add_f32 v[96:97], v[60:61], v[28:29]
	v_pk_add_f32 v[28:29], v[48:49], v[120:121]
	v_pk_add_f32 v[26:27], v[46:47], v[118:119]
	v_pk_add_f32 v[32:33], v[44:45], v[32:33]
	v_pk_add_f32 v[30:31], v[42:43], v[30:31]
	s_waitcnt vmcnt(3)
	v_cvt_f32_f16_e32 v42, v98
	v_cvt_f32_f16_sdwa v43, v98 dst_sel:DWORD dst_unused:UNUSED_PAD src0_sel:WORD_1
	v_cvt_f32_f16_e32 v44, v99
	v_cvt_f32_f16_sdwa v45, v99 dst_sel:DWORD dst_unused:UNUSED_PAD src0_sel:WORD_1
	v_cvt_f32_f16_e32 v46, v100
	v_cvt_f32_f16_e32 v48, v101
	v_cvt_f32_f16_sdwa v49, v101 dst_sel:DWORD dst_unused:UNUSED_PAD src0_sel:WORD_1
	v_cvt_f32_f16_sdwa v47, v100 dst_sel:DWORD dst_unused:UNUSED_PAD src0_sel:WORD_1
	v_pk_add_f32 v[36:37], v[36:37], v[44:45]
	v_pk_add_f32 v[34:35], v[34:35], v[42:43]
	v_pk_add_f32 v[40:41], v[40:41], v[48:49]
	v_pk_add_f32 v[38:39], v[38:39], v[46:47]
	s_waitcnt vmcnt(2)
	v_cvt_f32_f16_e32 v42, v102
	v_cvt_f32_f16_sdwa v43, v102 dst_sel:DWORD dst_unused:UNUSED_PAD src0_sel:WORD_1
	v_cvt_f32_f16_e32 v44, v103
	v_cvt_f32_f16_sdwa v45, v103 dst_sel:DWORD dst_unused:UNUSED_PAD src0_sel:WORD_1
	v_cvt_f32_f16_e32 v46, v104
	v_cvt_f32_f16_e32 v48, v105
	v_cvt_f32_f16_sdwa v49, v105 dst_sel:DWORD dst_unused:UNUSED_PAD src0_sel:WORD_1
	v_cvt_f32_f16_sdwa v47, v104 dst_sel:DWORD dst_unused:UNUSED_PAD src0_sel:WORD_1
	v_cvt_f32_f16_e32 v114, v70
	v_cvt_f32_f16_sdwa v115, v70 dst_sel:DWORD dst_unused:UNUSED_PAD src0_sel:WORD_1
	v_cvt_f32_f16_e32 v70, v71
	v_cvt_f32_f16_sdwa v71, v71 dst_sel:DWORD dst_unused:UNUSED_PAD src0_sel:WORD_1
	v_cvt_f32_f16_e32 v116, v72
	v_cvt_f32_f16_sdwa v117, v72 dst_sel:DWORD dst_unused:UNUSED_PAD src0_sel:WORD_1
	v_cvt_f32_f16_e32 v72, v73
	v_cvt_f32_f16_sdwa v73, v73 dst_sel:DWORD dst_unused:UNUSED_PAD src0_sel:WORD_1
	v_pk_add_f32 v[44:45], v[24:25], v[44:45]
	v_pk_add_f32 v[42:43], v[22:23], v[42:43]
	v_pk_add_f32 v[48:49], v[20:21], v[48:49]
	v_pk_add_f32 v[46:47], v[18:19], v[46:47]
	s_waitcnt vmcnt(1)
	v_cvt_f32_f16_e32 v18, v66
	v_cvt_f32_f16_sdwa v19, v66 dst_sel:DWORD dst_unused:UNUSED_PAD src0_sel:WORD_1
	v_cvt_f32_f16_e32 v20, v67
	v_cvt_f32_f16_sdwa v21, v67 dst_sel:DWORD dst_unused:UNUSED_PAD src0_sel:WORD_1
	v_cvt_f32_f16_e32 v22, v68
	v_cvt_f32_f16_e32 v24, v69
	v_cvt_f32_f16_sdwa v25, v69 dst_sel:DWORD dst_unused:UNUSED_PAD src0_sel:WORD_1
	v_cvt_f32_f16_sdwa v23, v68 dst_sel:DWORD dst_unused:UNUSED_PAD src0_sel:WORD_1
	v_pk_add_f32 v[106:107], v[62:63], v[86:87]
	v_pk_add_f32 v[94:95], v[58:59], v[92:93]
	v_pk_add_f32 v[86:87], v[54:55], v[110:111]
	v_pk_add_f32 v[54:55], v[74:75], v[112:113]
	v_pk_add_f32 v[64:65], v[80:81], v[70:71]
	v_pk_add_f32 v[62:63], v[78:79], v[114:115]
	v_pk_add_f32 v[60:61], v[84:85], v[72:73]
	v_pk_add_f32 v[58:59], v[82:83], v[116:117]
	v_pk_add_f32 v[16:17], v[16:17], v[20:21]
	v_pk_add_f32 v[14:15], v[14:15], v[18:19]
	v_pk_add_f32 v[12:13], v[12:13], v[24:25]
	v_pk_add_f32 v[10:11], v[10:11], v[22:23]
	s_waitcnt vmcnt(0)
	v_cvt_f32_f16_e32 v18, v50
	v_cvt_f32_f16_sdwa v19, v50 dst_sel:DWORD dst_unused:UNUSED_PAD src0_sel:WORD_1
	v_cvt_f32_f16_e32 v20, v51
	v_cvt_f32_f16_sdwa v21, v51 dst_sel:DWORD dst_unused:UNUSED_PAD src0_sel:WORD_1
	v_cvt_f32_f16_e32 v22, v52
	v_cvt_f32_f16_e32 v24, v53
	v_cvt_f32_f16_sdwa v25, v53 dst_sel:DWORD dst_unused:UNUSED_PAD src0_sel:WORD_1
	v_cvt_f32_f16_sdwa v23, v52 dst_sel:DWORD dst_unused:UNUSED_PAD src0_sel:WORD_1
	v_pk_add_f32 v[72:73], v[8:9], v[20:21]
	v_pk_add_f32 v[70:71], v[6:7], v[18:19]
	v_pk_add_f32 v[76:77], v[4:5], v[24:25]
	v_pk_add_f32 v[74:75], v[2:3], v[22:23]
	s_nop 0
	buffer_load_dwordx4 v[2:5], v193, s[8:11], s3 offen
	buffer_load_dwordx4 v[6:9], v193, s[8:11], s30 offen
	s_or_b32 s30, s3, 0x800
	buffer_load_dwordx4 v[18:21], v193, s[8:11], s30 offen
	s_or_b32 s30, s3, 0xc00
	buffer_load_dwordx4 v[98:101], v193, s[8:11], s30 offen
	s_or_b32 s30, s3, 0x1000
	buffer_load_dwordx4 v[102:105], v193, s[8:11], s30 offen
	s_or_b32 s30, s3, 0x1400
	buffer_load_dwordx4 v[110:113], v193, s[8:11], s30 offen
	s_or_b32 s30, s3, 0x1800
	s_or_b32 s3, s3, 0x1c00
	buffer_load_dwordx4 v[90:93], v193, s[8:11], s30 offen
	buffer_load_dwordx4 v[82:85], v193, s[8:11], s3 offen
	v_ashrrev_i32_e32 v193, 31, v192
	s_waitcnt vmcnt(7)
	v_cvt_f32_f16_e32 v22, v2
	v_cvt_f32_f16_sdwa v23, v2 dst_sel:DWORD dst_unused:UNUSED_PAD src0_sel:WORD_1
	v_cvt_f32_f16_e32 v2, v3
	v_cvt_f32_f16_sdwa v3, v3 dst_sel:DWORD dst_unused:UNUSED_PAD src0_sel:WORD_1
	v_cvt_f32_f16_e32 v24, v4
	v_cvt_f32_f16_e32 v50, v5
	v_cvt_f32_f16_sdwa v51, v5 dst_sel:DWORD dst_unused:UNUSED_PAD src0_sel:WORD_1
	v_cvt_f32_f16_sdwa v25, v4 dst_sel:DWORD dst_unused:UNUSED_PAD src0_sel:WORD_1
	v_pk_add_f32 v[80:81], v[108:109], v[2:3]
	s_waitcnt vmcnt(6)
	v_cvt_f32_f16_e32 v2, v6
	v_cvt_f32_f16_sdwa v3, v6 dst_sel:DWORD dst_unused:UNUSED_PAD src0_sel:WORD_1
	v_cvt_f32_f16_e32 v4, v7
	v_cvt_f32_f16_sdwa v5, v7 dst_sel:DWORD dst_unused:UNUSED_PAD src0_sel:WORD_1
	v_cvt_f32_f16_e32 v6, v8
	v_cvt_f32_f16_sdwa v7, v8 dst_sel:DWORD dst_unused:UNUSED_PAD src0_sel:WORD_1
	v_pk_add_f32 v[78:79], v[106:107], v[22:23]
	v_pk_add_f32 v[68:69], v[96:97], v[50:51]
	v_cvt_f32_f16_e32 v22, v9
	v_cvt_f32_f16_sdwa v23, v9 dst_sel:DWORD dst_unused:UNUSED_PAD src0_sel:WORD_1
	v_pk_add_f32 v[52:53], v[88:89], v[4:5]
	v_pk_add_f32 v[50:51], v[86:87], v[2:3]
	v_pk_add_f32 v[54:55], v[54:55], v[6:7]
	s_waitcnt vmcnt(5)
	v_cvt_f32_f16_e32 v2, v18
	v_cvt_f32_f16_sdwa v3, v18 dst_sel:DWORD dst_unused:UNUSED_PAD src0_sel:WORD_1
	v_cvt_f32_f16_e32 v4, v19
	v_cvt_f32_f16_sdwa v5, v19 dst_sel:DWORD dst_unused:UNUSED_PAD src0_sel:WORD_1
	v_cvt_f32_f16_e32 v6, v20
	v_cvt_f32_f16_e32 v8, v21
	v_cvt_f32_f16_sdwa v9, v21 dst_sel:DWORD dst_unused:UNUSED_PAD src0_sel:WORD_1
	v_cvt_f32_f16_sdwa v7, v20 dst_sel:DWORD dst_unused:UNUSED_PAD src0_sel:WORD_1
	v_pk_add_f32 v[66:67], v[94:95], v[24:25]
	v_pk_add_f32 v[56:57], v[56:57], v[22:23]
	v_pk_add_f32 v[20:21], v[64:65], v[4:5]
	v_pk_add_f32 v[18:19], v[62:63], v[2:3]
	v_pk_add_f32 v[24:25], v[60:61], v[8:9]
	v_pk_add_f32 v[22:23], v[58:59], v[6:7]
	s_waitcnt vmcnt(4)
	v_cvt_f32_f16_e32 v2, v98
	v_cvt_f32_f16_sdwa v3, v98 dst_sel:DWORD dst_unused:UNUSED_PAD src0_sel:WORD_1
	v_cvt_f32_f16_e32 v4, v99
	v_cvt_f32_f16_sdwa v5, v99 dst_sel:DWORD dst_unused:UNUSED_PAD src0_sel:WORD_1
	v_cvt_f32_f16_e32 v6, v100
	v_cvt_f32_f16_e32 v8, v101
	v_cvt_f32_f16_sdwa v9, v101 dst_sel:DWORD dst_unused:UNUSED_PAD src0_sel:WORD_1
	v_cvt_f32_f16_sdwa v7, v100 dst_sel:DWORD dst_unused:UNUSED_PAD src0_sel:WORD_1
	v_pk_add_f32 v[4:5], v[28:29], v[4:5]
	v_pk_add_f32 v[2:3], v[26:27], v[2:3]
	v_pk_add_f32 v[8:9], v[32:33], v[8:9]
	v_pk_add_f32 v[6:7], v[30:31], v[6:7]
	s_waitcnt vmcnt(3)
	v_cvt_f32_f16_e32 v26, v102
	v_cvt_f32_f16_sdwa v27, v102 dst_sel:DWORD dst_unused:UNUSED_PAD src0_sel:WORD_1
	v_cvt_f32_f16_e32 v28, v103
	v_cvt_f32_f16_sdwa v29, v103 dst_sel:DWORD dst_unused:UNUSED_PAD src0_sel:WORD_1
	v_cvt_f32_f16_e32 v30, v104
	v_cvt_f32_f16_e32 v32, v105
	v_cvt_f32_f16_sdwa v33, v105 dst_sel:DWORD dst_unused:UNUSED_PAD src0_sel:WORD_1
	v_cvt_f32_f16_sdwa v31, v104 dst_sel:DWORD dst_unused:UNUSED_PAD src0_sel:WORD_1
	v_pk_add_f32 v[88:89], v[36:37], v[28:29]
	v_pk_add_f32 v[86:87], v[34:35], v[26:27]
	v_pk_add_f32 v[96:97], v[40:41], v[32:33]
	v_pk_add_f32 v[94:95], v[38:39], v[30:31]
	s_waitcnt vmcnt(2)
	v_cvt_f32_f16_e32 v26, v110
	v_cvt_f32_f16_sdwa v27, v110 dst_sel:DWORD dst_unused:UNUSED_PAD src0_sel:WORD_1
	v_cvt_f32_f16_e32 v28, v111
	v_cvt_f32_f16_sdwa v29, v111 dst_sel:DWORD dst_unused:UNUSED_PAD src0_sel:WORD_1
	v_cvt_f32_f16_e32 v30, v112
	v_cvt_f32_f16_e32 v32, v113
	v_cvt_f32_f16_sdwa v33, v113 dst_sel:DWORD dst_unused:UNUSED_PAD src0_sel:WORD_1
	v_cvt_f32_f16_sdwa v31, v112 dst_sel:DWORD dst_unused:UNUSED_PAD src0_sel:WORD_1
	v_pk_add_f32 v[60:61], v[44:45], v[28:29]
	v_pk_add_f32 v[58:59], v[42:43], v[26:27]
	v_pk_add_f32 v[64:65], v[48:49], v[32:33]
	v_pk_add_f32 v[62:63], v[46:47], v[30:31]
	s_waitcnt vmcnt(1)
	v_cvt_f32_f16_e32 v26, v90
	v_cvt_f32_f16_sdwa v27, v90 dst_sel:DWORD dst_unused:UNUSED_PAD src0_sel:WORD_1
	v_cvt_f32_f16_e32 v28, v91
	v_cvt_f32_f16_sdwa v29, v91 dst_sel:DWORD dst_unused:UNUSED_PAD src0_sel:WORD_1
	v_cvt_f32_f16_e32 v30, v92
	v_cvt_f32_f16_e32 v32, v93
	v_cvt_f32_f16_sdwa v33, v93 dst_sel:DWORD dst_unused:UNUSED_PAD src0_sel:WORD_1
	v_cvt_f32_f16_sdwa v31, v92 dst_sel:DWORD dst_unused:UNUSED_PAD src0_sel:WORD_1
	v_pk_add_f32 v[44:45], v[16:17], v[28:29]
	v_pk_add_f32 v[42:43], v[14:15], v[26:27]
	v_pk_add_f32 v[48:49], v[12:13], v[32:33]
	v_pk_add_f32 v[46:47], v[10:11], v[30:31]
	s_waitcnt vmcnt(0)
	v_cvt_f32_f16_e32 v10, v82
	v_cvt_f32_f16_sdwa v11, v82 dst_sel:DWORD dst_unused:UNUSED_PAD src0_sel:WORD_1
	v_cvt_f32_f16_e32 v12, v83
	v_cvt_f32_f16_sdwa v13, v83 dst_sel:DWORD dst_unused:UNUSED_PAD src0_sel:WORD_1
	v_cvt_f32_f16_e32 v14, v84
	v_cvt_f32_f16_e32 v16, v85
	v_cvt_f32_f16_sdwa v17, v85 dst_sel:DWORD dst_unused:UNUSED_PAD src0_sel:WORD_1
	v_cvt_f32_f16_sdwa v15, v84 dst_sel:DWORD dst_unused:UNUSED_PAD src0_sel:WORD_1
	v_pk_add_f32 v[12:13], v[72:73], v[12:13]
	v_pk_add_f32 v[10:11], v[70:71], v[10:11]
	v_pk_add_f32 v[16:17], v[76:77], v[16:17]
	v_pk_add_f32 v[14:15], v[74:75], v[14:15]
	v_lshl_add_u64 v[70:71], v[196:197], 2, s[12:13]
	v_lshlrev_b64 v[26:27], 12, v[192:193]
	v_lshl_add_u64 v[76:77], v[70:71], 0, v[26:27]
	global_load_dwordx4 v[72:75], v[76:77], off
	global_load_dwordx4 v[38:41], v[194:195], off
	global_load_dwordx4 v[34:37], v[194:195], off offset:64
	global_load_dwordx4 v[82:85], v[76:77], off offset:64
	global_load_dwordx4 v[30:33], v[194:195], off offset:512
	global_load_dwordx4 v[26:29], v[194:195], off offset:576
	v_add_u32_e32 v90, 12, v209
	v_cndmask_b32_e32 v1, v90, v209, vcc
	v_add_u32_e32 v146, v1, v208
	v_ashrrev_i32_e32 v147, 31, v146
	s_waitcnt vmcnt(4)
	v_pk_fma_f32 v[72:73], v[78:79], v[38:39], v[72:73]
	s_nop 0
	s_waitcnt vmcnt(2)
	v_pk_fma_f32 v[66:67], v[66:67], v[34:35], v[82:83]
	v_cvt_pk_bf16_f32 v72, v72, v73
	v_pk_fma_f32 v[80:81], v[80:81], v[40:41], v[74:75]
	v_cvt_pk_bf16_f32 v74, v66, v67
	v_pk_fma_f32 v[68:69], v[68:69], v[36:37], v[84:85]
	v_cvt_pk_bf16_f32 v73, v80, v81
	v_cvt_pk_bf16_f32 v75, v68, v69
	v_lshlrev_b64 v[66:67], 11, v[192:193]
	v_lshl_add_u64 v[68:69], v[176:177], 0, v[66:67]
	v_lshlrev_b64 v[66:67], 1, v[146:147]
	v_permlane16_swap_b32_e32 v72, v74
	v_permlane16_swap_b32_e32 v73, v75
	v_lshl_add_u64 v[68:69], v[68:69], 0, v[66:67]
	global_store_dwordx4 v[68:69], v[72:75], off
	global_load_dwordx4 v[72:75], v[76:77], off offset:512
	s_nop 0
	global_load_dwordx4 v[76:79], v[76:77], off offset:576
	s_waitcnt vmcnt(1)
	v_pk_fma_f32 v[74:75], v[88:89], v[32:33], v[74:75]
	v_pk_fma_f32 v[72:73], v[86:87], v[30:31], v[72:73]
	s_waitcnt vmcnt(0)
	v_pk_fma_f32 v[78:79], v[96:97], v[28:29], v[78:79]
	v_pk_fma_f32 v[76:77], v[94:95], v[26:27], v[76:77]
	v_cvt_pk_bf16_f32 v72, v72, v73
	v_bfe_u32 v81, v76, 16, 1
	v_bfe_u32 v82, v77, 16, 1
	v_bfe_u32 v83, v74, 16, 1
	v_bfe_u32 v85, v78, 16, 1
	v_bfe_u32 v84, v75, 16, 1
	v_bfe_u32 v86, v79, 16, 1
	v_add3_u32 v73, v76, v81, s66
	v_add3_u32 v76, v77, v82, s66
	v_add3_u32 v74, v74, v83, s66
	v_add3_u32 v77, v78, v85, s66
	v_add3_u32 v75, v75, v84, s66
	v_add3_u32 v78, v79, v86, s66
	v_lshrrev_b32_e32 v73, 16, v73
	v_lshrrev_b32_e32 v79, 16, v74
	v_lshrrev_b32_e32 v77, 16, v77
	v_and_or_b32 v74, v76, s67, v73
	v_and_or_b32 v73, v75, s67, v79
	v_and_or_b32 v75, v78, s67, v77
	v_permlane16_swap_b32_e32 v72, v74
	s_nop 0
	v_permlane16_swap_b32_e32 v73, v75
	global_store_dwordx4 v[68:69], v[72:75], off offset:256
	v_add_u32_e32 v68, 16, v192
	v_ashrrev_i32_e32 v69, 31, v68
	v_lshlrev_b64 v[72:73], 12, v[68:69]
	v_lshl_add_u64 v[80:81], v[70:71], 0, v[72:73]
	global_load_dwordx4 v[72:75], v[80:81], off
	global_load_dwordx4 v[76:79], v[80:81], off offset:64
	v_lshlrev_b64 v[68:69], 11, v[68:69]
	v_lshl_add_u64 v[68:69], v[176:177], 0, v[68:69]
	v_lshl_add_u64 v[68:69], v[68:69], 0, v[66:67]
	s_waitcnt vmcnt(1)
	v_pk_fma_f32 v[52:53], v[52:53], v[40:41], v[74:75]
	v_pk_fma_f32 v[50:51], v[50:51], v[38:39], v[72:73]
	s_waitcnt vmcnt(0)
	v_pk_fma_f32 v[56:57], v[56:57], v[36:37], v[78:79]
	v_pk_fma_f32 v[54:55], v[54:55], v[34:35], v[76:77]
	v_cvt_pk_bf16_f32 v50, v50, v51
	v_bfe_u32 v73, v54, 16, 1
	v_bfe_u32 v74, v55, 16, 1
	v_bfe_u32 v75, v52, 16, 1
	v_bfe_u32 v77, v56, 16, 1
	v_bfe_u32 v76, v53, 16, 1
	v_bfe_u32 v78, v57, 16, 1
	v_add3_u32 v51, v54, v73, s66
	v_add3_u32 v54, v55, v74, s66
	v_add3_u32 v52, v52, v75, s66
	v_add3_u32 v55, v56, v77, s66
	v_add3_u32 v53, v53, v76, s66
	v_add3_u32 v56, v57, v78, s66
	v_lshrrev_b32_e32 v51, 16, v51
	v_lshrrev_b32_e32 v57, 16, v52
	v_lshrrev_b32_e32 v55, 16, v55
	v_and_or_b32 v52, v54, s67, v51
	v_and_or_b32 v51, v53, s67, v57
	v_and_or_b32 v53, v56, s67, v55
	v_permlane16_swap_b32_e32 v50, v52
	s_nop 0
	v_permlane16_swap_b32_e32 v51, v53
	global_store_dwordx4 v[68:69], v[50:53], off
	global_load_dwordx4 v[50:53], v[80:81], off offset:512
	s_nop 0
	global_load_dwordx4 v[54:57], v[80:81], off offset:576
	v_add_u32_e32 v72, 32, v192
	v_ashrrev_i32_e32 v73, 31, v72
	v_lshlrev_b64 v[74:75], 12, v[72:73]
	v_lshl_add_u64 v[74:75], v[70:71], 0, v[74:75]
	s_waitcnt vmcnt(1)
	v_pk_fma_f32 v[52:53], v[60:61], v[32:33], v[52:53]
	v_pk_fma_f32 v[50:51], v[58:59], v[30:31], v[50:51]
	s_waitcnt vmcnt(0)
	v_pk_fma_f32 v[56:57], v[64:65], v[28:29], v[56:57]
	v_pk_fma_f32 v[54:55], v[62:63], v[26:27], v[54:55]
	v_cvt_pk_bf16_f32 v50, v50, v51
	v_bfe_u32 v59, v54, 16, 1
	v_bfe_u32 v60, v55, 16, 1
	v_bfe_u32 v61, v52, 16, 1
	v_bfe_u32 v63, v56, 16, 1
	v_bfe_u32 v62, v53, 16, 1
	v_bfe_u32 v64, v57, 16, 1
	v_add3_u32 v51, v54, v59, s66
	v_add3_u32 v54, v55, v60, s66
	v_add3_u32 v52, v52, v61, s66
	v_add3_u32 v55, v56, v63, s66
	v_add3_u32 v53, v53, v62, s66
	v_add3_u32 v56, v57, v64, s66
	v_lshrrev_b32_e32 v51, 16, v51
	v_lshrrev_b32_e32 v57, 16, v52
	v_lshrrev_b32_e32 v55, 16, v55
	v_and_or_b32 v52, v54, s67, v51
	v_and_or_b32 v51, v53, s67, v57
	v_and_or_b32 v53, v56, s67, v55
	v_permlane16_swap_b32_e32 v50, v52
	s_nop 0
	v_permlane16_swap_b32_e32 v51, v53
	global_store_dwordx4 v[68:69], v[50:53], off offset:256
	global_load_dwordx4 v[50:53], v[74:75], off
	s_nop 0
	global_load_dwordx4 v[54:57], v[74:75], off offset:64
	v_lshlrev_b64 v[58:59], 11, v[72:73]
	v_lshl_add_u64 v[58:59], v[176:177], 0, v[58:59]
	v_lshl_add_u64 v[58:59], v[58:59], 0, v[66:67]
	s_waitcnt vmcnt(1)
	v_pk_fma_f32 v[20:21], v[20:21], v[40:41], v[52:53]
	v_pk_fma_f32 v[18:19], v[18:19], v[38:39], v[50:51]
	s_waitcnt vmcnt(0)
	v_pk_fma_f32 v[24:25], v[24:25], v[36:37], v[56:57]
	v_pk_fma_f32 v[22:23], v[22:23], v[34:35], v[54:55]
	v_cvt_pk_bf16_f32 v18, v18, v19
	v_bfe_u32 v51, v22, 16, 1
	v_bfe_u32 v52, v23, 16, 1
	v_bfe_u32 v53, v20, 16, 1
	v_bfe_u32 v55, v24, 16, 1
	v_bfe_u32 v54, v21, 16, 1
	v_bfe_u32 v56, v25, 16, 1
	v_add3_u32 v19, v22, v51, s66
	v_add3_u32 v22, v23, v52, s66
	v_add3_u32 v20, v20, v53, s66
	v_add3_u32 v23, v24, v55, s66
	v_add3_u32 v21, v21, v54, s66
	v_add3_u32 v24, v25, v56, s66
	v_lshrrev_b32_e32 v19, 16, v19
	v_lshrrev_b32_e32 v25, 16, v20
	v_lshrrev_b32_e32 v23, 16, v23
	v_and_or_b32 v20, v22, s67, v19
	v_and_or_b32 v19, v21, s67, v25
	v_and_or_b32 v21, v24, s67, v23
	v_permlane16_swap_b32_e32 v18, v20
	s_nop 0
	v_permlane16_swap_b32_e32 v19, v21
	global_store_dwordx4 v[58:59], v[18:21], off
	global_load_dwordx4 v[18:21], v[74:75], off offset:512
	s_nop 0
	global_load_dwordx4 v[22:25], v[74:75], off offset:576
	v_add_u32_e32 v50, 48, v192
	v_ashrrev_i32_e32 v51, 31, v50
	v_lshlrev_b64 v[52:53], 12, v[50:51]
	v_lshl_add_u64 v[52:53], v[70:71], 0, v[52:53]
	v_lshlrev_b64 v[138:139], 10, v[50:51]
	s_waitcnt vmcnt(1)
	v_pk_fma_f32 v[20:21], v[44:45], v[32:33], v[20:21]
	v_pk_fma_f32 v[18:19], v[42:43], v[30:31], v[18:19]
	s_waitcnt vmcnt(0)
	v_pk_fma_f32 v[24:25], v[48:49], v[28:29], v[24:25]
	v_pk_fma_f32 v[22:23], v[46:47], v[26:27], v[22:23]
	v_cvt_pk_bf16_f32 v18, v18, v19
	v_bfe_u32 v43, v22, 16, 1
	v_bfe_u32 v44, v23, 16, 1
	v_bfe_u32 v45, v20, 16, 1
	v_bfe_u32 v47, v24, 16, 1
	v_bfe_u32 v46, v21, 16, 1
	v_bfe_u32 v48, v25, 16, 1
	v_add3_u32 v19, v22, v43, s66
	v_add3_u32 v22, v23, v44, s66
	v_add3_u32 v20, v20, v45, s66
	v_add3_u32 v23, v24, v47, s66
	v_add3_u32 v21, v21, v46, s66
	v_add3_u32 v24, v25, v48, s66
	v_lshrrev_b32_e32 v19, 16, v19
	v_lshrrev_b32_e32 v25, 16, v20
	v_lshrrev_b32_e32 v23, 16, v23
	v_and_or_b32 v20, v22, s67, v19
	v_and_or_b32 v19, v21, s67, v25
	v_and_or_b32 v21, v24, s67, v23
	v_permlane16_swap_b32_e32 v18, v20
	s_nop 0
	v_permlane16_swap_b32_e32 v19, v21
	global_store_dwordx4 v[58:59], v[18:21], off offset:256
	global_load_dwordx4 v[18:21], v[52:53], off
	s_nop 0
	global_load_dwordx4 v[22:25], v[52:53], off offset:64
	v_lshlrev_b64 v[42:43], 11, v[50:51]
	v_lshl_add_u64 v[42:43], v[176:177], 0, v[42:43]
	v_lshl_add_u64 v[42:43], v[42:43], 0, v[66:67]
	s_waitcnt vmcnt(1)
	v_pk_fma_f32 v[4:5], v[4:5], v[40:41], v[20:21]
	v_pk_fma_f32 v[2:3], v[2:3], v[38:39], v[18:19]
	s_waitcnt vmcnt(0)
	v_pk_fma_f32 v[8:9], v[8:9], v[36:37], v[24:25]
	v_pk_fma_f32 v[6:7], v[6:7], v[34:35], v[22:23]
	v_cvt_pk_bf16_f32 v2, v2, v3
	v_bfe_u32 v19, v6, 16, 1
	v_bfe_u32 v20, v7, 16, 1
	v_bfe_u32 v21, v4, 16, 1
	v_bfe_u32 v23, v8, 16, 1
	v_bfe_u32 v22, v5, 16, 1
	v_bfe_u32 v24, v9, 16, 1
	v_add3_u32 v3, v6, v19, s66
	v_add3_u32 v6, v7, v20, s66
	v_add3_u32 v4, v4, v21, s66
	v_add3_u32 v7, v8, v23, s66
	v_add3_u32 v5, v5, v22, s66
	v_add3_u32 v8, v9, v24, s66
	v_lshrrev_b32_e32 v3, 16, v3
	v_lshrrev_b32_e32 v9, 16, v4
	v_lshrrev_b32_e32 v7, 16, v7
	v_and_or_b32 v4, v6, s67, v3
	v_and_or_b32 v3, v5, s67, v9
	v_and_or_b32 v5, v8, s67, v7
	v_permlane16_swap_b32_e32 v2, v4
	s_nop 0
	v_permlane16_swap_b32_e32 v3, v5
	global_store_dwordx4 v[42:43], v[2:5], off
	global_load_dwordx4 v[2:5], v[52:53], off offset:512
	s_nop 0
	global_load_dwordx4 v[6:9], v[52:53], off offset:576
	s_waitcnt vmcnt(1)
	v_pk_fma_f32 v[4:5], v[12:13], v[32:33], v[4:5]
	v_pk_fma_f32 v[2:3], v[10:11], v[30:31], v[2:3]
	s_waitcnt vmcnt(0)
	v_pk_fma_f32 v[8:9], v[16:17], v[28:29], v[8:9]
	v_pk_fma_f32 v[6:7], v[14:15], v[26:27], v[6:7]
	v_cvt_pk_bf16_f32 v130, v2, v3
	v_cvt_pk_bf16_f32 v132, v6, v7
	v_cvt_pk_bf16_f32 v131, v4, v5
	v_cvt_pk_bf16_f32 v133, v8, v9
	v_permlane16_swap_b32_e32 v130, v132
	s_nop 0
	v_permlane16_swap_b32_e32 v131, v133
